# prep2 (decay/iclr prep): OCML log1pf/expf expansions replaced by v_log_f32(1+x)*ln2 and v_exp_f32(x*log2e) (f32, outputs still bf16-rounded), dead chains removed; gate phase work rebalanced
# speedup vs baseline: 1.0704x; 1.0454x over previous
.LBB0_539:
	s_and_b32 s0, s47, 0xffffff80
	v_add_u32_e32 v99, s0, v151
	v_or_b32_e32 v0, v99, v149
	v_ashrrev_i32_e32 v1, 31, v0
	v_lshlrev_b64 v[8:9], 7, v[0:1]
	v_lshl_add_u64 v[146:147], v[88:89], 0, v[8:9]
	global_load_dwordx4 v[0:3], v[146:147], off
	s_and_b32 s10, s87, 15
	v_lshl_or_b32 v68, s10, 13, v200
	s_waitcnt lgkmcnt(0)
	v_lshl_add_u64 v[4:5], v[72:73], 0, v[68:69]
	global_load_dwordx4 v[4:7], v[4:5], off
	v_lshl_add_u64 v[160:161], v[90:91], 0, v[8:9]
	global_load_dwordx4 v[8:11], v[160:161], off
	v_mov_b32_e32 v163, v69
	v_or_b32_e32 v162, 0x1000, v68
	v_lshl_add_u64 v[16:17], v[72:73], 0, v[162:163]
	v_lshl_add_u64 v[12:13], v[74:75], 0, v[68:69]
	global_load_dwordx4 v[16:19], v[16:17], off
	v_lshl_add_u64 v[20:21], v[74:75], 0, v[162:163]
	global_load_dwordx4 v[12:15], v[12:13], off
	s_nop 0
	global_load_dwordx4 v[64:67], v[20:21], off
	global_load_dwordx4 v[100:103], v[146:147], off offset:32
	v_lshl_add_u64 v[164:165], s[68:69], 0, v[68:69]
	v_lshl_add_u64 v[20:21], v[164:165], 0, v[92:93]
	v_lshl_add_u64 v[166:167], s[4:5], 0, v[68:69]
	global_load_dwordx4 v[104:107], v[20:21], off
	global_load_dwordx4 v[108:111], v[160:161], off offset:32
	v_lshl_add_u64 v[20:21], v[166:167], 0, v[92:93]
	global_load_dwordx4 v[112:115], v[20:21], off
	v_lshl_add_u64 v[20:21], v[76:77], 0, v[162:163]
	global_load_dwordx4 v[116:119], v[20:21], off
	v_lshl_add_u64 v[20:21], v[78:79], 0, v[162:163]
	global_load_dwordx4 v[120:123], v[20:21], off
	global_load_dwordx4 v[124:127], v[146:147], off offset:64
	v_lshl_add_u64 v[20:21], v[164:165], 0, v[94:95]
	global_load_dwordx4 v[128:131], v[20:21], off
	global_load_dwordx4 v[132:135], v[160:161], off offset:64
	v_lshl_add_u64 v[152:153], v[82:83], 0, v[162:163]
	v_lshl_or_b32 v211, s10, 6, v149
	v_lshlrev_b32_e32 v145, 2, v211
	s_lshl_b32 s70, s10, 7
	s_waitcnt vmcnt(13)
	v_mfma_f32_32x32x16_bf16 v[48:63], v[0:3], v[4:7], 0
	v_lshl_add_u64 v[4:5], v[166:167], 0, v[94:95]
	global_load_dwordx4 v[136:139], v[4:5], off
	v_lshl_add_u64 v[4:5], v[80:81], 0, v[162:163]
	global_load_dwordx4 v[140:143], v[4:5], off
	s_nop 0
	global_load_dwordx4 v[152:155], v[152:153], off
	s_nop 0
	global_load_dwordx4 v[156:159], v[146:147], off offset:96
	v_lshl_add_u64 v[146:147], v[166:167], 0, v[96:97]
	s_waitcnt vmcnt(15)
	v_mfma_f32_32x32x16_bf16 v[16:31], v[0:3], v[16:19], 0
	s_waitcnt vmcnt(14)
	v_mfma_f32_32x32x16_bf16 v[32:47], v[8:11], v[12:15], 0
	s_waitcnt vmcnt(13)
	v_mfma_f32_32x32x16_bf16 v[0:15], v[8:11], v[64:67], 0
	v_lshl_add_u64 v[64:65], v[164:165], 0, v[96:97]
	s_waitcnt vmcnt(11)
	v_mfma_f32_32x32x16_bf16 v[48:63], v[100:103], v[104:107], v[48:63]
	global_load_dwordx4 v[104:107], v[64:65], off
	s_nop 0
	global_load_dwordx4 v[64:67], v[160:161], off offset:96
	s_waitcnt vmcnt(10)
	v_mfma_f32_32x32x16_bf16 v[16:31], v[100:103], v[116:119], v[16:31]
	v_lshl_add_u64 v[100:101], v[86:87], 0, v[162:163]
	v_or_b32_e32 v102, v99, v198
	v_or_b32_e32 v170, 1, v102
	v_or_b32_e32 v160, 2, v102
	v_ashrrev_i32_e32 v171, 31, v170
	v_ashrrev_i32_e32 v161, 31, v160
	v_ashrrev_i32_e32 v103, 31, v102
	v_mfma_f32_32x32x16_bf16 v[32:47], v[108:111], v[112:115], v[32:47]
	global_load_dwordx4 v[112:115], v[146:147], off
	v_lshlrev_b64 v[180:181], 11, v[102:103]
	v_lshl_or_b32 v190, v211, 1, v180
	v_mov_b32_e32 v191, v181
	v_mov_b32_e32 v183, v181
	v_or_b32_e32 v182, 64, v190
	v_lshl_add_u64 v[192:193], s[26:27], 0, v[190:191]
	s_waitcnt vmcnt(10)
	v_mfma_f32_32x32x16_bf16 v[0:15], v[108:111], v[120:123], v[0:15]
	global_load_dwordx4 v[108:111], v[100:101], off
	v_lshl_add_u64 v[146:147], v[84:85], 0, v[162:163]
	global_load_dwordx4 v[116:119], v[146:147], off
	v_lshlrev_b64 v[100:101], 10, v[170:171]
	v_lshlrev_b64 v[120:121], 10, v[160:161]
	v_or_b32_e32 v100, v100, v211
	v_or_b32_e32 v120, v120, v211
	v_lshlrev_b64 v[176:177], 1, v[100:101]
	v_or_b32_e32 v100, 32, v100
	v_lshlrev_b64 v[166:167], 1, v[120:121]
	v_or_b32_e32 v120, 32, v120
	v_lshl_add_u64 v[122:123], s[30:31], 0, v[190:191]
	v_lshlrev_b64 v[172:173], 1, v[100:101]
	v_lshlrev_b64 v[162:163], 1, v[120:121]
	s_waitcnt vmcnt(10)
	v_mfma_f32_32x32x16_bf16 v[48:63], v[124:127], v[128:131], v[48:63]
	v_lshl_add_u64 v[184:185], s[26:27], 0, v[182:183]
	v_lshl_add_u64 v[100:101], s[30:31], 0, v[166:167]
	v_lshl_add_u64 v[120:121], s[30:31], 0, v[172:173]
	v_lshl_add_u64 v[128:129], s[30:31], 0, v[162:163]
	v_lshl_add_u64 v[178:179], s[26:27], 0, v[176:177]
	v_lshl_add_u64 v[174:175], s[26:27], 0, v[172:173]
	v_lshl_add_u64 v[168:169], s[26:27], 0, v[166:167]
	v_lshl_add_u64 v[164:165], s[26:27], 0, v[162:163]
	s_waitcnt vmcnt(8)
	v_mfma_f32_32x32x16_bf16 v[32:47], v[132:135], v[136:139], v[32:47]
	s_waitcnt vmcnt(7)
	v_mfma_f32_32x32x16_bf16 v[16:31], v[124:127], v[140:143], v[16:31]
	v_lshl_add_u64 v[124:125], s[30:31], 0, v[182:183]
	v_lshl_add_u64 v[126:127], s[30:31], 0, v[176:177]
	global_load_ushort v197, v[122:123], off
	global_load_ushort v238, v[124:125], off
	global_load_ushort v237, v[126:127], off
	global_load_ushort v234, v[120:121], off
	global_load_ushort v233, v[100:101], off
	global_load_ushort v230, v[128:129], off
	global_load_ushort v99, v[184:185], off
	global_load_ushort v188, v[192:193], off
	global_load_dword v210, v145, s[24:25]
	global_load_dword v209, v145, s[28:29]
	global_load_dword v100, v145, s[36:37]
	global_load_dword v208, v145, s[38:39]
	global_load_dword v68, v145, s[40:41]
	global_load_dword v101, v145, s[36:37] offset:128
	global_load_dword v207, v145, s[24:25] offset:128
	global_load_dword v206, v145, s[28:29] offset:128
	global_load_dword v205, v145, s[38:39] offset:128
	global_load_dword v204, v145, s[40:41] offset:128
	v_or_b32_e32 v142, 3, v102
	v_ashrrev_i32_e32 v143, 31, v142
	v_or_b32_e32 v122, 9, v102
	s_waitcnt vmcnt(24)
	v_mfma_f32_32x32x16_bf16 v[0:15], v[132:135], v[152:155], v[0:15]
	v_or_b32_e32 v132, 8, v102
	v_ashrrev_i32_e32 v133, 31, v132
	v_ashrrev_i32_e32 v123, 31, v122
	s_waitcnt vmcnt(22)
	v_mfma_f32_32x32x16_bf16 v[48:63], v[156:159], v[104:107], v[48:63]
	v_lshlrev_b64 v[104:105], 10, v[142:143]
	v_or_b32_e32 v104, v104, v211
	s_waitcnt vmcnt(9)
	s_nop 8
	v_add_f32_e32 v48, v48, v210
	v_mfma_f32_32x32x16_bf16 v[32:47], v[64:67], v[112:115], v[32:47]
	v_or_b32_e32 v112, 10, v102
	v_ashrrev_i32_e32 v113, 31, v112
	v_lshlrev_b64 v[114:115], 10, v[112:113]
	v_or_b32_e32 v114, v114, v211
	v_max_f32_e64 v252, -v48, 0
	s_waitcnt vmcnt(8)
	s_nop 5
	v_add_f32_e32 v32, v32, v209
	v_mfma_f32_32x32x16_bf16 v[16:31], v[156:159], v[116:119], v[16:31]
	v_lshlrev_b64 v[156:157], 1, v[104:105]
	v_or_b32_e32 v104, 32, v104
	v_lshlrev_b64 v[152:153], 1, v[104:105]
	v_lshlrev_b64 v[104:105], 10, v[132:133]
	v_or_b32_e32 v104, v104, v211
	v_lshlrev_b64 v[118:119], 1, v[114:115]
	v_or_b32_e32 v114, 32, v114
	v_mfma_f32_32x32x16_bf16 v[0:15], v[64:67], v[108:111], v[0:15]
	v_lshlrev_b64 v[108:109], 10, v[122:123]
	v_or_b32_e32 v108, v108, v211
	v_lshlrev_b64 v[138:139], 1, v[104:105]
	v_or_b32_e32 v104, 32, v104
	v_lshlrev_b64 v[128:129], 1, v[108:109]
	v_or_b32_e32 v108, 32, v108
	v_lshlrev_b64 v[114:115], 1, v[114:115]
	v_lshl_add_u64 v[64:65], s[30:31], 0, v[156:157]
	v_lshlrev_b64 v[134:135], 1, v[104:105]
	v_lshlrev_b64 v[124:125], 1, v[108:109]
	v_lshl_add_u64 v[186:187], s[30:31], 0, v[114:115]
	v_lshl_add_u64 v[158:159], s[26:27], 0, v[156:157]
	v_lshl_add_u64 v[154:155], s[26:27], 0, v[152:153]
	v_lshl_add_u64 v[66:67], s[30:31], 0, v[152:153]
	v_lshl_add_u64 v[140:141], s[26:27], 0, v[138:139]
	v_lshl_add_u64 v[106:107], s[30:31], 0, v[138:139]
	v_lshl_add_u64 v[136:137], s[26:27], 0, v[134:135]
	global_load_ushort v239, v[178:179], off
	global_load_ushort v240, v[174:175], off
	global_load_ushort v235, v[168:169], off
	global_load_ushort v236, v[164:165], off
	global_load_ushort v231, v[158:159], off
	global_load_ushort v232, v[154:155], off
	global_load_ushort v226, v[140:141], off
	global_load_ushort v227, v[136:137], off
	v_lshl_add_u64 v[104:105], s[30:31], 0, v[134:135]
	v_lshl_add_u64 v[110:111], s[30:31], 0, v[128:129]
	v_lshl_add_u64 v[108:109], s[30:31], 0, v[124:125]
	v_lshl_add_u64 v[146:147], s[30:31], 0, v[118:119]
	global_load_ushort v229, v[64:65], off
	global_load_ushort v228, v[66:67], off
	global_load_ushort v225, v[106:107], off
	global_load_ushort v224, v[104:105], off
	global_load_ushort v221, v[110:111], off
	global_load_ushort v220, v[108:109], off
	global_load_ushort v217, v[146:147], off
	global_load_ushort v216, v[186:187], off
	v_lshlrev_b32_e32 v186, 16, v188
	v_lshlrev_b32_e32 v187, 16, v99
	s_waitcnt vmcnt(20)
	v_pk_mul_f32 v[188:189], v[100:101], v[186:187]
	v_or_b32_e32 v66, 11, v102
	v_pk_mul_f32 v[104:105], v[188:189], v[188:189]
	v_ashrrev_i32_e32 v67, 31, v66
	v_add_f32_e32 v99, v104, v105
	v_lshlrev_b64 v[64:65], 10, v[66:67]
	v_or_b32_e32 v64, v64, v211
	v_add_f32_dpp v99, v99, v99 quad_perm:[1,0,3,2] row_mask:0xf bank_mask:0xf bound_ctrl:1
	v_lshlrev_b64 v[108:109], 1, v[64:65]
	v_or_b32_e32 v64, 32, v64
	v_add_f32_dpp v99, v99, v99 quad_perm:[2,3,0,1] row_mask:0xf bank_mask:0xf bound_ctrl:1
	v_lshlrev_b64 v[104:105], 1, v[64:65]
	v_lshl_add_u64 v[130:131], s[26:27], 0, v[128:129]
	v_add_f32_dpp v99, v99, v99 row_half_mirror row_mask:0xf bank_mask:0xf bound_ctrl:1
	v_lshl_add_u64 v[146:147], s[30:31], 0, v[108:109]
	v_lshl_add_u64 v[126:127], s[26:27], 0, v[124:125]
	v_add_f32_dpp v99, v99, v99 row_mirror row_mask:0xf bank_mask:0xf bound_ctrl:1
	ds_bpermute_b32 v145, v199, v99
	v_lshl_add_u64 v[120:121], s[26:27], 0, v[118:119]
	v_lshl_add_u64 v[116:117], s[26:27], 0, v[114:115]
	v_lshl_add_u64 v[110:111], s[26:27], 0, v[108:109]
	v_lshl_add_u64 v[106:107], s[26:27], 0, v[104:105]
	s_waitcnt lgkmcnt(0)
	v_add_f32_e32 v64, v99, v145
	v_mul_f32_e32 v65, 0x4f800000, v64
	v_cmp_gt_f32_e32 vcc, s75, v64
	global_load_ushort v222, v[130:131], off
	global_load_ushort v223, v[126:127], off
	global_load_ushort v218, v[120:121], off
	global_load_ushort v219, v[116:117], off
	global_load_ushort v214, v[110:111], off
	global_load_ushort v215, v[106:107], off
	v_cndmask_b32_e32 v64, v64, v65, vcc
	v_sqrt_f32_e32 v65, v64
	s_waitcnt vmcnt(25)
	v_add_f32_e32 v16, v16, v207
	s_waitcnt vmcnt(24)
	v_add_f32_e32 v0, v0, v206
	v_add_u32_e32 v99, -1, v65
	v_fma_f32 v145, -v99, v65, v64
	v_cmp_ge_f32_e64 s[0:1], 0, v145
	v_add_u32_e32 v145, 1, v65
	s_nop 0
	v_cndmask_b32_e64 v99, v65, v99, s[0:1]
	v_fma_f32 v65, -v145, v65, v64
	v_cmp_lt_f32_e64 s[0:1], 0, v65
	s_nop 1
	v_cndmask_b32_e64 v65, v99, v145, s[0:1]
	v_mul_f32_e32 v99, 0x37800000, v65
	v_cndmask_b32_e32 v65, v65, v99, vcc
	v_cmp_class_f32_e32 vcc, v64, v201
	s_nop 1
	v_cndmask_b32_e32 v64, v65, v64, vcc
	v_max_f32_e32 v145, 0x2b8cbccc, v64
	v_div_scale_f32 v99, s[0:1], v145, v145, 1.0
	v_rcp_f32_e32 v241, v99
	v_lshl_add_u64 v[64:65], s[30:31], 0, v[104:105]
	global_load_ushort v213, v[146:147], off
	global_load_ushort v212, v[64:65], off
	v_fma_f32 v64, -v99, v241, 1.0
	v_fmac_f32_e32 v241, v64, v241
	v_div_scale_f32 v64, vcc, 1.0, v145, 1.0
	v_mul_f32_e32 v250, v64, v241
	v_fma_f32 v65, -v99, v250, v64
	v_fmac_f32_e32 v250, v65, v241
	v_fma_f32 v251, -v99, v250, v64
	s_nop 1
	v_mul_f32_e64 v48, |v48|, s76
	v_exp_f32_e32 v48, v48
	v_lshl_add_u64 v[194:195], s[54:55], 0, v[190:191]
	s_nop 0
	v_add_f32_e32 v64, 1.0, v48
	v_log_f32_e32 v64, v64
	s_nop 0
	v_mul_f32_e32 v48, 0x3f317218, v64
	v_add_f32_e32 v48, v252, v48
	v_sub_f32_e32 v48, -0.5, v48
	v_div_fmas_f32 v147, v251, v241, v250
	v_div_fixup_f32 v145, v147, v145, 1.0
	s_nop 1
	v_mul_f32_e32 v32, 0xbfb8aa3b, v32
	v_exp_f32_e32 v32, v32
	s_nop 0
	v_add_f32_e32 v32, 1.0, v32
	v_div_scale_f32 v65, s[0:1], v32, v32, 1.0
	v_rcp_f32_e32 v99, v65
	s_lshl_b32 s0, s10, 3
	s_add_u32 s72, s97, s0
	s_addc_u32 s73, s46, 0
	s_nop 0
	v_mul_f32_e32 v48, 0x3fb8aa3b, v48
	v_exp_f32_e32 v48, v48
	v_fma_f32 v64, -v65, v99, 1.0
	v_fmac_f32_e32 v99, v64, v99
	v_div_scale_f32 v64, vcc, 1.0, v32, 1.0
	v_mul_f32_e32 v146, v64, v99
	v_fma_f32 v147, -v65, v146, v64
	v_fmac_f32_e32 v146, v147, v99
	v_fma_f32 v64, -v65, v146, v64
	v_div_fmas_f32 v64, v64, v99, v146
	v_div_fixup_f32 v32, v64, v32, 1.0
	v_add_f32_e32 v65, -1.0, v32
	v_fma_f32 v65, v208, v65, 1.0
	v_mul_f32_e32 v64, v188, v145
	v_mul_f32_e32 v65, v65, v186
	v_cvt_pk_bf16_f32 v48, v48, 0
	v_cvt_pk_bf16_f32 v99, v65, 0
	v_cvt_pk_bf16_f32 v186, v64, 0
	v_mul_f32_e32 v32, v32, v64
	v_lshl_add_u64 v[64:65], s[20:21], 0, v[190:191]
	global_store_short v[194:195], v48, off
	global_store_short v[192:193], v99, off
	global_store_short v[64:65], v186, off
	v_lshl_add_u64 v[64:65], s[18:19], 0, v[190:191]
	v_lshlrev_b32_e32 v191, 16, v99
	v_cvt_pk_bf16_f32 v32, v32, 0
	v_lshlrev_b32_e32 v48, 16, v48
	v_mul_f32_e64 v99, |v16|, s76
	v_exp_f32_e32 v99, v99
	global_store_short v[64:65], v32, off
	v_lshlrev_b32_e32 v190, 16, v197
	v_mov_b32_e32 v64, v99
	v_max_f32_e64 v16, -v16, 0
	v_lshlrev_b32_e32 v32, 16, v32
	v_mov_b32_e32 v241, v64
	v_add_f32_e32 v99, 1.0, v241
	v_add_f32_e32 v64, -1.0, v99
	v_sub_f32_e32 v65, v64, v99
	v_add_f32_e32 v65, 1.0, v65
	v_sub_f32_e32 v64, v241, v64
	v_add_f32_e32 v146, v64, v65
	v_frexp_mant_f32_e32 v147, v99
	v_cvt_f64_f32_e32 v[64:65], v99
	v_frexp_exp_i32_f64_e32 v64, v[64:65]
	v_cmp_gt_f32_e32 vcc, s81, v147
	v_fma_f32 v32, v32, v190, 0
	v_lshlrev_b32_e32 v186, 16, v186
	v_subbrev_co_u32_e32 v244, vcc, 0, v64, vcc
	v_sub_u32_e32 v64, 0, v244
	v_ldexp_f32 v65, v99, v64
	v_add_f32_e32 v99, -1.0, v65
	v_add_f32_e32 v147, 1.0, v65
	v_ldexp_f32 v64, v146, v64
	v_add_f32_e32 v146, 1.0, v99
	v_add_f32_e32 v192, -1.0, v147
	v_sub_f32_e32 v146, v65, v146
	v_sub_f32_e32 v65, v65, v192
	v_add_f32_e32 v146, v64, v146
	v_add_f32_e32 v64, v64, v65
	v_add_f32_e32 v245, v147, v64
	v_rcp_f32_e32 v247, v245
	v_sub_f32_e32 v65, v147, v245
	v_add_f32_e32 v246, v64, v65
	v_add_f32_e32 v65, v99, v146
	v_sub_f32_e32 v64, v99, v65
	v_mul_f32_e32 v248, v65, v247
	v_add_f32_e32 v99, v146, v64
	v_mul_f32_e32 v146, v245, v248
	v_fma_f32 v192, v248, v245, -v146
	v_fmac_f32_e32 v192, v248, v246
	v_add_f32_e32 v64, v146, v192
	v_sub_f32_e32 v147, v65, v64
	v_pk_add_f32 v[242:243], v[64:65], v[146:147] neg_lo:[0,1] neg_hi:[0,1]
	v_mov_b32_e32 v193, v64
	v_pk_add_f32 v[64:65], v[242:243], v[192:193] neg_lo:[0,1] neg_hi:[0,1]
	v_add_f32_e32 v65, v99, v65
	v_add_f32_e32 v64, v64, v65
	v_add_f32_e32 v65, v147, v64
	v_mul_f32_e32 v99, v247, v65
	v_mul_f32_e32 v146, v245, v99
	v_fma_f32 v192, v99, v245, -v146
	v_fmac_f32_e32 v192, v99, v246
	v_sub_f32_e32 v147, v147, v65
	v_add_f32_e32 v245, v64, v147
	v_add_f32_e32 v64, v146, v192
	v_sub_f32_e32 v147, v65, v64
	v_pk_add_f32 v[242:243], v[64:65], v[146:147] neg_lo:[0,1] neg_hi:[0,1]
	v_mov_b32_e32 v193, v64
	v_pk_add_f32 v[64:65], v[242:243], v[192:193] neg_lo:[0,1] neg_hi:[0,1]
	s_nop 0
	v_add_f32_e32 v65, v245, v65
	v_add_f32_e32 v64, v64, v65
	v_add_f32_e32 v65, v248, v99
	v_add_f32_e32 v64, v147, v64
	v_sub_f32_e32 v146, v65, v248
	v_mul_f32_e32 v64, v247, v64
	v_sub_f32_e32 v99, v99, v146
	v_add_f32_e32 v146, v99, v64
	v_add_f32_e32 v192, v65, v146
	v_mul_f32_e32 v193, v192, v192
	v_fmamk_f32 v64, v193, 0x3e9b6dac, v202
	v_fmaak_f32 v99, v193, v64, 0x3f2aaada
	v_cvt_f32_i32_e32 v64, v244
	v_sub_f32_e32 v65, v192, v65
	v_sub_f32_e32 v65, v146, v65
	v_ldexp_f32 v244, v65, 1
	v_mul_f32_e32 v65, v192, v193
	v_ldexp_f32 v147, v192, 1
	v_pk_mul_f32 v[192:193], v[64:65], v[98:99]
	v_mov_b32_e32 v99, v190
	v_fma_f32 v146, v64, s82, -v192
	v_fmac_f32_e32 v146, 0xb102e308, v64
	v_pk_add_f32 v[242:243], v[192:193], v[146:147]
	s_nop 0
	v_sub_f32_e32 v64, v243, v147
	v_sub_f32_e32 v64, v193, v64
	v_add_f32_e32 v245, v244, v64
	v_mov_b32_e32 v244, v192
	v_pk_add_f32 v[64:65], v[242:243], v[192:193] neg_lo:[0,1] neg_hi:[0,1]
	v_pk_add_f32 v[192:193], v[242:243], v[244:245]
	v_mov_b32_e32 v147, v242
	v_mov_b32_e32 v65, v193
	v_pk_add_f32 v[246:247], v[146:147], v[64:65] neg_lo:[0,1] neg_hi:[0,1]
	v_pk_add_f32 v[146:147], v[146:147], v[64:65]
	v_mov_b32_e32 v244, v245
	v_pk_add_f32 v[64:65], v[146:147], v[242:243] op_sel:[1,0] op_sel_hi:[0,1] neg_lo:[0,1] neg_hi:[0,1]
	v_pk_add_f32 v[248:249], v[192:193], v[64:65] op_sel_hi:[1,0] neg_lo:[0,1] neg_hi:[0,1]
	v_mov_b32_e32 v192, v193
	v_mov_b32_e32 v193, v147
	v_pk_mov_b32 v[64:65], v[242:243], v[64:65] op_sel:[1,0]
	v_mov_b32_e32 v245, v242
	v_pk_add_f32 v[192:193], v[192:193], v[64:65] neg_lo:[0,1] neg_hi:[0,1]
	v_mov_b32_e32 v248, v246
	v_pk_add_f32 v[192:193], v[244:245], v[192:193] neg_lo:[0,1] neg_hi:[0,1]
	v_mov_b32_e32 v247, v147
	v_pk_add_f32 v[244:245], v[248:249], v[192:193]
	v_pk_mul_f32 v[242:243], v[98:99], v[190:191]
	v_pk_add_f32 v[248:249], v[244:245], v[244:245] op_sel:[0,1] op_sel_hi:[1,0]
	s_nop 0
	v_pk_add_f32 v[146:147], v[146:147], v[248:249] op_sel:[1,0] op_sel_hi:[0,1]
	v_mov_b32_e32 v245, v146
	v_pk_add_f32 v[248:249], v[244:245], v[246:247] neg_lo:[0,1] neg_hi:[0,1]
	v_mov_b32_e32 v242, v191
	v_mov_b32_e32 v191, v68
	v_lshl_add_u64 v[64:65], v[70:71], 0, s[70:71]
	v_lshl_add_u64 v[180:181], v[64:65], 0, v[180:181]
	v_add_f32_e32 v146, 1.0, v241
	v_log_f32_e32 v146, v146
	s_nop 0
	v_mul_f32_e32 v146, 0x3f317218, v146
	v_add_f32_e32 v16, v16, v146
	v_sub_f32_e32 v16, -0.5, v16
	s_nop 1
	v_mul_f32_e32 v48, 0xbfb8aa3b, v48
	v_exp_f32_e32 v48, v48
	s_nop 1
	v_mul_f32_e32 v0, 0xbfb8aa3b, v0
	v_exp_f32_e32 v0, v0
	s_nop 0
	v_add_f32_e32 v0, 1.0, v0
	v_div_scale_f32 v146, s[0:1], v0, v0, 1.0
	v_rcp_f32_e32 v147, v146
	s_nop 1
	v_mul_f32_e32 v16, 0x3fb8aa3b, v16
	v_exp_f32_e32 v16, v16
	v_fma_f32 v99, -v146, v147, 1.0
	v_fmac_f32_e32 v147, v99, v147
	v_div_scale_f32 v99, vcc, 1.0, v0, 1.0
	v_mul_f32_e32 v188, v99, v147
	v_fma_f32 v192, -v146, v188, v99
	v_fmac_f32_e32 v188, v192, v147
	v_fma_f32 v99, -v146, v188, v99
	v_div_fmas_f32 v99, v99, v147, v188
	v_div_fixup_f32 v0, v99, v0, 1.0
	v_mul_f32_e32 v99, v189, v145
	v_add_f32_e32 v145, -1.0, v0
	s_waitcnt vmcnt(29)
	v_fma_f32 v145, v205, v145, 1.0
	v_mul_f32_e32 v145, v145, v187
	v_cvt_pk_bf16_f32 v16, v16, 0
	v_cvt_pk_bf16_f32 v145, v145, 0
	v_cvt_pk_bf16_f32 v187, v99, 0
	v_mul_f32_e32 v0, v0, v99
	global_store_short v[194:195], v16, off offset:64
	global_store_short v[184:185], v145, off
	v_lshl_add_u64 v[146:147], s[20:21], 0, v[182:183]
	v_lshlrev_b32_e32 v16, 16, v16
	v_cvt_pk_bf16_f32 v0, v0, 0
	global_store_short v[146:147], v187, off
	v_lshl_add_u64 v[146:147], s[18:19], 0, v[182:183]
	global_store_short v[146:147], v0, off
	v_lshlrev_b32_e32 v147, 16, v145
	v_mul_f32_e32 v145, 0xbfb8aa3b, v16
	v_exp_f32_e32 v145, v145
	v_lshlrev_b32_e32 v146, 16, v238
	v_mov_b32_e32 v99, v146
	v_lshlrev_b32_e32 v0, 16, v0
	v_pk_mul_f32 v[182:183], v[98:99], v[146:147]
	v_fmac_f32_e32 v32, v0, v146
	v_mov_b32_e32 v0, v145
	v_pk_fma_f32 v[184:185], v[242:243], v[190:191], 0 op_sel_hi:[1,1,0]
	v_mov_b32_e32 v182, v147
	s_waitcnt vmcnt(32)
	v_mov_b32_e32 v147, v204
	v_pk_fma_f32 v[182:183], v[182:183], v[146:147], v[184:185]
	v_add_f32_dpp v32, v32, v32 quad_perm:[1,0,3,2] row_mask:0xf bank_mask:0xf bound_ctrl:1
	s_nop 0
	v_mov_b32_dpp v184, v182 quad_perm:[1,0,3,2] row_mask:0xf bank_mask:0xf bound_ctrl:1
	v_mov_b32_dpp v185, v183 quad_perm:[1,0,3,2] row_mask:0xf bank_mask:0xf bound_ctrl:1
	v_add_f32_dpp v32, v32, v32 quad_perm:[2,3,0,1] row_mask:0xf bank_mask:0xf bound_ctrl:1
	v_pk_add_f32 v[182:183], v[182:183], v[184:185]
	s_nop 0
	v_add_f32_dpp v32, v32, v32 row_half_mirror row_mask:0xf bank_mask:0xf bound_ctrl:1
	v_mov_b32_dpp v184, v182 quad_perm:[2,3,0,1] row_mask:0xf bank_mask:0xf bound_ctrl:1
	v_mov_b32_dpp v185, v183 quad_perm:[2,3,0,1] row_mask:0xf bank_mask:0xf bound_ctrl:1
	v_add_f32_dpp v32, v32, v32 row_mirror row_mask:0xf bank_mask:0xf bound_ctrl:1
	v_pk_add_f32 v[182:183], v[182:183], v[184:185]
	ds_bpermute_b32 v99, v199, v32
	s_nop 0
	v_mov_b32_dpp v184, v182 row_half_mirror row_mask:0xf bank_mask:0xf bound_ctrl:1
	v_mov_b32_dpp v185, v183 row_half_mirror row_mask:0xf bank_mask:0xf bound_ctrl:1
	v_pk_add_f32 v[182:183], v[182:183], v[184:185]
	v_lshlrev_b32_e32 v16, 16, v187
	s_waitcnt lgkmcnt(0)
	v_add_f32_e32 v32, v32, v99
	v_mov_b32_dpp v184, v182 row_mirror row_mask:0xf bank_mask:0xf bound_ctrl:1
	v_mov_b32_dpp v185, v183 row_mirror row_mask:0xf bank_mask:0xf bound_ctrl:1
	v_pk_add_f32 v[182:183], v[182:183], v[184:185]
	ds_bpermute_b32 v184, v199, v182
	ds_bpermute_b32 v185, v199, v183
	v_mul_f32_e32 v99, v32, v186
	v_mul_f32_e32 v16, v32, v16
	v_fma_f32 v48, v48, v190, -v99
	v_fma_f32 v0, v0, v146, -v16
	v_cvt_pk_bf16_f32 v48, v48, s0
	v_cvt_pk_bf16_f32 v0, v0, s0
	global_store_short v[180:181], v48, off
	global_store_short v[180:181], v0, off offset:64
	s_and_saveexec_b64 s[0:1], s[2:3]
	s_cbranch_execz .LBB0_541
	v_lshlrev_b64 v[146:147], 7, v[102:103]
	v_lshl_add_u64 v[146:147], s[72:73], 0, v[146:147]
	s_waitcnt lgkmcnt(0)
	v_pk_add_f32 v[180:181], v[182:183], v[184:185]
	global_store_dwordx2 v[146:147], v[180:181], off
.LBB0_541:
	s_or_b64 exec, exec, s[0:1]
	s_waitcnt vmcnt(32)
	v_lshlrev_b32_e32 v181, 16, v240
	v_lshlrev_b32_e32 v180, 16, v239
	v_pk_mul_f32 v[182:183], v[100:101], v[180:181]
	v_add_f32_e32 v49, v49, v210
	v_pk_mul_f32 v[146:147], v[182:183], v[182:183]
	v_add_f32_e32 v0, v146, v147
	s_nop 1
	v_add_f32_dpp v0, v0, v0 quad_perm:[1,0,3,2] row_mask:0xf bank_mask:0xf bound_ctrl:1
	s_nop 1
	v_add_f32_dpp v0, v0, v0 quad_perm:[2,3,0,1] row_mask:0xf bank_mask:0xf bound_ctrl:1
	s_nop 1
	v_add_f32_dpp v0, v0, v0 row_half_mirror row_mask:0xf bank_mask:0xf bound_ctrl:1
	v_max_f32_e64 v194, -v49, 0
	s_nop 0
	v_add_f32_dpp v0, v0, v0 row_mirror row_mask:0xf bank_mask:0xf bound_ctrl:1
	ds_bpermute_b32 v16, v199, v0
	v_add_f32_e32 v33, v33, v209
	v_add_f32_e32 v17, v17, v207
	v_add_f32_e32 v1, v1, v206
	s_waitcnt lgkmcnt(0)
	v_add_f32_e32 v0, v0, v16
	v_mul_f32_e32 v16, 0x4f800000, v0
	v_cmp_gt_f32_e32 vcc, s75, v0
	s_nop 1
	v_cndmask_b32_e32 v0, v0, v16, vcc
	v_sqrt_f32_e32 v16, v0
	s_nop 0
	v_add_u32_e32 v32, -1, v16
	v_add_u32_e32 v48, 1, v16
	v_fma_f32 v99, -v32, v16, v0
	v_fma_f32 v103, -v48, v16, v0
	v_cmp_ge_f32_e64 s[0:1], 0, v99
	s_nop 1
	v_cndmask_b32_e64 v16, v16, v32, s[0:1]
	v_cmp_lt_f32_e64 s[0:1], 0, v103
	s_nop 1
	v_cndmask_b32_e64 v16, v16, v48, s[0:1]
	v_mul_f32_e32 v32, 0x37800000, v16
	v_cndmask_b32_e32 v16, v16, v32, vcc
	v_cmp_class_f32_e32 vcc, v0, v201
	s_nop 1
	v_cndmask_b32_e32 v0, v16, v0, vcc
	v_max_f32_e32 v0, 0x2b8cbccc, v0
	v_div_scale_f32 v16, s[0:1], v0, v0, 1.0
	v_rcp_f32_e32 v32, v16
	v_div_scale_f32 v48, vcc, 1.0, v0, 1.0
	v_fma_f32 v99, -v16, v32, 1.0
	v_fmac_f32_e32 v32, v99, v32
	v_mul_f32_e32 v103, v48, v32
	v_fma_f32 v99, -v16, v103, v48
	v_fmac_f32_e32 v103, v99, v32
	v_fma_f32 v16, -v16, v103, v48
	v_div_fmas_f32 v16, v16, v32, v103
	v_mul_f32_e64 v145, |v49|, s76
	v_exp_f32_e32 v145, v145
	v_div_fixup_f32 v0, v16, v0, 1.0
	s_nop 0
	v_max_f32_e64 v192, -v17, 0
	v_lshl_add_u64 v[184:185], s[54:55], 0, v[176:177]
	s_nop 0
	v_add_f32_e32 v48, 1.0, v145
	v_log_f32_e32 v48, v48
	s_nop 0
	v_mul_f32_e32 v48, 0x3f317218, v48
	v_add_f32_e32 v48, v194, v48
	v_sub_f32_e32 v48, -0.5, v48
	v_mul_f32_e32 v49, 0x3fb8aa3b, v48
	v_exp_f32_e32 v49, v49
	s_nop 0
	v_mov_b32_e32 v16, v49
	s_nop 0
	v_mul_f32_e32 v32, 0xbfb8aa3b, v33
	v_exp_f32_e32 v32, v32
	s_nop 0
	v_add_f32_e32 v32, 1.0, v32
	v_div_scale_f32 v33, s[0:1], v32, v32, 1.0
	v_rcp_f32_e32 v49, v33
	s_nop 0
	v_fma_f32 v48, -v33, v49, 1.0
	v_fmac_f32_e32 v49, v48, v49
	v_div_scale_f32 v48, vcc, 1.0, v32, 1.0
	v_mul_f32_e32 v99, v48, v49
	v_fma_f32 v103, -v33, v99, v48
	v_fmac_f32_e32 v99, v103, v49
	v_fma_f32 v33, -v33, v99, v48
	v_div_fmas_f32 v33, v33, v49, v99
	v_div_fixup_f32 v32, v33, v32, 1.0
	v_mul_f32_e32 v33, v182, v0
	v_add_f32_e32 v48, -1.0, v32
	v_fma_f32 v48, v208, v48, 1.0
	v_cvt_pk_bf16_f32 v16, v16, 0
	v_mul_f32_e32 v32, v32, v33
	v_mul_f32_e32 v48, v48, v180
	v_cvt_pk_bf16_f32 v103, v33, 0
	v_cvt_pk_bf16_f32 v49, v32, 0
	v_lshl_add_u64 v[32:33], s[20:21], 0, v[176:177]
	v_lshlrev_b32_e32 v145, 16, v16
	v_cvt_pk_bf16_f32 v48, v48, 0
	global_store_short v[184:185], v16, off
	global_store_short v[178:179], v48, off
	global_store_short v[32:33], v103, off
	v_lshl_add_u64 v[32:33], s[18:19], 0, v[176:177]
	global_store_short v[32:33], v49, off
	v_lshlrev_b32_e32 v33, 16, v48
	v_lshlrev_b32_e32 v48, 16, v49
	v_lshlrev_b32_e32 v32, 16, v237
	v_mov_b32_e32 v49, v32
	v_fma_f32 v180, v48, v32, 0
	v_pk_mul_f32 v[48:49], v[48:49], v[32:33]
	v_mul_f32_e32 v0, v183, v0
	v_lshlrev_b32_e32 v103, 16, v103
	s_nop 1
	v_mul_f32_e64 v48, |v17|, s76
	v_exp_f32_e32 v48, v48
	s_nop 1
	v_add_f32_e32 v16, 1.0, v48
	v_log_f32_e32 v16, v16
	s_nop 0
	v_mul_f32_e32 v16, 0x3f317218, v16
	v_add_f32_e32 v16, v192, v16
	v_sub_f32_e32 v16, -0.5, v16
	v_mul_f32_e32 v145, 0xbfb8aa3b, v145
	v_exp_f32_e32 v145, v145
	s_nop 1
	v_mul_f32_e32 v1, 0xbfb8aa3b, v1
	v_exp_f32_e32 v1, v1
	s_nop 0
	v_add_f32_e32 v1, 1.0, v1
	v_div_scale_f32 v48, s[0:1], v1, v1, 1.0
	v_rcp_f32_e32 v99, v48
	s_nop 1
	v_mul_f32_e32 v16, 0x3fb8aa3b, v16
	v_exp_f32_e32 v16, v16
	v_fma_f32 v17, -v48, v99, 1.0
	v_fmac_f32_e32 v99, v17, v99
	v_div_scale_f32 v17, vcc, 1.0, v1, 1.0
	v_mul_f32_e32 v146, v17, v99
	v_fma_f32 v147, -v48, v146, v17
	v_fmac_f32_e32 v146, v147, v99
	v_fma_f32 v17, -v48, v146, v17
	v_div_fmas_f32 v17, v17, v99, v146
	v_div_fixup_f32 v1, v17, v1, 1.0
	v_add_f32_e32 v17, -1.0, v1
	v_fma_f32 v17, v205, v17, 1.0
	v_cvt_pk_bf16_f32 v48, v0, 0
	v_mul_f32_e32 v0, v1, v0
	v_mul_f32_e32 v17, v17, v181
	v_cvt_pk_bf16_f32 v16, v16, 0
	v_cvt_pk_bf16_f32 v99, v0, 0
	v_lshl_add_u64 v[0:1], s[20:21], 0, v[172:173]
	v_cvt_pk_bf16_f32 v17, v17, 0
	global_store_short v[184:185], v16, off offset:64
	global_store_short v[174:175], v17, off
	global_store_short v[0:1], v48, off
	v_lshl_add_u64 v[0:1], s[18:19], 0, v[172:173]
	v_lshlrev_b32_e32 v16, 16, v16
	global_store_short v[0:1], v99, off
	v_mul_f32_e32 v1, 0xbfb8aa3b, v16
	v_lshlrev_b32_e32 v147, 16, v17
	v_lshlrev_b32_e32 v0, 16, v99
	v_fma_f32 v17, v16, s76, -v1
	v_rndne_f32_e32 v99, v1
	v_fmac_f32_e32 v17, 0xb2a5705f, v16
	v_sub_f32_e32 v1, v1, v99
	v_add_f32_e32 v1, v1, v17
	v_exp_f32_e32 v17, v1
	v_lshlrev_b32_e32 v146, 16, v234
	v_mov_b32_e32 v1, v146
	v_fmac_f32_e32 v180, v0, v146
	v_pk_mul_f32 v[0:1], v[0:1], v[146:147]
	s_nop 0
	v_add_f32_dpp v17, v180, v180 quad_perm:[1,0,3,2] row_mask:0xf bank_mask:0xf bound_ctrl:1
	s_nop 1
	v_add_f32_dpp v17, v17, v17 quad_perm:[2,3,0,1] row_mask:0xf bank_mask:0xf bound_ctrl:1
	v_lshlrev_b32_e32 v173, 16, v48
	v_mov_b32_e32 v48, v33
	v_add_f32_dpp v17, v17, v17 row_half_mirror row_mask:0xf bank_mask:0xf bound_ctrl:1
	v_mov_b32_e32 v33, v68
	v_mul_f32_e32 v172, 0xbfb8aa3b, v16
	v_exp_f32_e32 v172, v172
	v_add_f32_dpp v17, v17, v17 row_mirror row_mask:0xf bank_mask:0xf bound_ctrl:1
	ds_bpermute_b32 v99, v199, v17
	v_mov_b32_e32 v0, v147
	v_mov_b32_e32 v147, v204
	s_waitcnt lgkmcnt(0)
	v_add_f32_e32 v99, v17, v99
	v_pk_fma_f32 v[16:17], v[48:49], v[32:33], 0 op_sel_hi:[1,1,0]
	v_mul_f32_e32 v33, v99, v103
	v_pk_fma_f32 v[0:1], v[0:1], v[146:147], v[16:17]
	v_lshlrev_b64 v[48:49], 11, v[170:171]
	v_fma_f32 v32, v145, v32, -v33
	v_mov_b32_dpp v16, v0 quad_perm:[1,0,3,2] row_mask:0xf bank_mask:0xf bound_ctrl:1
	v_mov_b32_dpp v17, v1 quad_perm:[1,0,3,2] row_mask:0xf bank_mask:0xf bound_ctrl:1
	v_pk_add_f32 v[0:1], v[0:1], v[16:17]
	v_lshl_add_u64 v[48:49], v[64:65], 0, v[48:49]
	v_cvt_pk_bf16_f32 v32, v32, s0
	v_mov_b32_dpp v16, v0 quad_perm:[2,3,0,1] row_mask:0xf bank_mask:0xf bound_ctrl:1
	v_mov_b32_dpp v17, v1 quad_perm:[2,3,0,1] row_mask:0xf bank_mask:0xf bound_ctrl:1
	v_pk_add_f32 v[0:1], v[0:1], v[16:17]
	global_store_short v[48:49], v32, off
	v_mul_f32_e32 v32, v99, v173
	v_mov_b32_dpp v16, v0 row_half_mirror row_mask:0xf bank_mask:0xf bound_ctrl:1
	v_mov_b32_dpp v17, v1 row_half_mirror row_mask:0xf bank_mask:0xf bound_ctrl:1
	v_pk_add_f32 v[0:1], v[0:1], v[16:17]
	v_fma_f32 v32, v172, v146, -v32
	v_cvt_pk_bf16_f32 v32, v32, s0
	v_mov_b32_dpp v16, v0 row_mirror row_mask:0xf bank_mask:0xf bound_ctrl:1
	v_mov_b32_dpp v17, v1 row_mirror row_mask:0xf bank_mask:0xf bound_ctrl:1
	v_pk_add_f32 v[0:1], v[0:1], v[16:17]
	ds_bpermute_b32 v16, v199, v0
	ds_bpermute_b32 v17, v199, v1
	global_store_short v[48:49], v32, off offset:64
	s_and_saveexec_b64 s[0:1], s[2:3]
	s_cbranch_execz .LBB0_543
	v_lshlrev_b64 v[32:33], 7, v[170:171]
	v_lshl_add_u64 v[32:33], s[72:73], 0, v[32:33]
	s_waitcnt lgkmcnt(0)
	v_pk_add_f32 v[0:1], v[0:1], v[16:17]
	global_store_dwordx2 v[32:33], v[0:1], off
.LBB0_543:
	s_or_b64 exec, exec, s[0:1]
	s_waitcnt vmcnt(40)
	v_lshlrev_b32_e32 v1, 16, v236
	v_lshlrev_b32_e32 v0, 16, v235
	s_waitcnt lgkmcnt(0)
	v_pk_mul_f32 v[16:17], v[100:101], v[0:1]
	v_add_f32_e32 v34, v34, v209
	v_pk_mul_f32 v[32:33], v[16:17], v[16:17]
	v_add_f32_e32 v18, v18, v207
	v_add_f32_e32 v32, v32, v33
	v_add_f32_e32 v2, v2, v206
	s_nop 0
	v_add_f32_dpp v32, v32, v32 quad_perm:[1,0,3,2] row_mask:0xf bank_mask:0xf bound_ctrl:1
	s_nop 1
	v_add_f32_dpp v32, v32, v32 quad_perm:[2,3,0,1] row_mask:0xf bank_mask:0xf bound_ctrl:1
	s_nop 1
	v_add_f32_dpp v32, v32, v32 row_half_mirror row_mask:0xf bank_mask:0xf bound_ctrl:1
	s_nop 1
	v_add_f32_dpp v32, v32, v32 row_mirror row_mask:0xf bank_mask:0xf bound_ctrl:1
	ds_bpermute_b32 v33, v199, v32
	s_waitcnt lgkmcnt(0)
	v_add_f32_e32 v32, v32, v33
	v_mul_f32_e32 v33, 0x4f800000, v32
	v_cmp_gt_f32_e32 vcc, s75, v32
	s_nop 1
	v_cndmask_b32_e32 v32, v32, v33, vcc
	v_sqrt_f32_e32 v33, v32
	s_nop 0
	v_add_u32_e32 v48, -1, v33
	v_add_u32_e32 v49, 1, v33
	v_fma_f32 v99, -v48, v33, v32
	v_fma_f32 v103, -v49, v33, v32
	v_cmp_ge_f32_e64 s[0:1], 0, v99
	s_nop 1
	v_cndmask_b32_e64 v33, v33, v48, s[0:1]
	v_cmp_lt_f32_e64 s[0:1], 0, v103
	s_nop 1
	v_cndmask_b32_e64 v33, v33, v49, s[0:1]
	v_mul_f32_e32 v48, 0x37800000, v33
	v_cndmask_b32_e32 v33, v33, v48, vcc
	v_cmp_class_f32_e32 vcc, v32, v201
	v_add_f32_e32 v49, v50, v210
	s_nop 0
	v_cndmask_b32_e32 v32, v33, v32, vcc
	v_max_f32_e32 v103, 0x2b8cbccc, v32
	v_div_scale_f32 v32, s[0:1], v103, v103, 1.0
	v_rcp_f32_e32 v145, v32
	s_nop 0
	v_fma_f32 v48, -v32, v145, 1.0
	v_div_scale_f32 v33, vcc, 1.0, v103, 1.0
	v_fmac_f32_e32 v145, v48, v145
	v_mul_f32_e32 v178, v33, v145
	v_fma_f32 v48, -v32, v178, v33
	v_fmac_f32_e32 v178, v48, v145
	v_fma_f32 v179, -v32, v178, v33
	v_max_f32_e64 v180, -v49, 0
	s_nop 0
	s_nop 1
	v_mul_f32_e64 v50, |v49|, s76
	v_exp_f32_e32 v50, v50
	v_lshl_add_u64 v[170:171], s[54:55], 0, v[166:167]
	s_nop 0
	v_add_f32_e32 v32, 1.0, v50
	v_log_f32_e32 v32, v32
	s_nop 0
	v_mul_f32_e32 v32, 0x3f317218, v32
	v_add_f32_e32 v32, v180, v32
	v_sub_f32_e32 v32, -0.5, v32
	v_div_fmas_f32 v99, v179, v145, v178
	v_div_fixup_f32 v103, v99, v103, 1.0
	v_mul_f32_e32 v16, v16, v103
	v_max_f32_e64 v180, -v18, 0
	v_mul_f32_e32 v34, 0xbfb8aa3b, v34
	v_exp_f32_e32 v34, v34
	s_nop 0
	v_add_f32_e32 v34, 1.0, v34
	v_div_scale_f32 v48, s[0:1], v34, v34, 1.0
	v_rcp_f32_e32 v49, v48
	s_nop 1
	v_mul_f32_e32 v32, 0x3fb8aa3b, v32
	v_exp_f32_e32 v32, v32
	v_fma_f32 v33, -v48, v49, 1.0
	v_fmac_f32_e32 v49, v33, v49
	v_div_scale_f32 v33, vcc, 1.0, v34, 1.0
	v_mul_f32_e32 v50, v33, v49
	v_fma_f32 v99, -v48, v50, v33
	v_fmac_f32_e32 v50, v99, v49
	v_fma_f32 v33, -v48, v50, v33
	v_div_fmas_f32 v33, v33, v49, v50
	v_div_fixup_f32 v33, v33, v34, 1.0
	v_add_f32_e32 v34, -1.0, v33
	v_fma_f32 v34, v208, v34, 1.0
	v_mul_f32_e32 v0, v34, v0
	v_cvt_pk_bf16_f32 v34, v32, 0
	v_cvt_pk_bf16_f32 v50, v16, 0
	v_mul_f32_e32 v16, v33, v16
	v_lshl_add_u64 v[32:33], s[20:21], 0, v[166:167]
	v_cvt_pk_bf16_f32 v0, v0, 0
	v_cvt_pk_bf16_f32 v16, v16, 0
	global_store_short v[170:171], v34, off
	global_store_short v[168:169], v0, off
	global_store_short v[32:33], v50, off
	v_lshl_add_u64 v[32:33], s[18:19], 0, v[166:167]
	global_store_short v[32:33], v16, off
	v_lshlrev_b32_e32 v33, 16, v0
	v_lshlrev_b32_e32 v0, 16, v16
	v_lshlrev_b32_e32 v16, 16, v34
	v_mul_f32_e32 v34, 0xbfb8aa3b, v16
	v_fma_f32 v48, v16, s76, -v34
	v_fmac_f32_e32 v48, 0xb2a5705f, v16
	v_mul_f32_e32 v34, 0xbfb8aa3b, v16
	v_exp_f32_e32 v34, v34
	v_lshlrev_b32_e32 v32, 16, v233
	v_mov_b32_e32 v49, v32
	v_fma_f32 v145, v0, v32, 0
	v_pk_mul_f32 v[48:49], v[48:49], v[32:33]
	v_mov_b32_e32 v0, v34
	v_lshlrev_b32_e32 v50, 16, v50
	s_nop 1
	v_mul_f32_e64 v18, |v18|, s76
	v_exp_f32_e32 v18, v18
	s_nop 1
	v_add_f32_e32 v34, 1.0, v18
	v_log_f32_e32 v34, v34
	s_nop 0
	v_mul_f32_e32 v18, 0x3f317218, v34
	v_add_f32_e32 v18, v180, v18
	v_sub_f32_e32 v18, -0.5, v18
	v_mul_f32_e32 v34, 0x3fb8aa3b, v18
	v_exp_f32_e32 v34, v34
	v_mov_b32_e32 v166, v0
	v_mov_b32_e32 v0, v34
	v_lshlrev_b32_e32 v146, 16, v230
	s_nop 1
	v_mul_f32_e32 v2, 0xbfb8aa3b, v2
	v_exp_f32_e32 v2, v2
	s_nop 0
	v_add_f32_e32 v2, 1.0, v2
	v_div_scale_f32 v16, s[0:1], v2, v2, 1.0
	v_rcp_f32_e32 v34, v16
	s_nop 0
	v_fma_f32 v18, -v16, v34, 1.0
	v_fmac_f32_e32 v34, v18, v34
	v_div_scale_f32 v18, vcc, 1.0, v2, 1.0
	v_mul_f32_e32 v48, v18, v34
	v_fma_f32 v99, -v16, v48, v18
	v_fmac_f32_e32 v48, v99, v34
	v_fma_f32 v16, -v16, v48, v18
	v_div_fmas_f32 v16, v16, v34, v48
	v_div_fixup_f32 v2, v16, v2, 1.0
	v_mul_f32_e32 v16, v17, v103
	v_add_f32_e32 v17, -1.0, v2
	v_fma_f32 v17, v205, v17, 1.0
	v_mul_f32_e32 v1, v17, v1
	v_cvt_pk_bf16_f32 v17, v0, 0
	v_mul_f32_e32 v0, v2, v16
	v_cvt_pk_bf16_f32 v18, v1, 0
	v_cvt_pk_bf16_f32 v34, v16, 0
	v_cvt_pk_bf16_f32 v2, v0, 0
	v_lshl_add_u64 v[0:1], s[20:21], 0, v[162:163]
	global_store_short v[170:171], v17, off offset:64
	global_store_short v[164:165], v18, off
	global_store_short v[0:1], v34, off
	v_lshl_add_u64 v[0:1], s[18:19], 0, v[162:163]
	global_store_short v[0:1], v2, off
	v_lshlrev_b32_e32 v0, 16, v2
	v_lshlrev_b32_e32 v2, 16, v17
	v_mul_f32_e32 v1, 0xbfb8aa3b, v2
	v_fma_f32 v16, v2, s76, -v1
	v_rndne_f32_e32 v17, v1
	v_fmac_f32_e32 v16, 0xb2a5705f, v2
	v_sub_f32_e32 v1, v1, v17
	v_add_f32_e32 v1, v1, v16
	v_exp_f32_e32 v16, v1
	v_lshlrev_b32_e32 v147, 16, v18
	v_mov_b32_e32 v1, v146
	v_fmac_f32_e32 v145, v0, v146
	v_pk_mul_f32 v[0:1], v[0:1], v[146:147]
	s_nop 0
	v_add_f32_dpp v16, v145, v145 quad_perm:[1,0,3,2] row_mask:0xf bank_mask:0xf bound_ctrl:1
	s_nop 1
	v_add_f32_dpp v16, v16, v16 quad_perm:[2,3,0,1] row_mask:0xf bank_mask:0xf bound_ctrl:1
	v_mov_b32_e32 v48, v33
	v_mov_b32_e32 v33, v68
	v_add_f32_dpp v16, v16, v16 row_half_mirror row_mask:0xf bank_mask:0xf bound_ctrl:1
	v_mul_f32_e32 v2, 0xbfb8aa3b, v2
	v_exp_f32_e32 v2, v2
	v_lshlrev_b32_e32 v18, 16, v34
	v_add_f32_dpp v16, v16, v16 row_mirror row_mask:0xf bank_mask:0xf bound_ctrl:1
	ds_bpermute_b32 v17, v199, v16
	v_mov_b32_e32 v0, v147
	v_mov_b32_e32 v147, v204
	s_waitcnt lgkmcnt(0)
	v_add_f32_e32 v34, v16, v17
	v_pk_fma_f32 v[16:17], v[48:49], v[32:33], 0 op_sel_hi:[1,1,0]
	v_mul_f32_e32 v33, v34, v50
	v_pk_fma_f32 v[0:1], v[0:1], v[146:147], v[16:17]
	v_mul_f32_e32 v18, v34, v18
	v_lshlrev_b64 v[48:49], 11, v[160:161]
	v_mov_b32_dpp v16, v0 quad_perm:[1,0,3,2] row_mask:0xf bank_mask:0xf bound_ctrl:1
	v_mov_b32_dpp v17, v1 quad_perm:[1,0,3,2] row_mask:0xf bank_mask:0xf bound_ctrl:1
	v_pk_add_f32 v[0:1], v[0:1], v[16:17]
	v_fma_f32 v32, v166, v32, -v33
	v_fma_f32 v2, v2, v146, -v18
	v_mov_b32_dpp v16, v0 quad_perm:[2,3,0,1] row_mask:0xf bank_mask:0xf bound_ctrl:1
	v_mov_b32_dpp v17, v1 quad_perm:[2,3,0,1] row_mask:0xf bank_mask:0xf bound_ctrl:1
	v_pk_add_f32 v[0:1], v[0:1], v[16:17]
	v_lshl_add_u64 v[48:49], v[64:65], 0, v[48:49]
	v_cvt_pk_bf16_f32 v32, v32, s0
	v_mov_b32_dpp v16, v0 row_half_mirror row_mask:0xf bank_mask:0xf bound_ctrl:1
	v_mov_b32_dpp v17, v1 row_half_mirror row_mask:0xf bank_mask:0xf bound_ctrl:1
	v_pk_add_f32 v[0:1], v[0:1], v[16:17]
	v_cvt_pk_bf16_f32 v2, v2, s0
	global_store_short v[48:49], v32, off
	v_mov_b32_dpp v16, v0 row_mirror row_mask:0xf bank_mask:0xf bound_ctrl:1
	v_mov_b32_dpp v17, v1 row_mirror row_mask:0xf bank_mask:0xf bound_ctrl:1
	v_pk_add_f32 v[0:1], v[0:1], v[16:17]
	ds_bpermute_b32 v16, v199, v0
	ds_bpermute_b32 v17, v199, v1
	global_store_short v[48:49], v2, off offset:64
	s_and_saveexec_b64 s[0:1], s[2:3]
	s_cbranch_execz .LBB0_545
	v_lshlrev_b64 v[32:33], 7, v[160:161]
	v_lshl_add_u64 v[32:33], s[72:73], 0, v[32:33]
	s_waitcnt lgkmcnt(0)
	v_pk_add_f32 v[0:1], v[0:1], v[16:17]
	global_store_dwordx2 v[32:33], v[0:1], off
.LBB0_545:
	s_or_b64 exec, exec, s[0:1]
	s_waitcnt vmcnt(48)
	v_lshlrev_b32_e32 v1, 16, v232
	v_lshlrev_b32_e32 v0, 16, v231
	s_waitcnt lgkmcnt(0)
	v_pk_mul_f32 v[16:17], v[100:101], v[0:1]
	v_add_f32_e32 v35, v35, v209
	v_pk_mul_f32 v[32:33], v[16:17], v[16:17]
	v_add_f32_e32 v3, v3, v206
	v_add_f32_e32 v2, v32, v33
	s_nop 1
	v_add_f32_dpp v2, v2, v2 quad_perm:[1,0,3,2] row_mask:0xf bank_mask:0xf bound_ctrl:1
	s_nop 1
	v_add_f32_dpp v2, v2, v2 quad_perm:[2,3,0,1] row_mask:0xf bank_mask:0xf bound_ctrl:1
	s_nop 1
	v_add_f32_dpp v2, v2, v2 row_half_mirror row_mask:0xf bank_mask:0xf bound_ctrl:1
	s_nop 1
	v_add_f32_dpp v2, v2, v2 row_mirror row_mask:0xf bank_mask:0xf bound_ctrl:1
	ds_bpermute_b32 v18, v199, v2
	s_waitcnt lgkmcnt(0)
	v_add_f32_e32 v2, v2, v18
	v_mul_f32_e32 v18, 0x4f800000, v2
	v_cmp_gt_f32_e32 vcc, s75, v2
	s_nop 1
	v_cndmask_b32_e32 v2, v2, v18, vcc
	v_sqrt_f32_e32 v18, v2
	s_nop 0
	v_add_u32_e32 v32, -1, v18
	v_add_u32_e32 v33, 1, v18
	v_fma_f32 v34, -v32, v18, v2
	v_fma_f32 v48, -v33, v18, v2
	v_cmp_ge_f32_e64 s[0:1], 0, v34
	s_nop 1
	v_cndmask_b32_e64 v18, v18, v32, s[0:1]
	v_cmp_lt_f32_e64 s[0:1], 0, v48
	v_add_f32_e32 v48, v51, v210
	s_nop 0
	v_cndmask_b32_e64 v18, v18, v33, s[0:1]
	v_mul_f32_e32 v32, 0x37800000, v18
	v_cndmask_b32_e32 v18, v18, v32, vcc
	v_cmp_class_f32_e32 vcc, v2, v201
	s_nop 1
	v_cndmask_b32_e32 v2, v18, v2, vcc
	v_max_f32_e32 v2, 0x2b8cbccc, v2
	v_div_scale_f32 v18, s[0:1], v2, v2, 1.0
	v_rcp_f32_e32 v34, v18
	s_nop 0
	v_fma_f32 v33, -v18, v34, 1.0
	v_div_scale_f32 v32, vcc, 1.0, v2, 1.0
	v_fmac_f32_e32 v34, v33, v34
	v_mul_f32_e32 v103, v32, v34
	v_fma_f32 v33, -v18, v103, v32
	v_fmac_f32_e32 v103, v33, v34
	v_fma_f32 v18, -v18, v103, v32
	v_max_f32_e64 v145, -v48, 0
	v_div_fmas_f32 v18, v18, v34, v103
	v_div_fixup_f32 v2, v18, v2, 1.0
	v_mul_f32_e64 v166, |v48|, s76
	v_exp_f32_e32 v166, v166
	v_mul_f32_e32 v16, v16, v2
	v_cvt_pk_bf16_f32 v103, v16, 0
	v_mul_f32_e32 v2, v17, v2
	s_nop 1
	v_add_f32_e32 v32, 1.0, v166
	v_log_f32_e32 v32, v32
	s_nop 0
	v_mul_f32_e32 v32, 0x3f317218, v32
	v_add_f32_e32 v32, v145, v32
	v_sub_f32_e32 v32, -0.5, v32
	v_mul_f32_e32 v33, 0x3fb8aa3b, v32
	v_exp_f32_e32 v33, v33
	s_nop 0
	v_mov_b32_e32 v18, v33
	s_nop 1
	v_mul_f32_e32 v33, 0xbfb8aa3b, v35
	v_exp_f32_e32 v33, v33
	s_nop 0
	v_add_f32_e32 v33, 1.0, v33
	v_div_scale_f32 v34, s[0:1], v33, v33, 1.0
	v_rcp_f32_e32 v35, v34
	s_nop 0
	v_fma_f32 v32, -v34, v35, 1.0
	v_fmac_f32_e32 v35, v32, v35
	v_div_scale_f32 v32, vcc, 1.0, v33, 1.0
	v_mul_f32_e32 v48, v32, v35
	v_fma_f32 v49, -v34, v48, v32
	v_fmac_f32_e32 v48, v49, v35
	v_fma_f32 v32, -v34, v48, v32
	v_div_fmas_f32 v32, v32, v35, v48
	v_div_fixup_f32 v32, v32, v33, 1.0
	v_add_f32_e32 v33, -1.0, v32
	v_fma_f32 v33, v208, v33, 1.0
	v_mul_f32_e32 v0, v33, v0
	v_cvt_pk_bf16_f32 v18, v18, 0
	v_mul_f32_e32 v16, v32, v16
	v_lshl_add_u64 v[48:49], s[54:55], 0, v[156:157]
	v_lshl_add_u64 v[32:33], s[20:21], 0, v[156:157]
	v_cvt_pk_bf16_f32 v0, v0, 0
	v_cvt_pk_bf16_f32 v16, v16, 0
	global_store_short v[48:49], v18, off
	global_store_short v[158:159], v0, off
	global_store_short v[32:33], v103, off
	v_lshl_add_u64 v[32:33], s[18:19], 0, v[156:157]
	global_store_short v[32:33], v16, off
	v_lshlrev_b32_e32 v33, 16, v0
	v_lshlrev_b32_e32 v0, 16, v16
	v_lshlrev_b32_e32 v16, 16, v18
	v_mul_f32_e32 v18, 0xbfb8aa3b, v16
	v_fma_f32 v34, v16, s76, -v18
	v_fmac_f32_e32 v34, 0xb2a5705f, v16
	v_mul_f32_e32 v18, 0xbfb8aa3b, v16
	v_exp_f32_e32 v18, v18
	s_waitcnt vmcnt(49)
	v_lshlrev_b32_e32 v32, 16, v229
	v_fma_f32 v145, v0, v32, 0
	v_mov_b32_e32 v35, v32
	v_mov_b32_e32 v0, v18
	v_add_f32_e32 v18, v19, v207
	v_pk_mul_f32 v[34:35], v[34:35], v[32:33]
	v_max_f32_e64 v164, -v18, 0
	v_lshlrev_b32_e32 v103, 16, v103
	s_nop 1
	v_mul_f32_e64 v34, |v18|, s76
	v_exp_f32_e32 v34, v34
	s_nop 1
	v_add_f32_e32 v18, 1.0, v34
	v_log_f32_e32 v18, v18
	s_nop 0
	v_mul_f32_e32 v18, 0x3f317218, v18
	v_add_f32_e32 v18, v164, v18
	v_sub_f32_e32 v18, -0.5, v18
	v_mul_f32_e32 v19, 0x3fb8aa3b, v18
	v_exp_f32_e32 v19, v19
	v_mov_b32_e32 v99, v0
	v_mov_b32_e32 v0, v19
	s_nop 0
	s_nop 1
	v_mul_f32_e32 v3, 0xbfb8aa3b, v3
	v_exp_f32_e32 v3, v3
	s_nop 0
	v_add_f32_e32 v3, 1.0, v3
	v_div_scale_f32 v16, s[0:1], v3, v3, 1.0
	v_rcp_f32_e32 v19, v16
	s_nop 0
	v_fma_f32 v18, -v16, v19, 1.0
	v_fmac_f32_e32 v19, v18, v19
	v_div_scale_f32 v18, vcc, 1.0, v3, 1.0
	v_mul_f32_e32 v34, v18, v19
	v_fma_f32 v50, -v16, v34, v18
	v_fmac_f32_e32 v34, v50, v19
	v_fma_f32 v16, -v16, v34, v18
	v_div_fmas_f32 v16, v16, v19, v34
	v_div_fixup_f32 v3, v16, v3, 1.0
	v_add_f32_e32 v16, -1.0, v3
	v_fma_f32 v16, v205, v16, 1.0
	v_mul_f32_e32 v1, v16, v1
	v_cvt_pk_bf16_f32 v18, v0, 0
	v_mul_f32_e32 v0, v3, v2
	v_cvt_pk_bf16_f32 v16, v1, 0
	v_cvt_pk_bf16_f32 v19, v2, 0
	v_cvt_pk_bf16_f32 v2, v0, 0
	v_lshl_add_u64 v[0:1], s[20:21], 0, v[152:153]
	global_store_short v[48:49], v18, off offset:64
	global_store_short v[154:155], v16, off
	global_store_short v[0:1], v19, off
	v_lshl_add_u64 v[0:1], s[18:19], 0, v[152:153]
	global_store_short v[0:1], v2, off
	v_lshlrev_b32_e32 v0, 16, v2
	v_lshlrev_b32_e32 v2, 16, v18
	v_mul_f32_e32 v1, 0xbfb8aa3b, v2
	v_fma_f32 v3, v2, s76, -v1
	v_rndne_f32_e32 v18, v1
	v_fmac_f32_e32 v3, 0xb2a5705f, v2
	v_sub_f32_e32 v1, v1, v18
	v_add_f32_e32 v1, v1, v3
	v_exp_f32_e32 v3, v1
	v_lshlrev_b32_e32 v17, 16, v16
	s_waitcnt vmcnt(52)
	v_lshlrev_b32_e32 v16, 16, v228
	v_mov_b32_e32 v1, v16
	v_fmac_f32_e32 v145, v0, v16
	v_pk_mul_f32 v[0:1], v[0:1], v[16:17]
	s_nop 0
	v_add_f32_dpp v3, v145, v145 quad_perm:[1,0,3,2] row_mask:0xf bank_mask:0xf bound_ctrl:1
	s_nop 1
	v_add_f32_dpp v3, v3, v3 quad_perm:[2,3,0,1] row_mask:0xf bank_mask:0xf bound_ctrl:1
	v_mov_b32_e32 v34, v33
	v_mov_b32_e32 v33, v68
	v_add_f32_dpp v3, v3, v3 row_half_mirror row_mask:0xf bank_mask:0xf bound_ctrl:1
	v_mul_f32_e32 v48, 0xbfb8aa3b, v2
	v_exp_f32_e32 v48, v48
	v_mov_b32_e32 v0, v17
	v_add_f32_dpp v3, v3, v3 row_mirror row_mask:0xf bank_mask:0xf bound_ctrl:1
	ds_bpermute_b32 v18, v199, v3
	v_mov_b32_e32 v17, v204
	v_lshlrev_b32_e32 v49, 16, v19
	s_waitcnt lgkmcnt(0)
	v_add_f32_e32 v50, v3, v18
	v_pk_fma_f32 v[2:3], v[34:35], v[32:33], 0 op_sel_hi:[1,1,0]
	v_lshlrev_b64 v[18:19], 11, v[142:143]
	v_pk_fma_f32 v[0:1], v[0:1], v[16:17], v[2:3]
	v_mul_f32_e32 v17, v50, v103
	v_fma_f32 v17, v99, v32, -v17
	v_mov_b32_dpp v2, v0 quad_perm:[1,0,3,2] row_mask:0xf bank_mask:0xf bound_ctrl:1
	v_mov_b32_dpp v3, v1 quad_perm:[1,0,3,2] row_mask:0xf bank_mask:0xf bound_ctrl:1
	v_pk_add_f32 v[0:1], v[0:1], v[2:3]
	v_lshl_add_u64 v[18:19], v[64:65], 0, v[18:19]
	v_cvt_pk_bf16_f32 v17, v17, s0
	v_mov_b32_dpp v2, v0 quad_perm:[2,3,0,1] row_mask:0xf bank_mask:0xf bound_ctrl:1
	v_mov_b32_dpp v3, v1 quad_perm:[2,3,0,1] row_mask:0xf bank_mask:0xf bound_ctrl:1
	v_pk_add_f32 v[0:1], v[0:1], v[2:3]
	global_store_short v[18:19], v17, off
	v_mul_f32_e32 v17, v50, v49
	v_mov_b32_dpp v2, v0 row_half_mirror row_mask:0xf bank_mask:0xf bound_ctrl:1
	v_mov_b32_dpp v3, v1 row_half_mirror row_mask:0xf bank_mask:0xf bound_ctrl:1
	v_pk_add_f32 v[0:1], v[0:1], v[2:3]
	v_fma_f32 v16, v48, v16, -v17
	v_cvt_pk_bf16_f32 v16, v16, s0
	v_mov_b32_dpp v2, v0 row_mirror row_mask:0xf bank_mask:0xf bound_ctrl:1
	v_mov_b32_dpp v3, v1 row_mirror row_mask:0xf bank_mask:0xf bound_ctrl:1
	v_pk_add_f32 v[0:1], v[0:1], v[2:3]
	ds_bpermute_b32 v2, v199, v0
	ds_bpermute_b32 v3, v199, v1
	global_store_short v[18:19], v16, off offset:64
	s_and_saveexec_b64 s[0:1], s[2:3]
	s_cbranch_execz .LBB0_547
	v_lshlrev_b64 v[16:17], 7, v[142:143]
	v_lshl_add_u64 v[16:17], s[72:73], 0, v[16:17]
	s_waitcnt lgkmcnt(0)
	v_pk_add_f32 v[0:1], v[0:1], v[2:3]
	global_store_dwordx2 v[16:17], v[0:1], off
.LBB0_547:
	s_or_b64 exec, exec, s[0:1]
	v_lshlrev_b32_e32 v1, 16, v227
	v_lshlrev_b32_e32 v0, 16, v226
	s_waitcnt lgkmcnt(0)
	v_pk_mul_f32 v[2:3], v[100:101], v[0:1]
	v_add_f32_e32 v4, v4, v206
	v_pk_mul_f32 v[16:17], v[2:3], v[2:3]
	s_nop 0
	v_add_f32_e32 v16, v16, v17
	s_nop 1
	v_add_f32_dpp v16, v16, v16 quad_perm:[1,0,3,2] row_mask:0xf bank_mask:0xf bound_ctrl:1
	s_nop 1
	v_add_f32_dpp v16, v16, v16 quad_perm:[2,3,0,1] row_mask:0xf bank_mask:0xf bound_ctrl:1
	s_nop 1
	v_add_f32_dpp v16, v16, v16 row_half_mirror row_mask:0xf bank_mask:0xf bound_ctrl:1
	s_nop 1
	v_add_f32_dpp v16, v16, v16 row_mirror row_mask:0xf bank_mask:0xf bound_ctrl:1
	ds_bpermute_b32 v17, v199, v16
	s_waitcnt lgkmcnt(0)
	v_add_f32_e32 v16, v16, v17
	v_mul_f32_e32 v17, 0x4f800000, v16
	v_cmp_gt_f32_e32 vcc, s75, v16
	s_nop 1
	v_cndmask_b32_e32 v16, v16, v17, vcc
	v_sqrt_f32_e32 v17, v16
	s_nop 0
	v_add_u32_e32 v18, -1, v17
	v_add_u32_e32 v19, 1, v17
	v_fma_f32 v32, -v18, v17, v16
	v_fma_f32 v33, -v19, v17, v16
	v_cmp_ge_f32_e64 s[0:1], 0, v32
	s_nop 1
	v_cndmask_b32_e64 v17, v17, v18, s[0:1]
	v_cmp_lt_f32_e64 s[0:1], 0, v33
	s_nop 1
	v_cndmask_b32_e64 v17, v17, v19, s[0:1]
	v_mul_f32_e32 v18, 0x37800000, v17
	v_cndmask_b32_e32 v17, v17, v18, vcc
	v_cmp_class_f32_e32 vcc, v16, v201
	v_add_f32_e32 v19, v52, v210
	s_nop 0
	v_cndmask_b32_e32 v16, v17, v16, vcc
	v_max_f32_e32 v103, 0x2b8cbccc, v16
	v_div_scale_f32 v16, s[0:1], v103, v103, 1.0
	v_rcp_f32_e32 v145, v16
	s_nop 0
	v_fma_f32 v18, -v16, v145, 1.0
	v_div_scale_f32 v17, vcc, 1.0, v103, 1.0
	v_fmac_f32_e32 v145, v18, v145
	v_mul_f32_e32 v146, v17, v145
	v_fma_f32 v18, -v16, v146, v17
	v_fmac_f32_e32 v146, v18, v145
	v_fma_f32 v52, -v16, v146, v17
	v_max_f32_e64 v147, -v19, 0
	s_nop 0
	s_nop 1
	v_mul_f32_e64 v152, |v19|, s76
	v_exp_f32_e32 v152, v152
	s_nop 1
	v_add_f32_e32 v16, 1.0, v152
	v_log_f32_e32 v16, v16
	s_nop 0
	v_mul_f32_e32 v16, 0x3f317218, v16
	v_add_f32_e32 v16, v147, v16
	v_sub_f32_e32 v16, -0.5, v16
	v_add_f32_e32 v19, v36, v209
	v_div_fmas_f32 v34, v52, v145, v146
	v_div_fixup_f32 v36, v34, v103, 1.0
	v_mul_f32_e32 v2, v2, v36
	v_cvt_pk_bf16_f32 v52, v2, 0
	v_mul_f32_e32 v18, 0xbfb8aa3b, v19
	v_exp_f32_e32 v18, v18
	s_nop 0
	v_add_f32_e32 v18, 1.0, v18
	v_div_scale_f32 v19, s[0:1], v18, v18, 1.0
	v_rcp_f32_e32 v32, v19
	v_mul_f32_e32 v3, v3, v36
	s_nop 0
	s_nop 1
	v_mul_f32_e32 v16, 0x3fb8aa3b, v16
	v_exp_f32_e32 v16, v16
	v_fma_f32 v17, -v19, v32, 1.0
	v_fmac_f32_e32 v32, v17, v32
	v_div_scale_f32 v17, vcc, 1.0, v18, 1.0
	v_mul_f32_e32 v33, v17, v32
	v_fma_f32 v34, -v19, v33, v17
	v_fmac_f32_e32 v33, v34, v32
	v_fma_f32 v17, -v19, v33, v17
	v_div_fmas_f32 v17, v17, v32, v33
	v_div_fixup_f32 v17, v17, v18, 1.0
	v_add_f32_e32 v18, -1.0, v17
	v_fma_f32 v18, v208, v18, 1.0
	v_mul_f32_e32 v0, v18, v0
	v_cvt_pk_bf16_f32 v18, v16, 0
	v_mul_f32_e32 v2, v17, v2
	v_lshl_add_u64 v[32:33], s[54:55], 0, v[138:139]
	v_lshl_add_u64 v[16:17], s[20:21], 0, v[138:139]
	v_cvt_pk_bf16_f32 v0, v0, 0
	v_cvt_pk_bf16_f32 v2, v2, 0
	global_store_short v[32:33], v18, off
	global_store_short v[140:141], v0, off
	global_store_short v[16:17], v52, off
	v_lshl_add_u64 v[16:17], s[18:19], 0, v[138:139]
	global_store_short v[16:17], v2, off
	v_lshlrev_b32_e32 v17, 16, v0
	v_lshlrev_b32_e32 v0, 16, v2
	v_lshlrev_b32_e32 v2, 16, v18
	v_mul_f32_e32 v18, 0xbfb8aa3b, v2
	v_fma_f32 v19, v2, s76, -v18
	v_rndne_f32_e32 v34, v18
	v_fmac_f32_e32 v19, 0xb2a5705f, v2
	v_sub_f32_e32 v18, v18, v34
	s_waitcnt vmcnt(57)
	v_lshlrev_b32_e32 v16, 16, v225
	v_add_f32_e32 v18, v18, v19
	v_mul_f32_e32 v35, 0xbfb8aa3b, v2
	v_exp_f32_e32 v35, v35
	v_mov_b32_e32 v19, v16
	v_pk_mul_f32 v[18:19], v[18:19], v[16:17]
	v_fma_f32 v103, v0, v16, 0
	v_add_f32_e32 v18, v20, v207
	v_mov_b32_e32 v0, v35
	v_max_f32_e64 v145, -v18, 0
	s_nop 1
	v_mul_f32_e64 v18, |v18|, s76
	v_exp_f32_e32 v18, v18
	v_lshlrev_b32_e32 v50, 16, v52
	s_nop 0
	v_add_f32_e32 v20, 1.0, v18
	v_log_f32_e32 v20, v20
	s_nop 0
	v_mul_f32_e32 v18, 0x3f317218, v20
	v_add_f32_e32 v18, v145, v18
	v_sub_f32_e32 v18, -0.5, v18
	v_mul_f32_e32 v20, 0x3fb8aa3b, v18
	v_exp_f32_e32 v20, v20
	v_mov_b32_e32 v49, v0
	v_mov_b32_e32 v0, v20
	s_nop 0
	s_nop 1
	v_mul_f32_e32 v2, 0xbfb8aa3b, v4
	v_exp_f32_e32 v2, v2
	s_nop 0
	v_add_f32_e32 v2, 1.0, v2
	v_div_scale_f32 v4, s[0:1], v2, v2, 1.0
	v_rcp_f32_e32 v20, v4
	s_nop 0
	v_fma_f32 v18, -v4, v20, 1.0
	v_fmac_f32_e32 v20, v18, v20
	v_div_scale_f32 v18, vcc, 1.0, v2, 1.0
	v_mul_f32_e32 v34, v18, v20
	v_fma_f32 v35, -v4, v34, v18
	v_fmac_f32_e32 v34, v35, v20
	v_fma_f32 v4, -v4, v34, v18
	v_div_fmas_f32 v4, v4, v20, v34
	v_div_fixup_f32 v2, v4, v2, 1.0
	v_add_f32_e32 v4, -1.0, v2
	v_fma_f32 v4, v205, v4, 1.0
	v_mul_f32_e32 v1, v4, v1
	v_cvt_pk_bf16_f32 v4, v0, 0
	v_mul_f32_e32 v0, v2, v3
	v_cvt_pk_bf16_f32 v18, v1, 0
	v_cvt_pk_bf16_f32 v20, v3, 0
	v_cvt_pk_bf16_f32 v2, v0, 0
	v_lshl_add_u64 v[0:1], s[20:21], 0, v[134:135]
	global_store_short v[32:33], v4, off offset:64
	global_store_short v[136:137], v18, off
	global_store_short v[0:1], v20, off
	v_lshl_add_u64 v[0:1], s[18:19], 0, v[134:135]
	global_store_short v[0:1], v2, off
	v_lshlrev_b32_e32 v0, 16, v2
	v_lshlrev_b32_e32 v2, 16, v4
	v_mul_f32_e32 v1, 0xbfb8aa3b, v2
	v_fma_f32 v3, v2, s76, -v1
	v_rndne_f32_e32 v4, v1
	v_fmac_f32_e32 v3, 0xb2a5705f, v2
	v_sub_f32_e32 v1, v1, v4
	v_add_f32_e32 v1, v1, v3
	v_exp_f32_e32 v3, v1
	s_waitcnt vmcnt(60)
	v_lshlrev_b32_e32 v32, 16, v224
	v_lshlrev_b32_e32 v33, 16, v18
	v_mov_b32_e32 v1, v32
	v_fmac_f32_e32 v103, v0, v32
	v_pk_mul_f32 v[0:1], v[0:1], v[32:33]
	s_nop 0
	v_add_f32_dpp v3, v103, v103 quad_perm:[1,0,3,2] row_mask:0xf bank_mask:0xf bound_ctrl:1
	s_nop 1
	v_add_f32_dpp v3, v3, v3 quad_perm:[2,3,0,1] row_mask:0xf bank_mask:0xf bound_ctrl:1
	v_mov_b32_e32 v18, v17
	v_mov_b32_e32 v17, v68
	v_add_f32_dpp v3, v3, v3 row_half_mirror row_mask:0xf bank_mask:0xf bound_ctrl:1
	v_mul_f32_e32 v34, 0xbfb8aa3b, v2
	v_exp_f32_e32 v34, v34
	v_mov_b32_e32 v0, v33
	v_add_f32_dpp v3, v3, v3 row_mirror row_mask:0xf bank_mask:0xf bound_ctrl:1
	ds_bpermute_b32 v4, v199, v3
	v_mov_b32_e32 v33, v204
	v_lshlrev_b32_e32 v20, 16, v20
	s_waitcnt lgkmcnt(0)
	v_add_f32_e32 v4, v3, v4
	v_pk_fma_f32 v[2:3], v[18:19], v[16:17], 0 op_sel_hi:[1,1,0]
	v_mul_f32_e32 v17, v4, v50
	v_pk_fma_f32 v[0:1], v[0:1], v[32:33], v[2:3]
	v_mul_f32_e32 v4, v4, v20
	v_lshlrev_b64 v[18:19], 11, v[132:133]
	v_mov_b32_dpp v2, v0 quad_perm:[1,0,3,2] row_mask:0xf bank_mask:0xf bound_ctrl:1
	v_mov_b32_dpp v3, v1 quad_perm:[1,0,3,2] row_mask:0xf bank_mask:0xf bound_ctrl:1
	v_pk_add_f32 v[0:1], v[0:1], v[2:3]
	v_fma_f32 v16, v49, v16, -v17
	v_fma_f32 v4, v34, v32, -v4
	v_mov_b32_dpp v2, v0 quad_perm:[2,3,0,1] row_mask:0xf bank_mask:0xf bound_ctrl:1
	v_mov_b32_dpp v3, v1 quad_perm:[2,3,0,1] row_mask:0xf bank_mask:0xf bound_ctrl:1
	v_pk_add_f32 v[0:1], v[0:1], v[2:3]
	v_lshl_add_u64 v[18:19], v[64:65], 0, v[18:19]
	v_cvt_pk_bf16_f32 v16, v16, s0
	v_mov_b32_dpp v2, v0 row_half_mirror row_mask:0xf bank_mask:0xf bound_ctrl:1
	v_mov_b32_dpp v3, v1 row_half_mirror row_mask:0xf bank_mask:0xf bound_ctrl:1
	v_pk_add_f32 v[0:1], v[0:1], v[2:3]
	v_cvt_pk_bf16_f32 v4, v4, s0
	global_store_short v[18:19], v16, off
	v_mov_b32_dpp v2, v0 row_mirror row_mask:0xf bank_mask:0xf bound_ctrl:1
	v_mov_b32_dpp v3, v1 row_mirror row_mask:0xf bank_mask:0xf bound_ctrl:1
	v_pk_add_f32 v[0:1], v[0:1], v[2:3]
	ds_bpermute_b32 v2, v199, v0
	ds_bpermute_b32 v3, v199, v1
	global_store_short v[18:19], v4, off offset:64
	s_and_saveexec_b64 s[0:1], s[2:3]
	s_cbranch_execz .LBB0_549
	v_lshlrev_b64 v[16:17], 7, v[132:133]
	v_lshl_add_u64 v[16:17], s[72:73], 0, v[16:17]
	s_waitcnt lgkmcnt(0)
	v_pk_add_f32 v[0:1], v[0:1], v[2:3]
	global_store_dwordx2 v[16:17], v[0:1], off
.LBB0_549:
	s_or_b64 exec, exec, s[0:1]
	s_waitcnt vmcnt(56)
	v_lshlrev_b32_e32 v1, 16, v223
	v_lshlrev_b32_e32 v0, 16, v222
	s_waitcnt lgkmcnt(0)
	v_pk_mul_f32 v[2:3], v[100:101], v[0:1]
	v_add_f32_e32 v5, v5, v206
	v_pk_mul_f32 v[16:17], v[2:3], v[2:3]
	s_nop 0
	v_add_f32_e32 v4, v16, v17
	s_nop 1
	v_add_f32_dpp v4, v4, v4 quad_perm:[1,0,3,2] row_mask:0xf bank_mask:0xf bound_ctrl:1
	s_nop 1
	v_add_f32_dpp v4, v4, v4 quad_perm:[2,3,0,1] row_mask:0xf bank_mask:0xf bound_ctrl:1
	s_nop 1
	v_add_f32_dpp v4, v4, v4 row_half_mirror row_mask:0xf bank_mask:0xf bound_ctrl:1
	s_nop 1
	v_add_f32_dpp v4, v4, v4 row_mirror row_mask:0xf bank_mask:0xf bound_ctrl:1
	ds_bpermute_b32 v16, v199, v4
	s_waitcnt lgkmcnt(0)
	v_add_f32_e32 v4, v4, v16
	v_mul_f32_e32 v16, 0x4f800000, v4
	v_cmp_gt_f32_e32 vcc, s75, v4
	s_nop 1
	v_cndmask_b32_e32 v4, v4, v16, vcc
	v_sqrt_f32_e32 v16, v4
	s_nop 0
	v_add_u32_e32 v17, -1, v16
	v_add_u32_e32 v18, 1, v16
	v_fma_f32 v19, -v17, v16, v4
	v_fma_f32 v20, -v18, v16, v4
	v_cmp_ge_f32_e64 s[0:1], 0, v19
	v_add_f32_e32 v19, v53, v210
	s_nop 0
	v_cndmask_b32_e64 v16, v16, v17, s[0:1]
	v_cmp_lt_f32_e64 s[0:1], 0, v20
	s_nop 1
	v_cndmask_b32_e64 v16, v16, v18, s[0:1]
	v_mul_f32_e32 v17, 0x37800000, v16
	v_cndmask_b32_e32 v16, v16, v17, vcc
	v_cmp_class_f32_e32 vcc, v4, v201
	s_nop 1
	v_cndmask_b32_e32 v4, v16, v4, vcc
	v_max_f32_e32 v4, 0x2b8cbccc, v4
	v_div_scale_f32 v16, s[0:1], v4, v4, 1.0
	v_rcp_f32_e32 v20, v16
	v_div_scale_f32 v17, vcc, 1.0, v4, 1.0
	v_fma_f32 v18, -v16, v20, 1.0
	v_fmac_f32_e32 v20, v18, v20
	v_mul_f32_e32 v36, v17, v20
	v_fma_f32 v18, -v16, v36, v17
	v_fmac_f32_e32 v36, v18, v20
	v_fma_f32 v103, -v16, v36, v17
	v_max_f32_e64 v132, -v19, 0
	v_div_fmas_f32 v20, v103, v20, v36
	v_div_fixup_f32 v4, v20, v4, 1.0
	v_mul_f32_e32 v2, v2, v4
	v_mul_f32_e64 v133, |v19|, s76
	v_exp_f32_e32 v133, v133
	v_cvt_pk_bf16_f32 v103, v2, 0
	v_mul_f32_e32 v3, v3, v4
	s_nop 1
	v_add_f32_e32 v16, 1.0, v133
	v_log_f32_e32 v16, v16
	s_nop 0
	v_mul_f32_e32 v16, 0x3f317218, v16
	v_add_f32_e32 v16, v132, v16
	v_sub_f32_e32 v16, -0.5, v16
	v_add_f32_e32 v19, v37, v209
	s_nop 1
	v_mul_f32_e32 v18, 0xbfb8aa3b, v19
	v_exp_f32_e32 v18, v18
	s_nop 0
	v_add_f32_e32 v18, 1.0, v18
	v_div_scale_f32 v19, s[0:1], v18, v18, 1.0
	v_rcp_f32_e32 v20, v19
	s_nop 1
	v_mul_f32_e32 v16, 0x3fb8aa3b, v16
	v_exp_f32_e32 v16, v16
	v_fma_f32 v17, -v19, v20, 1.0
	v_fmac_f32_e32 v20, v17, v20
	v_div_scale_f32 v17, vcc, 1.0, v18, 1.0
	v_mul_f32_e32 v32, v17, v20
	v_fma_f32 v33, -v19, v32, v17
	v_fmac_f32_e32 v32, v33, v20
	v_fma_f32 v17, -v19, v32, v17
	v_div_fmas_f32 v17, v17, v20, v32
	v_div_fixup_f32 v17, v17, v18, 1.0
	v_add_f32_e32 v18, -1.0, v17
	v_fma_f32 v18, v208, v18, 1.0
	v_mul_f32_e32 v0, v18, v0
	v_cvt_pk_bf16_f32 v18, v16, 0
	v_mul_f32_e32 v2, v17, v2
	v_lshl_add_u64 v[32:33], s[54:55], 0, v[128:129]
	v_lshl_add_u64 v[16:17], s[20:21], 0, v[128:129]
	v_cvt_pk_bf16_f32 v0, v0, 0
	v_cvt_pk_bf16_f32 v2, v2, 0
	global_store_short v[32:33], v18, off
	global_store_short v[130:131], v0, off
	global_store_short v[16:17], v103, off
	v_lshl_add_u64 v[16:17], s[18:19], 0, v[128:129]
	global_store_short v[16:17], v2, off
	v_lshlrev_b32_e32 v17, 16, v0
	v_lshlrev_b32_e32 v0, 16, v2
	v_lshlrev_b32_e32 v2, 16, v18
	v_mul_f32_e32 v18, 0xbfb8aa3b, v2
	v_fma_f32 v19, v2, s76, -v18
	v_rndne_f32_e32 v20, v18
	v_fmac_f32_e32 v19, 0xb2a5705f, v2
	v_sub_f32_e32 v18, v18, v20
	v_add_f32_e32 v18, v18, v19
	v_lshlrev_b32_e32 v16, 16, v221
	v_mul_f32_e32 v34, 0xbfb8aa3b, v2
	v_exp_f32_e32 v34, v34
	v_mov_b32_e32 v19, v16
	v_pk_mul_f32 v[18:19], v[18:19], v[16:17]
	v_fma_f32 v130, v0, v16, 0
	v_add_f32_e32 v18, v21, v207
	v_mov_b32_e32 v0, v34
	v_max_f32_e64 v131, -v18, 0
	s_nop 1
	v_mul_f32_e64 v18, |v18|, s76
	v_exp_f32_e32 v18, v18
	v_lshlrev_b32_e32 v37, 16, v103
	s_nop 0
	v_add_f32_e32 v20, 1.0, v18
	v_log_f32_e32 v20, v20
	s_nop 0
	v_mul_f32_e32 v18, 0x3f317218, v20
	v_add_f32_e32 v18, v131, v18
	v_sub_f32_e32 v18, -0.5, v18
	v_mul_f32_e32 v20, 0x3fb8aa3b, v18
	v_exp_f32_e32 v20, v20
	v_mov_b32_e32 v36, v0
	v_mov_b32_e32 v0, v20
	s_nop 0
	s_nop 1
	v_mul_f32_e32 v2, 0xbfb8aa3b, v5
	v_exp_f32_e32 v2, v2
	s_nop 0
	v_add_f32_e32 v2, 1.0, v2
	v_div_scale_f32 v5, s[0:1], v2, v2, 1.0
	v_rcp_f32_e32 v20, v5
	s_nop 0
	v_fma_f32 v18, -v5, v20, 1.0
	v_fmac_f32_e32 v20, v18, v20
	v_div_scale_f32 v18, vcc, 1.0, v2, 1.0
	v_mul_f32_e32 v21, v18, v20
	v_fma_f32 v34, -v5, v21, v18
	v_fmac_f32_e32 v21, v34, v20
	v_fma_f32 v5, -v5, v21, v18
	v_div_fmas_f32 v5, v5, v20, v21
	v_div_fixup_f32 v2, v5, v2, 1.0
	v_add_f32_e32 v4, -1.0, v2
	v_fma_f32 v4, v205, v4, 1.0
	v_mul_f32_e32 v1, v4, v1
	v_cvt_pk_bf16_f32 v18, v0, 0
	v_mul_f32_e32 v0, v2, v3
	v_cvt_pk_bf16_f32 v4, v1, 0
	v_cvt_pk_bf16_f32 v20, v3, 0
	v_cvt_pk_bf16_f32 v2, v0, 0
	v_lshl_add_u64 v[0:1], s[20:21], 0, v[124:125]
	global_store_short v[32:33], v18, off offset:64
	global_store_short v[126:127], v4, off
	global_store_short v[0:1], v20, off
	v_lshl_add_u64 v[0:1], s[18:19], 0, v[124:125]
	global_store_short v[0:1], v2, off
	v_lshlrev_b32_e32 v0, 16, v2
	v_lshlrev_b32_e32 v2, 16, v18
	v_mul_f32_e32 v1, 0xbfb8aa3b, v2
	v_fma_f32 v3, v2, s76, -v1
	v_rndne_f32_e32 v18, v1
	v_fmac_f32_e32 v3, 0xb2a5705f, v2
	v_sub_f32_e32 v1, v1, v18
	v_add_f32_e32 v1, v1, v3
	v_exp_f32_e32 v3, v1
	v_lshlrev_b32_e32 v5, 16, v4
	v_lshlrev_b32_e32 v4, 16, v220
	v_mov_b32_e32 v1, v4
	v_fmac_f32_e32 v130, v0, v4
	v_pk_mul_f32 v[0:1], v[0:1], v[4:5]
	s_nop 0
	v_add_f32_dpp v3, v130, v130 quad_perm:[1,0,3,2] row_mask:0xf bank_mask:0xf bound_ctrl:1
	s_nop 1
	v_add_f32_dpp v3, v3, v3 quad_perm:[2,3,0,1] row_mask:0xf bank_mask:0xf bound_ctrl:1
	v_lshlrev_b32_e32 v20, 16, v20
	v_mul_f32_e32 v21, 0xbfb8aa3b, v2
	v_exp_f32_e32 v21, v21
	v_add_f32_dpp v3, v3, v3 row_half_mirror row_mask:0xf bank_mask:0xf bound_ctrl:1
	v_mov_b32_e32 v0, v5
	v_mov_b32_e32 v5, v204
	v_add_f32_dpp v3, v3, v3 row_mirror row_mask:0xf bank_mask:0xf bound_ctrl:1
	ds_bpermute_b32 v18, v199, v3
	s_waitcnt lgkmcnt(0)
	v_add_f32_e32 v32, v3, v18
	v_mov_b32_e32 v18, v17
	v_mov_b32_e32 v17, v68
	v_pk_fma_f32 v[2:3], v[18:19], v[16:17], 0 op_sel_hi:[1,1,0]
	v_lshlrev_b64 v[18:19], 11, v[122:123]
	v_pk_fma_f32 v[0:1], v[0:1], v[4:5], v[2:3]
	v_mul_f32_e32 v5, v32, v37
	v_fma_f32 v5, v36, v16, -v5
	v_mov_b32_dpp v2, v0 quad_perm:[1,0,3,2] row_mask:0xf bank_mask:0xf bound_ctrl:1
	v_mov_b32_dpp v3, v1 quad_perm:[1,0,3,2] row_mask:0xf bank_mask:0xf bound_ctrl:1
	v_pk_add_f32 v[0:1], v[0:1], v[2:3]
	v_lshl_add_u64 v[18:19], v[64:65], 0, v[18:19]
	v_cvt_pk_bf16_f32 v5, v5, s0
	v_mov_b32_dpp v2, v0 quad_perm:[2,3,0,1] row_mask:0xf bank_mask:0xf bound_ctrl:1
	v_mov_b32_dpp v3, v1 quad_perm:[2,3,0,1] row_mask:0xf bank_mask:0xf bound_ctrl:1
	v_pk_add_f32 v[0:1], v[0:1], v[2:3]
	global_store_short v[18:19], v5, off
	v_mul_f32_e32 v5, v32, v20
	v_mov_b32_dpp v2, v0 row_half_mirror row_mask:0xf bank_mask:0xf bound_ctrl:1
	v_mov_b32_dpp v3, v1 row_half_mirror row_mask:0xf bank_mask:0xf bound_ctrl:1
	v_pk_add_f32 v[0:1], v[0:1], v[2:3]
	v_fma_f32 v4, v21, v4, -v5
	v_cvt_pk_bf16_f32 v4, v4, s0
	v_mov_b32_dpp v2, v0 row_mirror row_mask:0xf bank_mask:0xf bound_ctrl:1
	v_mov_b32_dpp v3, v1 row_mirror row_mask:0xf bank_mask:0xf bound_ctrl:1
	v_pk_add_f32 v[0:1], v[0:1], v[2:3]
	ds_bpermute_b32 v2, v199, v0
	ds_bpermute_b32 v3, v199, v1
	global_store_short v[18:19], v4, off offset:64
	s_and_saveexec_b64 s[0:1], s[2:3]
	s_cbranch_execz .LBB0_551
	v_lshlrev_b64 v[4:5], 7, v[122:123]
	v_lshl_add_u64 v[4:5], s[72:73], 0, v[4:5]
	s_waitcnt lgkmcnt(0)
	v_pk_add_f32 v[0:1], v[0:1], v[2:3]
	global_store_dwordx2 v[4:5], v[0:1], off
.LBB0_551:
	s_or_b64 exec, exec, s[0:1]
	s_waitcnt vmcnt(62)
	v_lshlrev_b32_e32 v1, 16, v219
	v_lshlrev_b32_e32 v0, 16, v218
	s_waitcnt lgkmcnt(0)
	v_pk_mul_f32 v[2:3], v[100:101], v[0:1]
	v_add_f32_e32 v6, v6, v206
	v_pk_mul_f32 v[4:5], v[2:3], v[2:3]
	s_nop 0
	v_add_f32_e32 v4, v4, v5
	s_nop 1
	v_add_f32_dpp v4, v4, v4 quad_perm:[1,0,3,2] row_mask:0xf bank_mask:0xf bound_ctrl:1
	s_nop 1
	v_add_f32_dpp v4, v4, v4 quad_perm:[2,3,0,1] row_mask:0xf bank_mask:0xf bound_ctrl:1
	s_nop 1
	v_add_f32_dpp v4, v4, v4 row_half_mirror row_mask:0xf bank_mask:0xf bound_ctrl:1
	s_nop 1
	v_add_f32_dpp v4, v4, v4 row_mirror row_mask:0xf bank_mask:0xf bound_ctrl:1
	ds_bpermute_b32 v5, v199, v4
	s_waitcnt lgkmcnt(0)
	v_add_f32_e32 v4, v4, v5
	v_mul_f32_e32 v5, 0x4f800000, v4
	v_cmp_gt_f32_e32 vcc, s75, v4
	s_nop 1
	v_cndmask_b32_e32 v4, v4, v5, vcc
	v_sqrt_f32_e32 v5, v4
	s_nop 0
	v_add_u32_e32 v16, -1, v5
	v_add_u32_e32 v17, 1, v5
	v_fma_f32 v18, -v16, v5, v4
	v_fma_f32 v19, -v17, v5, v4
	v_cmp_ge_f32_e64 s[0:1], 0, v18
	s_nop 1
	v_cndmask_b32_e64 v5, v5, v16, s[0:1]
	v_cmp_lt_f32_e64 s[0:1], 0, v19
	s_nop 1
	v_cndmask_b32_e64 v5, v5, v17, s[0:1]
	v_mul_f32_e32 v16, 0x37800000, v5
	v_cndmask_b32_e32 v5, v5, v16, vcc
	v_cmp_class_f32_e32 vcc, v4, v201
	v_add_f32_e32 v17, v54, v210
	s_nop 0
	v_cndmask_b32_e32 v4, v5, v4, vcc
	v_max_f32_e32 v48, 0x2b8cbccc, v4
	v_div_scale_f32 v4, s[0:1], v48, v48, 1.0
	v_rcp_f32_e32 v49, v4
	s_nop 0
	v_fma_f32 v16, -v4, v49, 1.0
	v_div_scale_f32 v5, vcc, 1.0, v48, 1.0
	v_fmac_f32_e32 v49, v16, v49
	v_mul_f32_e32 v50, v5, v49
	v_fma_f32 v16, -v4, v50, v5
	v_fmac_f32_e32 v50, v16, v49
	v_fma_f32 v51, -v4, v50, v5
	v_max_f32_e64 v52, -v17, 0
	s_nop 0
	s_nop 1
	v_mul_f32_e64 v53, |v17|, s76
	v_exp_f32_e32 v53, v53
	s_nop 1
	v_add_f32_e32 v4, 1.0, v53
	v_log_f32_e32 v4, v4
	s_nop 0
	v_mul_f32_e32 v4, 0x3f317218, v4
	v_add_f32_e32 v4, v52, v4
	v_sub_f32_e32 v4, -0.5, v4
	v_add_f32_e32 v17, v38, v209
	v_div_fmas_f32 v20, v51, v49, v50
	v_div_fixup_f32 v38, v20, v48, 1.0
	v_mul_f32_e32 v2, v2, v38
	v_cvt_pk_bf16_f32 v54, v2, 0
	v_mul_f32_e32 v16, 0xbfb8aa3b, v17
	v_exp_f32_e32 v16, v16
	s_nop 0
	v_add_f32_e32 v16, 1.0, v16
	v_div_scale_f32 v17, s[0:1], v16, v16, 1.0
	v_rcp_f32_e32 v18, v17
	v_mul_f32_e32 v3, v3, v38
	s_nop 0
	s_nop 1
	v_mul_f32_e32 v4, 0x3fb8aa3b, v4
	v_exp_f32_e32 v4, v4
	v_fma_f32 v5, -v17, v18, 1.0
	v_fmac_f32_e32 v18, v5, v18
	v_div_scale_f32 v5, vcc, 1.0, v16, 1.0
	v_mul_f32_e32 v19, v5, v18
	v_fma_f32 v20, -v17, v19, v5
	v_fmac_f32_e32 v19, v20, v18
	v_fma_f32 v5, -v17, v19, v5
	v_div_fmas_f32 v5, v5, v18, v19
	v_div_fixup_f32 v5, v5, v16, 1.0
	v_add_f32_e32 v16, -1.0, v5
	v_fma_f32 v16, v208, v16, 1.0
	v_mul_f32_e32 v0, v16, v0
	v_cvt_pk_bf16_f32 v16, v4, 0
	v_mul_f32_e32 v2, v5, v2
	v_lshl_add_u64 v[18:19], s[54:55], 0, v[118:119]
	v_lshl_add_u64 v[4:5], s[20:21], 0, v[118:119]
	v_cvt_pk_bf16_f32 v0, v0, 0
	v_cvt_pk_bf16_f32 v2, v2, 0
	global_store_short v[18:19], v16, off
	global_store_short v[120:121], v0, off
	global_store_short v[4:5], v54, off
	v_lshl_add_u64 v[4:5], s[18:19], 0, v[118:119]
	global_store_short v[4:5], v2, off
	v_lshlrev_b32_e32 v5, 16, v0
	v_lshlrev_b32_e32 v0, 16, v2
	v_lshlrev_b32_e32 v2, 16, v16
	v_mul_f32_e32 v16, 0xbfb8aa3b, v2
	v_fma_f32 v17, v2, s76, -v16
	v_rndne_f32_e32 v20, v16
	v_fmac_f32_e32 v17, 0xb2a5705f, v2
	v_sub_f32_e32 v16, v16, v20
	v_add_f32_e32 v16, v16, v17
	v_lshlrev_b32_e32 v4, 16, v217
	v_mul_f32_e32 v21, 0xbfb8aa3b, v2
	v_exp_f32_e32 v21, v21
	v_mov_b32_e32 v17, v4
	v_pk_mul_f32 v[16:17], v[16:17], v[4:5]
	v_fma_f32 v103, v0, v4, 0
	v_add_f32_e32 v16, v22, v207
	v_mov_b32_e32 v0, v21
	v_max_f32_e64 v22, -v16, 0
	s_nop 1
	v_mul_f32_e64 v16, |v16|, s76
	v_exp_f32_e32 v16, v16
	v_lshlrev_b32_e32 v34, 16, v54
	s_nop 0
	v_add_f32_e32 v20, 1.0, v16
	v_log_f32_e32 v20, v20
	s_nop 0
	v_mul_f32_e32 v16, 0x3f317218, v20
	v_add_f32_e32 v16, v22, v16
	v_sub_f32_e32 v16, -0.5, v16
	v_mul_f32_e32 v20, 0x3fb8aa3b, v16
	v_exp_f32_e32 v20, v20
	v_mov_b32_e32 v33, v0
	v_mov_b32_e32 v0, v20
	s_nop 0
	s_nop 1
	v_mul_f32_e32 v2, 0xbfb8aa3b, v6
	v_exp_f32_e32 v2, v2
	s_nop 0
	v_add_f32_e32 v2, 1.0, v2
	v_div_scale_f32 v6, s[0:1], v2, v2, 1.0
	v_rcp_f32_e32 v20, v6
	s_nop 0
	v_fma_f32 v16, -v6, v20, 1.0
	v_fmac_f32_e32 v20, v16, v20
	v_div_scale_f32 v16, vcc, 1.0, v2, 1.0
	v_mul_f32_e32 v21, v16, v20
	v_fma_f32 v22, -v6, v21, v16
	v_fmac_f32_e32 v21, v22, v20
	v_fma_f32 v6, -v6, v21, v16
	v_div_fmas_f32 v6, v6, v20, v21
	v_div_fixup_f32 v2, v6, v2, 1.0
	v_add_f32_e32 v6, -1.0, v2
	v_fma_f32 v6, v205, v6, 1.0
	v_mul_f32_e32 v1, v6, v1
	v_cvt_pk_bf16_f32 v6, v0, 0
	v_mul_f32_e32 v0, v2, v3
	v_cvt_pk_bf16_f32 v16, v1, 0
	v_cvt_pk_bf16_f32 v20, v3, 0
	v_cvt_pk_bf16_f32 v2, v0, 0
	v_lshl_add_u64 v[0:1], s[20:21], 0, v[114:115]
	global_store_short v[18:19], v6, off offset:64
	global_store_short v[116:117], v16, off
	global_store_short v[0:1], v20, off
	v_lshl_add_u64 v[0:1], s[18:19], 0, v[114:115]
	global_store_short v[0:1], v2, off
	v_lshlrev_b32_e32 v0, 16, v2
	v_lshlrev_b32_e32 v2, 16, v6
	v_mul_f32_e32 v1, 0xbfb8aa3b, v2
	v_fma_f32 v3, v2, s76, -v1
	v_rndne_f32_e32 v6, v1
	v_fmac_f32_e32 v3, 0xb2a5705f, v2
	v_sub_f32_e32 v1, v1, v6
	v_add_f32_e32 v1, v1, v3
	v_exp_f32_e32 v3, v1
	v_lshlrev_b32_e32 v18, 16, v216
	v_lshlrev_b32_e32 v19, 16, v16
	v_mov_b32_e32 v1, v18
	v_fmac_f32_e32 v103, v0, v18
	v_pk_mul_f32 v[0:1], v[0:1], v[18:19]
	s_nop 0
	v_add_f32_dpp v3, v103, v103 quad_perm:[1,0,3,2] row_mask:0xf bank_mask:0xf bound_ctrl:1
	s_nop 1
	v_add_f32_dpp v3, v3, v3 quad_perm:[2,3,0,1] row_mask:0xf bank_mask:0xf bound_ctrl:1
	v_mov_b32_e32 v16, v5
	v_mov_b32_e32 v5, v68
	v_add_f32_dpp v3, v3, v3 row_half_mirror row_mask:0xf bank_mask:0xf bound_ctrl:1
	v_mul_f32_e32 v21, 0xbfb8aa3b, v2
	v_exp_f32_e32 v21, v21
	v_mov_b32_e32 v0, v19
	v_add_f32_dpp v3, v3, v3 row_mirror row_mask:0xf bank_mask:0xf bound_ctrl:1
	ds_bpermute_b32 v6, v199, v3
	v_mov_b32_e32 v19, v204
	v_lshlrev_b32_e32 v20, 16, v20
	s_waitcnt lgkmcnt(0)
	v_add_f32_e32 v6, v3, v6
	v_pk_fma_f32 v[2:3], v[16:17], v[4:5], 0 op_sel_hi:[1,1,0]
	v_mul_f32_e32 v5, v6, v34
	v_pk_fma_f32 v[0:1], v[0:1], v[18:19], v[2:3]
	v_lshlrev_b64 v[16:17], 11, v[112:113]
	v_fma_f32 v4, v33, v4, -v5
	v_mov_b32_dpp v2, v0 quad_perm:[1,0,3,2] row_mask:0xf bank_mask:0xf bound_ctrl:1
	v_mov_b32_dpp v3, v1 quad_perm:[1,0,3,2] row_mask:0xf bank_mask:0xf bound_ctrl:1
	v_pk_add_f32 v[0:1], v[0:1], v[2:3]
	v_lshl_add_u64 v[16:17], v[64:65], 0, v[16:17]
	v_cvt_pk_bf16_f32 v4, v4, s0
	v_mov_b32_dpp v2, v0 quad_perm:[2,3,0,1] row_mask:0xf bank_mask:0xf bound_ctrl:1
	v_mov_b32_dpp v3, v1 quad_perm:[2,3,0,1] row_mask:0xf bank_mask:0xf bound_ctrl:1
	v_pk_add_f32 v[0:1], v[0:1], v[2:3]
	global_store_short v[16:17], v4, off
	v_mul_f32_e32 v4, v6, v20
	v_mov_b32_dpp v2, v0 row_half_mirror row_mask:0xf bank_mask:0xf bound_ctrl:1
	v_mov_b32_dpp v3, v1 row_half_mirror row_mask:0xf bank_mask:0xf bound_ctrl:1
	v_pk_add_f32 v[0:1], v[0:1], v[2:3]
	v_fma_f32 v4, v21, v18, -v4
	v_cvt_pk_bf16_f32 v4, v4, s0
	v_mov_b32_dpp v2, v0 row_mirror row_mask:0xf bank_mask:0xf bound_ctrl:1
	v_mov_b32_dpp v3, v1 row_mirror row_mask:0xf bank_mask:0xf bound_ctrl:1
	v_pk_add_f32 v[0:1], v[0:1], v[2:3]
	ds_bpermute_b32 v2, v199, v0
	ds_bpermute_b32 v3, v199, v1
	global_store_short v[16:17], v4, off offset:64
	s_and_saveexec_b64 s[0:1], s[2:3]
	s_cbranch_execz .LBB0_553
	v_lshlrev_b64 v[4:5], 7, v[112:113]
	v_lshl_add_u64 v[4:5], s[72:73], 0, v[4:5]
	s_waitcnt lgkmcnt(0)
	v_pk_add_f32 v[0:1], v[0:1], v[2:3]
	global_store_dwordx2 v[4:5], v[0:1], off
.LBB0_553:
	s_or_b64 exec, exec, s[0:1]
	v_lshlrev_b32_e32 v1, 16, v215
	v_lshlrev_b32_e32 v0, 16, v214
	s_waitcnt lgkmcnt(0)
	v_pk_mul_f32 v[2:3], v[100:101], v[0:1]
	v_add_f32_e32 v7, v7, v206
	v_pk_mul_f32 v[4:5], v[2:3], v[2:3]
	s_nop 0
	v_add_f32_e32 v4, v4, v5
	s_nop 1
	v_add_f32_dpp v4, v4, v4 quad_perm:[1,0,3,2] row_mask:0xf bank_mask:0xf bound_ctrl:1
	s_nop 1
	v_add_f32_dpp v4, v4, v4 quad_perm:[2,3,0,1] row_mask:0xf bank_mask:0xf bound_ctrl:1
	s_nop 1
	v_add_f32_dpp v4, v4, v4 row_half_mirror row_mask:0xf bank_mask:0xf bound_ctrl:1
	s_nop 1
	v_add_f32_dpp v4, v4, v4 row_mirror row_mask:0xf bank_mask:0xf bound_ctrl:1
	ds_bpermute_b32 v5, v199, v4
	s_waitcnt lgkmcnt(0)
	v_add_f32_e32 v4, v4, v5
	v_mul_f32_e32 v5, 0x4f800000, v4
	v_cmp_gt_f32_e32 vcc, s75, v4
	s_nop 1
	v_cndmask_b32_e32 v4, v4, v5, vcc
	v_sqrt_f32_e32 v5, v4
	s_nop 0
	v_add_u32_e32 v6, -1, v5
	v_add_u32_e32 v16, 1, v5
	v_fma_f32 v17, -v6, v5, v4
	v_fma_f32 v18, -v16, v5, v4
	v_cmp_ge_f32_e64 s[0:1], 0, v17
	v_add_f32_e32 v17, v55, v210
	v_max_f32_e64 v49, -v17, 0
	v_cndmask_b32_e64 v5, v5, v6, s[0:1]
	v_cmp_lt_f32_e64 s[0:1], 0, v18
	s_nop 1
	v_cndmask_b32_e64 v5, v5, v16, s[0:1]
	v_mul_f32_e32 v6, 0x37800000, v5
	v_cndmask_b32_e32 v5, v5, v6, vcc
	v_cmp_class_f32_e32 vcc, v4, v201
	s_nop 1
	v_cndmask_b32_e32 v4, v5, v4, vcc
	v_max_f32_e32 v6, 0x2b8cbccc, v4
	v_div_scale_f32 v4, s[0:1], v6, v6, 1.0
	v_rcp_f32_e32 v22, v4
	v_div_scale_f32 v5, vcc, 1.0, v6, 1.0
	v_fma_f32 v16, -v4, v22, 1.0
	v_fmac_f32_e32 v22, v16, v22
	v_mul_f32_e32 v38, v5, v22
	v_fma_f32 v16, -v4, v38, v5
	v_fmac_f32_e32 v38, v16, v22
	v_fma_f32 v48, -v4, v38, v5
	s_nop 1
	v_mul_f32_e64 v50, |v17|, s76
	v_exp_f32_e32 v50, v50
	s_nop 1
	v_add_f32_e32 v4, 1.0, v50
	v_log_f32_e32 v4, v4
	s_nop 0
	v_mul_f32_e32 v4, 0x3f317218, v4
	v_add_f32_e32 v4, v49, v4
	v_sub_f32_e32 v4, -0.5, v4
	v_add_f32_e32 v17, v39, v209
	v_div_fmas_f32 v20, v48, v22, v38
	v_div_fixup_f32 v6, v20, v6, 1.0
	v_mul_f32_e32 v2, v2, v6
	v_cvt_pk_bf16_f32 v50, v2, 0
	v_mul_f32_e32 v16, 0xbfb8aa3b, v17
	v_exp_f32_e32 v16, v16
	s_nop 0
	v_add_f32_e32 v16, 1.0, v16
	v_div_scale_f32 v17, s[0:1], v16, v16, 1.0
	v_rcp_f32_e32 v18, v17
	v_mul_f32_e32 v3, v3, v6
	s_nop 0
	s_nop 1
	v_mul_f32_e32 v4, 0x3fb8aa3b, v4
	v_exp_f32_e32 v4, v4
	v_fma_f32 v5, -v17, v18, 1.0
	v_fmac_f32_e32 v18, v5, v18
	v_div_scale_f32 v5, vcc, 1.0, v16, 1.0
	v_mul_f32_e32 v19, v5, v18
	v_fma_f32 v20, -v17, v19, v5
	v_fmac_f32_e32 v19, v20, v18
	v_fma_f32 v5, -v17, v19, v5
	v_div_fmas_f32 v5, v5, v18, v19
	v_div_fixup_f32 v5, v5, v16, 1.0
	v_add_f32_e32 v16, -1.0, v5
	v_fma_f32 v16, v208, v16, 1.0
	v_mul_f32_e32 v0, v16, v0
	v_cvt_pk_bf16_f32 v16, v4, 0
	v_mul_f32_e32 v2, v5, v2
	v_lshl_add_u64 v[18:19], s[54:55], 0, v[108:109]
	v_lshl_add_u64 v[4:5], s[20:21], 0, v[108:109]
	v_cvt_pk_bf16_f32 v0, v0, 0
	v_cvt_pk_bf16_f32 v2, v2, 0
	global_store_short v[18:19], v16, off
	global_store_short v[110:111], v0, off
	global_store_short v[4:5], v50, off
	v_lshl_add_u64 v[4:5], s[18:19], 0, v[108:109]
	global_store_short v[4:5], v2, off
	v_lshlrev_b32_e32 v5, 16, v0
	v_lshlrev_b32_e32 v0, 16, v2
	v_lshlrev_b32_e32 v2, 16, v16
	v_mul_f32_e32 v16, 0xbfb8aa3b, v2
	v_fma_f32 v17, v2, s76, -v16
	v_rndne_f32_e32 v20, v16
	v_fmac_f32_e32 v17, 0xb2a5705f, v2
	v_sub_f32_e32 v16, v16, v20
	v_add_f32_e32 v16, v16, v17
	s_waitcnt vmcnt(62)
	v_lshlrev_b32_e32 v4, 16, v213
	v_mul_f32_e32 v21, 0xbfb8aa3b, v2
	v_exp_f32_e32 v21, v21
	v_mov_b32_e32 v17, v4
	v_pk_mul_f32 v[16:17], v[16:17], v[4:5]
	v_fma_f32 v51, v0, v4, 0
	v_add_f32_e32 v16, v23, v207
	v_mov_b32_e32 v0, v21
	v_max_f32_e64 v52, -v16, 0
	s_nop 1
	v_mul_f32_e64 v16, |v16|, s76
	v_exp_f32_e32 v16, v16
	v_lshlrev_b32_e32 v33, 16, v50
	s_nop 0
	v_add_f32_e32 v20, 1.0, v16
	v_log_f32_e32 v20, v20
	s_nop 0
	v_mul_f32_e32 v16, 0x3f317218, v20
	v_add_f32_e32 v16, v52, v16
	v_sub_f32_e32 v16, -0.5, v16
	v_mul_f32_e32 v20, 0x3fb8aa3b, v16
	v_exp_f32_e32 v20, v20
	v_mov_b32_e32 v32, v0
	v_mov_b32_e32 v0, v20
	s_nop 0
	s_nop 1
	v_mul_f32_e32 v2, 0xbfb8aa3b, v7
	v_exp_f32_e32 v2, v2
	s_nop 0
	v_add_f32_e32 v2, 1.0, v2
	v_div_scale_f32 v7, s[0:1], v2, v2, 1.0
	v_rcp_f32_e32 v20, v7
	s_nop 0
	v_fma_f32 v16, -v7, v20, 1.0
	v_fmac_f32_e32 v20, v16, v20
	v_div_scale_f32 v16, vcc, 1.0, v2, 1.0
	v_mul_f32_e32 v21, v16, v20
	v_fma_f32 v22, -v7, v21, v16
	v_fmac_f32_e32 v21, v22, v20
	v_fma_f32 v7, -v7, v21, v16
	v_div_fmas_f32 v7, v7, v20, v21
	v_div_fixup_f32 v2, v7, v2, 1.0
	v_add_f32_e32 v6, -1.0, v2
	v_fma_f32 v6, v205, v6, 1.0
	v_mul_f32_e32 v1, v6, v1
	v_cvt_pk_bf16_f32 v16, v0, 0
	v_mul_f32_e32 v0, v2, v3
	v_cvt_pk_bf16_f32 v6, v1, 0
	v_cvt_pk_bf16_f32 v20, v3, 0
	v_cvt_pk_bf16_f32 v2, v0, 0
	v_lshl_add_u64 v[0:1], s[20:21], 0, v[104:105]
	global_store_short v[18:19], v16, off offset:64
	global_store_short v[106:107], v6, off
	global_store_short v[0:1], v20, off
	v_lshl_add_u64 v[0:1], s[18:19], 0, v[104:105]
	global_store_short v[0:1], v2, off
	v_lshlrev_b32_e32 v0, 16, v2
	v_lshlrev_b32_e32 v2, 16, v16
	v_mul_f32_e32 v1, 0xbfb8aa3b, v2
	v_fma_f32 v3, v2, s76, -v1
	v_rndne_f32_e32 v16, v1
	v_fmac_f32_e32 v3, 0xb2a5705f, v2
	v_sub_f32_e32 v1, v1, v16
	v_add_f32_e32 v1, v1, v3
	v_exp_f32_e32 v3, v1
	v_lshlrev_b32_e32 v7, 16, v6
	v_lshlrev_b32_e32 v6, 16, v212
	v_mov_b32_e32 v1, v6
	v_fmac_f32_e32 v51, v0, v6
	v_pk_mul_f32 v[0:1], v[0:1], v[6:7]
	s_nop 0
	v_add_f32_dpp v3, v51, v51 quad_perm:[1,0,3,2] row_mask:0xf bank_mask:0xf bound_ctrl:1
	s_nop 1
	v_add_f32_dpp v3, v3, v3 quad_perm:[2,3,0,1] row_mask:0xf bank_mask:0xf bound_ctrl:1
	v_lshlrev_b32_e32 v19, 16, v20
	v_mul_f32_e32 v18, 0xbfb8aa3b, v2
	v_exp_f32_e32 v18, v18
	v_add_f32_dpp v3, v3, v3 row_half_mirror row_mask:0xf bank_mask:0xf bound_ctrl:1
	v_mov_b32_e32 v0, v7
	v_mov_b32_e32 v7, v204
	v_add_f32_dpp v3, v3, v3 row_mirror row_mask:0xf bank_mask:0xf bound_ctrl:1
	ds_bpermute_b32 v16, v199, v3
	s_waitcnt lgkmcnt(0)
	v_add_f32_e32 v20, v3, v16
	v_mov_b32_e32 v16, v5
	v_mov_b32_e32 v5, v68
	v_pk_fma_f32 v[2:3], v[16:17], v[4:5], 0 op_sel_hi:[1,1,0]
	v_mul_f32_e32 v5, v20, v33
	v_pk_fma_f32 v[0:1], v[0:1], v[6:7], v[2:3]
	v_lshlrev_b64 v[16:17], 11, v[66:67]
	v_fma_f32 v4, v32, v4, -v5
	v_mov_b32_dpp v2, v0 quad_perm:[1,0,3,2] row_mask:0xf bank_mask:0xf bound_ctrl:1
	v_mov_b32_dpp v3, v1 quad_perm:[1,0,3,2] row_mask:0xf bank_mask:0xf bound_ctrl:1
	v_pk_add_f32 v[0:1], v[0:1], v[2:3]
	v_lshl_add_u64 v[16:17], v[64:65], 0, v[16:17]
	v_cvt_pk_bf16_f32 v4, v4, s0
	v_mov_b32_dpp v2, v0 quad_perm:[2,3,0,1] row_mask:0xf bank_mask:0xf bound_ctrl:1
	v_mov_b32_dpp v3, v1 quad_perm:[2,3,0,1] row_mask:0xf bank_mask:0xf bound_ctrl:1
	v_pk_add_f32 v[0:1], v[0:1], v[2:3]
	global_store_short v[16:17], v4, off
	v_mul_f32_e32 v4, v20, v19
	v_mov_b32_dpp v2, v0 row_half_mirror row_mask:0xf bank_mask:0xf bound_ctrl:1
	v_mov_b32_dpp v3, v1 row_half_mirror row_mask:0xf bank_mask:0xf bound_ctrl:1
	v_pk_add_f32 v[0:1], v[0:1], v[2:3]
	v_fma_f32 v4, v18, v6, -v4
	v_cvt_pk_bf16_f32 v4, v4, s0
	v_mov_b32_dpp v2, v0 row_mirror row_mask:0xf bank_mask:0xf bound_ctrl:1
	v_mov_b32_dpp v3, v1 row_mirror row_mask:0xf bank_mask:0xf bound_ctrl:1
	v_pk_add_f32 v[0:1], v[0:1], v[2:3]
	ds_bpermute_b32 v2, v199, v0
	ds_bpermute_b32 v3, v199, v1
	global_store_short v[16:17], v4, off offset:64
	s_and_saveexec_b64 s[0:1], s[2:3]
	s_cbranch_execz .LBB0_555
	v_lshlrev_b64 v[4:5], 7, v[66:67]
	v_lshl_add_u64 v[4:5], s[72:73], 0, v[4:5]
	s_waitcnt lgkmcnt(0)
	v_pk_add_f32 v[0:1], v[0:1], v[2:3]
	global_store_dwordx2 v[4:5], v[0:1], off
.LBB0_555:
	s_or_b64 exec, exec, s[0:1]
	v_or_b32_e32 v128, 17, v102
	v_or_b32_e32 v118, 18, v102
	v_or_b32_e32 v108, 19, v102
	v_or_b32_e32 v138, 16, v102
	v_ashrrev_i32_e32 v129, 31, v128
	v_ashrrev_i32_e32 v119, 31, v118
	v_ashrrev_i32_e32 v109, 31, v108
	v_ashrrev_i32_e32 v139, 31, v138
	v_lshlrev_b64 v[0:1], 10, v[128:129]
	v_lshlrev_b64 v[4:5], 10, v[118:119]
	v_lshlrev_b64 v[16:17], 10, v[108:109]
	v_lshlrev_b64 v[140:141], 11, v[138:139]
	v_or_b32_e32 v0, v0, v211
	v_or_b32_e32 v4, v4, v211
	v_or_b32_e32 v16, v16, v211
	v_lshl_or_b32 v158, v211, 1, v140
	v_mov_b32_e32 v159, v141
	v_lshlrev_b64 v[134:135], 1, v[0:1]
	v_or_b32_e32 v0, 32, v0
	v_lshlrev_b64 v[124:125], 1, v[4:5]
	v_or_b32_e32 v4, 32, v4
	v_lshlrev_b64 v[114:115], 1, v[16:17]
	v_or_b32_e32 v16, 32, v16
	v_lshl_add_u64 v[160:161], s[26:27], 0, v[158:159]
	v_or_b32_e32 v142, 64, v158
	v_mov_b32_e32 v143, v141
	v_lshlrev_b64 v[130:131], 1, v[0:1]
	v_lshlrev_b64 v[120:121], 1, v[4:5]
	v_lshlrev_b64 v[110:111], 1, v[16:17]
	v_lshl_add_u64 v[152:153], s[26:27], 0, v[142:143]
	s_waitcnt lgkmcnt(0)
	v_lshl_add_u64 v[2:3], s[30:31], 0, v[134:135]
	v_lshl_add_u64 v[0:1], s[30:31], 0, v[130:131]
	v_lshl_add_u64 v[6:7], s[30:31], 0, v[124:125]
	v_lshl_add_u64 v[4:5], s[30:31], 0, v[120:121]
	v_lshl_add_u64 v[18:19], s[30:31], 0, v[114:115]
	v_lshl_add_u64 v[16:17], s[30:31], 0, v[110:111]
	global_load_ushort v99, v[160:161], off
	global_load_ushort v189, v[2:3], off
	global_load_ushort v188, v[0:1], off
	global_load_ushort v185, v[6:7], off
	global_load_ushort v184, v[4:5], off
	global_load_ushort v181, v[18:19], off
	global_load_ushort v180, v[16:17], off
	global_load_ushort v145, v[152:153], off
	v_or_b32_e32 v36, 25, v102
	v_lshl_add_u64 v[0:1], s[30:31], 0, v[142:143]
	v_ashrrev_i32_e32 v37, 31, v36
	global_load_ushort v192, v[0:1], off
	v_lshlrev_b64 v[0:1], 10, v[36:37]
	v_or_b32_e32 v0, v0, v211
	v_or_b32_e32 v18, 26, v102
	v_lshlrev_b64 v[50:51], 1, v[0:1]
	v_or_b32_e32 v0, 32, v0
	v_ashrrev_i32_e32 v19, 31, v18
	v_lshlrev_b64 v[38:39], 1, v[0:1]
	v_lshlrev_b64 v[0:1], 10, v[18:19]
	v_or_b32_e32 v0, v0, v211
	v_lshlrev_b64 v[32:33], 1, v[0:1]
	v_or_b32_e32 v0, 32, v0
	v_lshlrev_b64 v[20:21], 1, v[0:1]
	v_or_b32_e32 v0, 27, v102
	v_ashrrev_i32_e32 v1, 31, v0
	v_lshlrev_b64 v[2:3], 10, v[0:1]
	v_or_b32_e32 v2, v2, v211
	v_lshlrev_b64 v[6:7], 1, v[2:3]
	v_or_b32_e32 v2, 32, v2
	v_lshl_add_u64 v[54:55], s[30:31], 0, v[158:159]
	v_lshlrev_b64 v[2:3], 1, v[2:3]
	v_lshl_add_u64 v[52:53], s[26:27], 0, v[50:51]
	v_lshl_add_u64 v[48:49], s[26:27], 0, v[38:39]
	v_lshl_add_u64 v[34:35], s[26:27], 0, v[32:33]
	v_lshl_add_u64 v[22:23], s[26:27], 0, v[20:21]
	v_lshl_add_u64 v[16:17], s[26:27], 0, v[6:7]
	v_lshl_add_u64 v[4:5], s[26:27], 0, v[2:3]
	global_load_ushort v193, v[54:55], off
	global_load_ushort v174, v[52:53], off
	global_load_ushort v175, v[48:49], off
	global_load_ushort v170, v[34:35], off
	global_load_ushort v171, v[22:23], off
	global_load_ushort v166, v[16:17], off
	global_load_ushort v167, v[4:5], off
	v_or_b32_e32 v54, 24, v102
	v_ashrrev_i32_e32 v55, 31, v54
	v_lshlrev_b64 v[66:67], 10, v[54:55]
	v_or_b32_e32 v66, v66, v211
	v_lshlrev_b64 v[104:105], 1, v[66:67]
	v_or_b32_e32 v66, 32, v66
	v_lshlrev_b64 v[66:67], 1, v[66:67]
	v_lshl_add_u64 v[136:137], s[26:27], 0, v[134:135]
	v_lshl_add_u64 v[146:147], s[30:31], 0, v[104:105]
	v_lshl_add_u64 v[164:165], s[30:31], 0, v[50:51]
	v_lshl_add_u64 v[168:169], s[30:31], 0, v[38:39]
	v_add_f32_e32 v56, v56, v210
	v_lshl_add_u64 v[132:133], s[26:27], 0, v[130:131]
	v_lshl_add_u64 v[126:127], s[26:27], 0, v[124:125]
	v_lshl_add_u64 v[122:123], s[26:27], 0, v[120:121]
	v_lshl_add_u64 v[116:117], s[26:27], 0, v[114:115]
	v_lshl_add_u64 v[112:113], s[26:27], 0, v[110:111]
	v_lshl_add_u64 v[106:107], s[26:27], 0, v[104:105]
	v_lshl_add_u64 v[102:103], s[26:27], 0, v[66:67]
	global_load_ushort v190, v[136:137], off
	global_load_ushort v191, v[132:133], off
	global_load_ushort v186, v[126:127], off
	global_load_ushort v187, v[122:123], off
	global_load_ushort v182, v[116:117], off
	global_load_ushort v183, v[112:113], off
	global_load_ushort v178, v[106:107], off
	global_load_ushort v179, v[102:103], off
	v_lshl_add_u64 v[194:195], s[30:31], 0, v[32:33]
	v_lshl_add_u64 v[212:213], s[30:31], 0, v[20:21]
	v_lshl_add_u64 v[214:215], s[30:31], 0, v[6:7]
	v_lshl_add_u64 v[216:217], s[30:31], 0, v[2:3]
	v_max_f32_e64 v221, -v56, 0
	v_add_f32_e32 v40, v40, v209
	v_add_f32_e32 v24, v24, v207
	v_add_f32_e32 v8, v8, v206
	v_lshl_add_u64 v[140:141], v[64:65], 0, v[140:141]
	s_waitcnt vmcnt(23)
	v_lshlrev_b32_e32 v154, 16, v99
	s_waitcnt vmcnt(16)
	v_lshlrev_b32_e32 v155, 16, v145
	v_pk_mul_f32 v[156:157], v[100:101], v[154:155]
	s_nop 0
	v_pk_mul_f32 v[162:163], v[156:157], v[156:157]
	s_nop 0
	v_add_f32_e32 v99, v162, v163
	v_lshl_add_u64 v[162:163], s[30:31], 0, v[66:67]
	s_nop 0
	v_add_f32_dpp v99, v99, v99 quad_perm:[1,0,3,2] row_mask:0xf bank_mask:0xf bound_ctrl:1
	s_nop 1
	v_add_f32_dpp v99, v99, v99 quad_perm:[2,3,0,1] row_mask:0xf bank_mask:0xf bound_ctrl:1
	s_nop 1
	v_add_f32_dpp v99, v99, v99 row_half_mirror row_mask:0xf bank_mask:0xf bound_ctrl:1
	s_nop 1
	v_add_f32_dpp v99, v99, v99 row_mirror row_mask:0xf bank_mask:0xf bound_ctrl:1
	ds_bpermute_b32 v145, v199, v99
	s_waitcnt lgkmcnt(0)
	v_add_f32_e32 v99, v99, v145
	v_mul_f32_e32 v145, 0x4f800000, v99
	v_cmp_gt_f32_e32 vcc, s75, v99
	s_nop 1
	v_cndmask_b32_e32 v99, v99, v145, vcc
	v_sqrt_f32_e32 v145, v99
	s_nop 0
	v_add_u32_e32 v172, -1, v145
	v_fma_f32 v173, -v172, v145, v99
	v_cmp_ge_f32_e64 s[0:1], 0, v173
	v_add_u32_e32 v173, 1, v145
	s_nop 0
	v_cndmask_b32_e64 v172, v145, v172, s[0:1]
	v_fma_f32 v145, -v173, v145, v99
	v_cmp_lt_f32_e64 s[0:1], 0, v145
	s_nop 1
	v_cndmask_b32_e64 v145, v172, v173, s[0:1]
	v_mul_f32_e32 v172, 0x37800000, v145
	v_cndmask_b32_e32 v145, v145, v172, vcc
	v_cmp_class_f32_e32 vcc, v99, v201
	global_load_ushort v177, v[146:147], off
	global_load_ushort v176, v[162:163], off
	global_load_ushort v173, v[164:165], off
	global_load_ushort v172, v[168:169], off
	s_nop 0
	global_load_ushort v169, v[194:195], off
	global_load_ushort v168, v[212:213], off
	global_load_ushort v165, v[214:215], off
	global_load_ushort v164, v[216:217], off
	v_cndmask_b32_e32 v99, v145, v99, vcc
	v_max_f32_e32 v145, 0x2b8cbccc, v99
	v_div_scale_f32 v99, s[0:1], v145, v145, 1.0
	v_rcp_f32_e32 v197, v99
	s_nop 0
	v_fma_f32 v146, -v99, v197, 1.0
	v_fmac_f32_e32 v197, v146, v197
	v_div_scale_f32 v146, vcc, 1.0, v145, 1.0
	v_mul_f32_e32 v211, v146, v197
	v_fma_f32 v147, -v99, v211, v146
	v_fmac_f32_e32 v211, v147, v197
	v_fma_f32 v220, -v99, v211, v146
	s_nop 1
	v_mul_f32_e64 v56, |v56|, s76
	v_exp_f32_e32 v56, v56
	s_nop 1
	v_add_f32_e32 v99, 1.0, v56
	v_log_f32_e32 v99, v99
	s_nop 0
	v_mul_f32_e32 v56, 0x3f317218, v99
	v_add_f32_e32 v56, v221, v56
	v_sub_f32_e32 v56, -0.5, v56
	v_div_fmas_f32 v163, v220, v197, v211
	v_div_fixup_f32 v145, v163, v145, 1.0
	s_nop 1
	v_mul_f32_e32 v40, 0xbfb8aa3b, v40
	v_exp_f32_e32 v40, v40
	s_nop 0
	v_add_f32_e32 v40, 1.0, v40
	v_div_scale_f32 v146, s[0:1], v40, v40, 1.0
	v_rcp_f32_e32 v147, v146
	s_nop 1
	v_mul_f32_e32 v56, 0x3fb8aa3b, v56
	v_exp_f32_e32 v56, v56
	v_fma_f32 v99, -v146, v147, 1.0
	v_fmac_f32_e32 v147, v99, v147
	v_div_scale_f32 v99, vcc, 1.0, v40, 1.0
	v_mul_f32_e32 v162, v99, v147
	v_fma_f32 v163, -v146, v162, v99
	v_fmac_f32_e32 v162, v163, v147
	v_fma_f32 v99, -v146, v162, v99
	v_div_fmas_f32 v99, v99, v147, v162
	v_div_fixup_f32 v40, v99, v40, 1.0
	v_add_f32_e32 v146, -1.0, v40
	v_fma_f32 v146, v208, v146, 1.0
	v_mul_f32_e32 v99, v156, v145
	v_mul_f32_e32 v146, v146, v154
	v_cvt_pk_bf16_f32 v56, v56, 0
	v_lshl_add_u64 v[162:163], s[54:55], 0, v[158:159]
	v_cvt_pk_bf16_f32 v154, v146, 0
	v_cvt_pk_bf16_f32 v156, v99, 0
	v_mul_f32_e32 v40, v40, v99
	global_store_short v[162:163], v56, off
	global_store_short v[160:161], v154, off
	v_lshl_add_u64 v[146:147], s[20:21], 0, v[158:159]
	v_lshlrev_b32_e32 v56, 16, v56
	v_cvt_pk_bf16_f32 v40, v40, 0
	global_store_short v[146:147], v156, off
	v_lshl_add_u64 v[146:147], s[18:19], 0, v[158:159]
	global_store_short v[146:147], v40, off
	s_waitcnt vmcnt(26)
	v_lshlrev_b32_e32 v158, 16, v193
	v_lshlrev_b32_e32 v159, 16, v154
	v_mov_b32_e32 v99, v158
	v_pk_mul_f32 v[160:161], v[98:99], v[158:159]
	v_max_f32_e64 v160, -v24, 0
	v_lshlrev_b32_e32 v40, 16, v40
	v_fma_f32 v40, v40, v158, 0
	s_nop 0
	s_nop 1
	v_mul_f32_e64 v24, |v24|, s76
	v_exp_f32_e32 v24, v24
	s_nop 0
	v_add_f32_e32 v99, 1.0, v24
	v_add_f32_e32 v146, -1.0, v99
	v_sub_f32_e32 v147, v146, v99
	v_add_f32_e32 v147, 1.0, v147
	v_sub_f32_e32 v146, v24, v146
	v_add_f32_e32 v193, v146, v147
	v_frexp_mant_f32_e32 v194, v99
	v_cvt_f64_f32_e32 v[146:147], v99
	v_frexp_exp_i32_f64_e32 v146, v[146:147]
	v_cmp_gt_f32_e32 vcc, s81, v194
	s_nop 1
	v_subbrev_co_u32_e32 v197, vcc, 0, v146, vcc
	v_sub_u32_e32 v146, 0, v197
	v_ldexp_f32 v99, v99, v146
	v_ldexp_f32 v146, v193, v146
	v_add_f32_e32 v193, -1.0, v99
	v_add_f32_e32 v147, 1.0, v193
	v_sub_f32_e32 v147, v99, v147
	v_add_f32_e32 v194, v146, v147
	v_add_f32_e32 v147, 1.0, v99
	v_add_f32_e32 v195, -1.0, v147
	v_sub_f32_e32 v99, v99, v195
	v_add_f32_e32 v99, v146, v99
	v_add_f32_e32 v211, v147, v99
	v_rcp_f32_e32 v216, v211
	v_sub_f32_e32 v146, v147, v211
	v_add_f32_e32 v147, v193, v194
	v_add_f32_e32 v99, v99, v146
	v_sub_f32_e32 v146, v193, v147
	v_mul_f32_e32 v217, v147, v216
	v_add_f32_e32 v193, v194, v146
	v_mul_f32_e32 v194, v211, v217
	v_fma_f32 v212, v217, v211, -v194
	v_fmac_f32_e32 v212, v217, v99
	v_add_f32_e32 v146, v194, v212
	v_sub_f32_e32 v195, v147, v146
	v_pk_add_f32 v[214:215], v[146:147], v[194:195] neg_lo:[0,1] neg_hi:[0,1]
	v_mov_b32_e32 v213, v146
	v_pk_add_f32 v[146:147], v[214:215], v[212:213] neg_lo:[0,1] neg_hi:[0,1]
	v_add_f32_e32 v147, v193, v147
	v_add_f32_e32 v146, v146, v147
	v_add_f32_e32 v147, v195, v146
	v_mul_f32_e32 v193, v216, v147
	v_mul_f32_e32 v194, v211, v193
	v_fma_f32 v212, v193, v211, -v194
	v_fmac_f32_e32 v212, v193, v99
	v_sub_f32_e32 v99, v195, v147
	v_add_f32_e32 v99, v146, v99
	v_add_f32_e32 v146, v194, v212
	v_sub_f32_e32 v195, v147, v146
	v_pk_add_f32 v[214:215], v[146:147], v[194:195] neg_lo:[0,1] neg_hi:[0,1]
	v_mov_b32_e32 v213, v146
	v_pk_add_f32 v[146:147], v[214:215], v[212:213] neg_lo:[0,1] neg_hi:[0,1]
	s_nop 0
	v_add_f32_e32 v99, v99, v147
	v_add_f32_e32 v99, v146, v99
	v_add_f32_e32 v147, v217, v193
	v_add_f32_e32 v99, v195, v99
	v_sub_f32_e32 v146, v147, v217
	v_mul_f32_e32 v99, v216, v99
	v_sub_f32_e32 v146, v193, v146
	v_add_f32_e32 v193, v146, v99
	v_add_f32_e32 v194, v147, v193
	v_cvt_f32_i32_e32 v146, v197
	v_mul_f32_e32 v211, v194, v194
	v_sub_f32_e32 v147, v194, v147
	v_fmamk_f32 v99, v211, 0x3e9b6dac, v202
	v_sub_f32_e32 v147, v193, v147
	v_fmaak_f32 v99, v211, v99, 0x3f2aaada
	v_ldexp_f32 v193, v147, 1
	v_mul_f32_e32 v147, v194, v211
	v_pk_mul_f32 v[212:213], v[146:147], v[98:99]
	v_ldexp_f32 v195, v194, 1
	v_fma_f32 v194, v146, s82, -v212
	v_fmac_f32_e32 v194, 0xb102e308, v146
	v_pk_add_f32 v[146:147], v[212:213], v[194:195]
	v_mov_b32_e32 v214, v212
	v_sub_f32_e32 v99, v147, v195
	v_sub_f32_e32 v99, v213, v99
	v_add_f32_e32 v215, v193, v99
	v_pk_add_f32 v[212:213], v[146:147], v[212:213] neg_lo:[0,1] neg_hi:[0,1]
	v_pk_add_f32 v[216:217], v[146:147], v[214:215]
	v_mov_b32_e32 v195, v146
	v_mov_b32_e32 v213, v217
	v_pk_add_f32 v[218:219], v[194:195], v[212:213] neg_lo:[0,1] neg_hi:[0,1]
	v_pk_add_f32 v[194:195], v[194:195], v[212:213]
	v_mov_b32_e32 v214, v215
	v_pk_add_f32 v[212:213], v[194:195], v[146:147] op_sel:[1,0] op_sel_hi:[0,1] neg_lo:[0,1] neg_hi:[0,1]
	v_pk_add_f32 v[220:221], v[216:217], v[212:213] op_sel_hi:[1,0] neg_lo:[0,1] neg_hi:[0,1]
	v_mov_b32_e32 v216, v217
	v_mov_b32_e32 v217, v195
	v_pk_mov_b32 v[212:213], v[146:147], v[212:213] op_sel:[1,0]
	v_mov_b32_e32 v215, v146
	v_pk_add_f32 v[212:213], v[216:217], v[212:213] neg_lo:[0,1] neg_hi:[0,1]
	v_mov_b32_e32 v220, v218
	v_pk_add_f32 v[146:147], v[214:215], v[212:213] neg_lo:[0,1] neg_hi:[0,1]
	v_mov_b32_e32 v219, v195
	v_pk_add_f32 v[212:213], v[220:221], v[146:147]
	s_nop 0
	v_pk_add_f32 v[214:215], v[212:213], v[212:213] op_sel:[0,1] op_sel_hi:[1,0]
	s_nop 0
	v_pk_add_f32 v[194:195], v[194:195], v[214:215] op_sel:[1,0] op_sel_hi:[0,1]
	v_mov_b32_e32 v213, v194
	v_pk_add_f32 v[216:217], v[212:213], v[218:219] neg_lo:[0,1] neg_hi:[0,1]
	s_nop 1
	v_add_f32_e32 v99, 1.0, v24
	v_log_f32_e32 v99, v99
	s_nop 0
	v_mul_f32_e32 v24, 0x3f317218, v99
	v_add_f32_e32 v24, v160, v24
	v_sub_f32_e32 v24, -0.5, v24
	v_mul_f32_e32 v147, 0xbfb8aa3b, v8
	v_rndne_f32_e32 v193, v147
	v_mul_f32_e32 v56, 0xbfb8aa3b, v56
	v_exp_f32_e32 v56, v56
	v_lshlrev_b32_e32 v154, 16, v156
	s_nop 0
	s_nop 1
	v_mul_f32_e32 v8, 0xbfb8aa3b, v8
	v_exp_f32_e32 v8, v8
	s_nop 0
	v_add_f32_e32 v8, 1.0, v8
	v_div_scale_f32 v146, s[0:1], v8, v8, 1.0
	v_rcp_f32_e32 v147, v146
	s_nop 1
	v_mul_f32_e32 v24, 0x3fb8aa3b, v24
	v_exp_f32_e32 v24, v24
	v_fma_f32 v99, -v146, v147, 1.0
	v_fmac_f32_e32 v147, v99, v147
	v_div_scale_f32 v99, vcc, 1.0, v8, 1.0
	v_mul_f32_e32 v156, v99, v147
	v_fma_f32 v160, -v146, v156, v99
	v_fmac_f32_e32 v156, v160, v147
	v_fma_f32 v99, -v146, v156, v99
	v_div_fmas_f32 v99, v99, v147, v156
	v_div_fixup_f32 v8, v99, v8, 1.0
	v_mul_f32_e32 v99, v157, v145
	v_add_f32_e32 v145, -1.0, v8
	v_fma_f32 v145, v205, v145, 1.0
	v_mul_f32_e32 v145, v145, v155
	v_cvt_pk_bf16_f32 v24, v24, 0
	v_cvt_pk_bf16_f32 v145, v145, 0
	v_mul_f32_e32 v8, v8, v99
	global_store_short v[162:163], v24, off offset:64
	global_store_short v[152:153], v145, off
	v_lshlrev_b32_e32 v24, 16, v24
	v_cvt_pk_bf16_f32 v155, v99, 0
	v_cvt_pk_bf16_f32 v8, v8, 0
	v_lshl_add_u64 v[146:147], s[20:21], 0, v[142:143]
	v_lshl_add_u64 v[142:143], s[18:19], 0, v[142:143]
	global_store_short v[142:143], v8, off
	global_store_short v[146:147], v155, off
	v_lshlrev_b32_e32 v147, 16, v145
	v_mul_f32_e32 v145, 0xbfb8aa3b, v24
	v_exp_f32_e32 v145, v145
	v_lshlrev_b32_e32 v146, 16, v192
	v_mov_b32_e32 v99, v146
	v_lshlrev_b32_e32 v8, 16, v8
	v_pk_mul_f32 v[142:143], v[98:99], v[146:147]
	v_mov_b32_e32 v160, v159
	v_mov_b32_e32 v159, v68
	v_fmac_f32_e32 v40, v8, v146
	v_mov_b32_e32 v8, v145
	v_pk_fma_f32 v[152:153], v[160:161], v[158:159], 0 op_sel_hi:[1,1,0]
	v_mov_b32_e32 v142, v147
	v_mov_b32_e32 v147, v204
	v_pk_fma_f32 v[142:143], v[142:143], v[146:147], v[152:153]
	v_add_f32_dpp v40, v40, v40 quad_perm:[1,0,3,2] row_mask:0xf bank_mask:0xf bound_ctrl:1
	s_nop 0
	v_mov_b32_dpp v152, v142 quad_perm:[1,0,3,2] row_mask:0xf bank_mask:0xf bound_ctrl:1
	v_mov_b32_dpp v153, v143 quad_perm:[1,0,3,2] row_mask:0xf bank_mask:0xf bound_ctrl:1
	v_add_f32_dpp v40, v40, v40 quad_perm:[2,3,0,1] row_mask:0xf bank_mask:0xf bound_ctrl:1
	v_pk_add_f32 v[142:143], v[142:143], v[152:153]
	s_nop 0
	v_add_f32_dpp v40, v40, v40 row_half_mirror row_mask:0xf bank_mask:0xf bound_ctrl:1
	v_mov_b32_dpp v152, v142 quad_perm:[2,3,0,1] row_mask:0xf bank_mask:0xf bound_ctrl:1
	v_mov_b32_dpp v153, v143 quad_perm:[2,3,0,1] row_mask:0xf bank_mask:0xf bound_ctrl:1
	v_add_f32_dpp v40, v40, v40 row_mirror row_mask:0xf bank_mask:0xf bound_ctrl:1
	v_pk_add_f32 v[142:143], v[142:143], v[152:153]
	ds_bpermute_b32 v99, v199, v40
	s_nop 0
	v_mov_b32_dpp v152, v142 row_half_mirror row_mask:0xf bank_mask:0xf bound_ctrl:1
	v_mov_b32_dpp v153, v143 row_half_mirror row_mask:0xf bank_mask:0xf bound_ctrl:1
	v_pk_add_f32 v[142:143], v[142:143], v[152:153]
	v_lshlrev_b32_e32 v24, 16, v155
	s_waitcnt lgkmcnt(0)
	v_add_f32_e32 v40, v40, v99
	v_mov_b32_dpp v152, v142 row_mirror row_mask:0xf bank_mask:0xf bound_ctrl:1
	v_mov_b32_dpp v153, v143 row_mirror row_mask:0xf bank_mask:0xf bound_ctrl:1
	v_pk_add_f32 v[142:143], v[142:143], v[152:153]
	ds_bpermute_b32 v152, v199, v142
	ds_bpermute_b32 v153, v199, v143
	v_mul_f32_e32 v99, v40, v154
	v_mul_f32_e32 v24, v40, v24
	v_fma_f32 v56, v56, v158, -v99
	v_fma_f32 v8, v8, v146, -v24
	v_cvt_pk_bf16_f32 v56, v56, s0
	v_cvt_pk_bf16_f32 v8, v8, s0
	global_store_short v[140:141], v56, off
	global_store_short v[140:141], v8, off offset:64
	s_and_saveexec_b64 s[0:1], s[2:3]
	s_cbranch_execz .LBB0_557
	v_lshlrev_b64 v[138:139], 7, v[138:139]
	v_lshl_add_u64 v[138:139], s[72:73], 0, v[138:139]
	s_waitcnt lgkmcnt(0)
	v_pk_add_f32 v[140:141], v[142:143], v[152:153]
	global_store_dwordx2 v[138:139], v[140:141], off
.LBB0_557:
	s_or_b64 exec, exec, s[0:1]
	s_waitcnt vmcnt(24)
	v_lshlrev_b32_e32 v139, 16, v191
	v_lshlrev_b32_e32 v138, 16, v190
	v_pk_mul_f32 v[140:141], v[100:101], v[138:139]
	v_add_f32_e32 v57, v57, v210
	v_pk_mul_f32 v[142:143], v[140:141], v[140:141]
	v_max_f32_e64 v160, -v57, 0
	v_add_f32_e32 v8, v142, v143
	v_add_f32_e32 v41, v41, v209
	v_add_f32_e32 v25, v25, v207
	v_add_f32_dpp v8, v8, v8 quad_perm:[1,0,3,2] row_mask:0xf bank_mask:0xf bound_ctrl:1
	v_add_f32_e32 v9, v9, v206
	s_nop 0
	v_add_f32_dpp v8, v8, v8 quad_perm:[2,3,0,1] row_mask:0xf bank_mask:0xf bound_ctrl:1
	s_nop 1
	v_add_f32_dpp v8, v8, v8 row_half_mirror row_mask:0xf bank_mask:0xf bound_ctrl:1
	s_nop 1
	v_add_f32_dpp v8, v8, v8 row_mirror row_mask:0xf bank_mask:0xf bound_ctrl:1
	ds_bpermute_b32 v24, v199, v8
	s_waitcnt lgkmcnt(0)
	v_add_f32_e32 v8, v8, v24
	v_mul_f32_e32 v24, 0x4f800000, v8
	v_cmp_gt_f32_e32 vcc, s75, v8
	s_nop 1
	v_cndmask_b32_e32 v8, v8, v24, vcc
	v_sqrt_f32_e32 v24, v8
	s_nop 0
	v_add_u32_e32 v40, -1, v24
	v_add_u32_e32 v56, 1, v24
	v_fma_f32 v99, -v40, v24, v8
	v_fma_f32 v142, -v56, v24, v8
	v_cmp_ge_f32_e64 s[0:1], 0, v99
	s_nop 1
	v_cndmask_b32_e64 v24, v24, v40, s[0:1]
	v_cmp_lt_f32_e64 s[0:1], 0, v142
	s_nop 1
	v_cndmask_b32_e64 v24, v24, v56, s[0:1]
	v_mul_f32_e32 v40, 0x37800000, v24
	v_cndmask_b32_e32 v24, v24, v40, vcc
	v_cmp_class_f32_e32 vcc, v8, v201
	s_nop 1
	v_cndmask_b32_e32 v8, v24, v8, vcc
	v_max_f32_e32 v8, 0x2b8cbccc, v8
	v_div_scale_f32 v24, s[0:1], v8, v8, 1.0
	v_rcp_f32_e32 v40, v24
	v_div_scale_f32 v56, vcc, 1.0, v8, 1.0
	v_fma_f32 v99, -v24, v40, 1.0
	v_fmac_f32_e32 v40, v99, v40
	v_mul_f32_e32 v145, v56, v40
	v_fma_f32 v99, -v24, v145, v56
	v_fmac_f32_e32 v145, v99, v40
	v_fma_f32 v24, -v24, v145, v56
	v_div_fmas_f32 v24, v24, v40, v145
	v_div_fixup_f32 v8, v24, v8, 1.0
	s_nop 0
	v_mul_f32_e64 v161, |v57|, s76
	v_exp_f32_e32 v161, v161
	v_max_f32_e64 v159, -v25, 0
	s_nop 1
	v_add_f32_e32 v56, 1.0, v161
	v_log_f32_e32 v56, v56
	s_nop 0
	v_mul_f32_e32 v56, 0x3f317218, v56
	v_add_f32_e32 v56, v160, v56
	v_sub_f32_e32 v56, -0.5, v56
	v_mul_f32_e32 v57, 0x3fb8aa3b, v56
	v_exp_f32_e32 v57, v57
	s_nop 0
	v_mov_b32_e32 v24, v57
	s_nop 0
	v_mul_f32_e32 v40, 0xbfb8aa3b, v41
	v_exp_f32_e32 v40, v40
	s_nop 0
	v_add_f32_e32 v40, 1.0, v40
	v_div_scale_f32 v41, s[0:1], v40, v40, 1.0
	v_rcp_f32_e32 v57, v41
	s_nop 0
	v_fma_f32 v56, -v41, v57, 1.0
	v_fmac_f32_e32 v57, v56, v57
	v_div_scale_f32 v56, vcc, 1.0, v40, 1.0
	v_mul_f32_e32 v99, v56, v57
	v_fma_f32 v142, -v41, v99, v56
	v_fmac_f32_e32 v99, v142, v57
	v_fma_f32 v41, -v41, v99, v56
	v_div_fmas_f32 v41, v41, v57, v99
	v_div_fixup_f32 v40, v41, v40, 1.0
	v_mul_f32_e32 v41, v140, v8
	v_add_f32_e32 v56, -1.0, v40
	v_fma_f32 v56, v208, v56, 1.0
	v_cvt_pk_bf16_f32 v24, v24, 0
	v_mul_f32_e32 v40, v40, v41
	v_mul_f32_e32 v56, v56, v138
	v_cvt_pk_bf16_f32 v138, v41, 0
	v_cvt_pk_bf16_f32 v57, v40, 0
	v_lshl_add_u64 v[142:143], s[54:55], 0, v[134:135]
	v_lshl_add_u64 v[40:41], s[20:21], 0, v[134:135]
	v_lshlrev_b32_e32 v140, 16, v24
	v_cvt_pk_bf16_f32 v56, v56, 0
	global_store_short v[142:143], v24, off
	global_store_short v[136:137], v56, off
	global_store_short v[40:41], v138, off
	v_lshl_add_u64 v[40:41], s[18:19], 0, v[134:135]
	v_mul_f32_e32 v24, 0xbfb8aa3b, v140
	global_store_short v[40:41], v57, off
	v_lshlrev_b32_e32 v41, 16, v56
	v_lshlrev_b32_e32 v56, 16, v57
	v_fma_f32 v57, v140, s76, -v24
	v_rndne_f32_e32 v99, v24
	v_fmac_f32_e32 v57, 0xb2a5705f, v140
	v_sub_f32_e32 v24, v24, v99
	v_add_f32_e32 v24, v24, v57
	v_lshlrev_b32_e32 v40, 16, v189
	v_exp_f32_e32 v24, v24
	v_cvt_i32_f32_e32 v99, v99
	v_mov_b32_e32 v57, v40
	v_fma_f32 v145, v56, v40, 0
	v_pk_mul_f32 v[56:57], v[56:57], v[40:41]
	v_ldexp_f32 v24, v24, v99
	v_cmp_nlt_f32_e32 vcc, s78, v140
	v_mul_f32_e32 v8, v141, v8
	s_nop 0
	v_cndmask_b32_e32 v158, 0, v24, vcc
	s_nop 1
	v_mul_f32_e64 v56, |v25|, s76
	v_exp_f32_e32 v56, v56
	s_nop 0
	v_add_f32_e32 v99, 1.0, v56
	v_add_f32_e32 v24, -1.0, v99
	v_sub_f32_e32 v25, v24, v99
	v_add_f32_e32 v25, 1.0, v25
	v_sub_f32_e32 v24, v56, v24
	v_add_f32_e32 v134, v24, v25
	v_frexp_mant_f32_e32 v135, v99
	v_cvt_f64_f32_e32 v[24:25], v99
	v_frexp_exp_i32_f64_e32 v24, v[24:25]
	v_cmp_gt_f32_e32 vcc, s81, v135
	s_nop 1
	v_subbrev_co_u32_e32 v152, vcc, 0, v24, vcc
	v_sub_u32_e32 v24, 0, v152
	v_ldexp_f32 v25, v99, v24
	v_add_f32_e32 v99, -1.0, v25
	v_add_f32_e32 v135, 1.0, v25
	v_ldexp_f32 v24, v134, v24
	v_add_f32_e32 v134, 1.0, v99
	v_add_f32_e32 v136, -1.0, v135
	v_sub_f32_e32 v134, v25, v134
	v_sub_f32_e32 v25, v25, v136
	v_add_f32_e32 v134, v24, v134
	v_add_f32_e32 v24, v24, v25
	v_add_f32_e32 v153, v135, v24
	v_rcp_f32_e32 v155, v153
	v_sub_f32_e32 v25, v135, v153
	v_add_f32_e32 v154, v24, v25
	v_add_f32_e32 v25, v99, v134
	v_sub_f32_e32 v24, v99, v25
	v_mul_f32_e32 v156, v25, v155
	v_add_f32_e32 v99, v134, v24
	v_mul_f32_e32 v134, v153, v156
	v_fma_f32 v136, v156, v153, -v134
	v_fmac_f32_e32 v136, v156, v154
	v_add_f32_e32 v24, v134, v136
	v_sub_f32_e32 v135, v25, v24
	v_pk_add_f32 v[146:147], v[24:25], v[134:135] neg_lo:[0,1] neg_hi:[0,1]
	v_mov_b32_e32 v137, v24
	v_pk_add_f32 v[24:25], v[146:147], v[136:137] neg_lo:[0,1] neg_hi:[0,1]
	v_add_f32_e32 v25, v99, v25
	v_add_f32_e32 v24, v24, v25
	v_add_f32_e32 v25, v135, v24
	v_mul_f32_e32 v99, v155, v25
	v_mul_f32_e32 v134, v153, v99
	v_fma_f32 v136, v99, v153, -v134
	v_fmac_f32_e32 v136, v99, v154
	v_sub_f32_e32 v135, v135, v25
	v_add_f32_e32 v153, v24, v135
	v_add_f32_e32 v24, v134, v136
	v_sub_f32_e32 v135, v25, v24
	v_pk_add_f32 v[146:147], v[24:25], v[134:135] neg_lo:[0,1] neg_hi:[0,1]
	v_mov_b32_e32 v137, v24
	v_pk_add_f32 v[24:25], v[146:147], v[136:137] neg_lo:[0,1] neg_hi:[0,1]
	s_nop 0
	v_add_f32_e32 v25, v153, v25
	v_add_f32_e32 v24, v24, v25
	v_add_f32_e32 v25, v156, v99
	v_add_f32_e32 v24, v135, v24
	v_sub_f32_e32 v134, v25, v156
	v_mul_f32_e32 v24, v155, v24
	v_sub_f32_e32 v99, v99, v134
	v_add_f32_e32 v134, v99, v24
	v_add_f32_e32 v136, v25, v134
	v_mul_f32_e32 v137, v136, v136
	v_fmamk_f32 v24, v137, 0x3e9b6dac, v202
	v_fmaak_f32 v99, v137, v24, 0x3f2aaada
	v_cvt_f32_i32_e32 v24, v152
	v_sub_f32_e32 v25, v136, v25
	v_sub_f32_e32 v25, v134, v25
	v_ldexp_f32 v146, v25, 1
	v_mul_f32_e32 v25, v136, v137
	v_ldexp_f32 v135, v136, 1
	v_pk_mul_f32 v[136:137], v[24:25], v[98:99]
	s_nop 0
	v_fma_f32 v134, v24, s82, -v136
	v_fmac_f32_e32 v134, 0xb102e308, v24
	v_pk_add_f32 v[24:25], v[136:137], v[134:135]
	s_nop 0
	v_sub_f32_e32 v99, v25, v135
	v_sub_f32_e32 v99, v137, v99
	v_add_f32_e32 v147, v146, v99
	v_mov_b32_e32 v146, v136
	v_pk_add_f32 v[136:137], v[24:25], v[136:137] neg_lo:[0,1] neg_hi:[0,1]
	v_pk_add_f32 v[152:153], v[24:25], v[146:147]
	v_mov_b32_e32 v135, v24
	v_mov_b32_e32 v137, v153
	v_pk_add_f32 v[154:155], v[134:135], v[136:137] neg_lo:[0,1] neg_hi:[0,1]
	v_pk_add_f32 v[134:135], v[134:135], v[136:137]
	v_mov_b32_e32 v146, v147
	v_pk_add_f32 v[136:137], v[134:135], v[24:25] op_sel:[1,0] op_sel_hi:[0,1] neg_lo:[0,1] neg_hi:[0,1]
	v_pk_add_f32 v[156:157], v[152:153], v[136:137] op_sel_hi:[1,0] neg_lo:[0,1] neg_hi:[0,1]
	v_mov_b32_e32 v152, v153
	v_mov_b32_e32 v153, v135
	v_pk_mov_b32 v[136:137], v[24:25], v[136:137] op_sel:[1,0]
	v_mov_b32_e32 v147, v24
	v_pk_add_f32 v[136:137], v[152:153], v[136:137] neg_lo:[0,1] neg_hi:[0,1]
	v_mov_b32_e32 v156, v154
	v_pk_add_f32 v[24:25], v[146:147], v[136:137] neg_lo:[0,1] neg_hi:[0,1]
	v_mov_b32_e32 v155, v135
	v_pk_add_f32 v[136:137], v[156:157], v[24:25]
	s_nop 0
	v_pk_add_f32 v[146:147], v[136:137], v[136:137] op_sel:[0,1] op_sel_hi:[1,0]
	s_nop 0
	v_pk_add_f32 v[134:135], v[134:135], v[146:147] op_sel:[1,0] op_sel_hi:[0,1]
	v_mov_b32_e32 v137, v134
	v_pk_add_f32 v[152:153], v[136:137], v[154:155] neg_lo:[0,1] neg_hi:[0,1]
	v_lshlrev_b32_e32 v136, 16, v138
	s_nop 0
	v_add_f32_e32 v24, 1.0, v56
	v_log_f32_e32 v24, v24
	s_nop 0
	v_mul_f32_e32 v24, 0x3f317218, v24
	v_add_f32_e32 v24, v159, v24
	v_sub_f32_e32 v24, -0.5, v24
	v_mul_f32_e32 v135, 0xbfb8aa3b, v140
	v_exp_f32_e32 v135, v135
	s_nop 1
	v_mul_f32_e32 v9, 0xbfb8aa3b, v9
	v_exp_f32_e32 v9, v9
	s_nop 0
	v_add_f32_e32 v9, 1.0, v9
	v_div_scale_f32 v56, s[0:1], v9, v9, 1.0
	v_rcp_f32_e32 v99, v56
	s_nop 1
	v_mul_f32_e32 v24, 0x3fb8aa3b, v24
	v_exp_f32_e32 v24, v24
	v_fma_f32 v25, -v56, v99, 1.0
	v_fmac_f32_e32 v99, v25, v99
	v_div_scale_f32 v25, vcc, 1.0, v9, 1.0
	v_mul_f32_e32 v134, v25, v99
	v_fma_f32 v137, -v56, v134, v25
	v_fmac_f32_e32 v134, v137, v99
	v_fma_f32 v25, -v56, v134, v25
	v_div_fmas_f32 v25, v25, v99, v134
	v_div_fixup_f32 v9, v25, v9, 1.0
	v_add_f32_e32 v25, -1.0, v9
	v_fma_f32 v25, v205, v25, 1.0
	v_cvt_pk_bf16_f32 v56, v8, 0
	v_mul_f32_e32 v8, v9, v8
	v_mul_f32_e32 v25, v25, v139
	v_cvt_pk_bf16_f32 v24, v24, 0
	v_cvt_pk_bf16_f32 v99, v8, 0
	v_lshl_add_u64 v[8:9], s[20:21], 0, v[130:131]
	v_cvt_pk_bf16_f32 v25, v25, 0
	global_store_short v[142:143], v24, off offset:64
	global_store_short v[132:133], v25, off
	global_store_short v[8:9], v56, off
	v_lshl_add_u64 v[8:9], s[18:19], 0, v[130:131]
	v_lshlrev_b32_e32 v24, 16, v24
	global_store_short v[8:9], v99, off
	v_mul_f32_e32 v9, 0xbfb8aa3b, v24
	v_lshlrev_b32_e32 v131, 16, v25
	v_lshlrev_b32_e32 v8, 16, v99
	v_fma_f32 v25, v24, s76, -v9
	v_rndne_f32_e32 v99, v9
	v_fmac_f32_e32 v25, 0xb2a5705f, v24
	v_sub_f32_e32 v9, v9, v99
	v_add_f32_e32 v9, v9, v25
	v_exp_f32_e32 v25, v9
	v_lshlrev_b32_e32 v130, 16, v188
	v_mov_b32_e32 v9, v130
	v_fmac_f32_e32 v145, v8, v130
	v_pk_mul_f32 v[8:9], v[8:9], v[130:131]
	s_nop 0
	v_add_f32_dpp v25, v145, v145 quad_perm:[1,0,3,2] row_mask:0xf bank_mask:0xf bound_ctrl:1
	s_nop 1
	v_add_f32_dpp v25, v25, v25 quad_perm:[2,3,0,1] row_mask:0xf bank_mask:0xf bound_ctrl:1
	v_lshlrev_b32_e32 v133, 16, v56
	v_mov_b32_e32 v56, v41
	v_add_f32_dpp v25, v25, v25 row_half_mirror row_mask:0xf bank_mask:0xf bound_ctrl:1
	v_mov_b32_e32 v41, v68
	v_mul_f32_e32 v132, 0xbfb8aa3b, v24
	v_exp_f32_e32 v132, v132
	v_add_f32_dpp v25, v25, v25 row_mirror row_mask:0xf bank_mask:0xf bound_ctrl:1
	ds_bpermute_b32 v99, v199, v25
	v_mov_b32_e32 v8, v131
	v_mov_b32_e32 v131, v204
	s_waitcnt lgkmcnt(0)
	v_add_f32_e32 v99, v25, v99
	v_pk_fma_f32 v[24:25], v[56:57], v[40:41], 0 op_sel_hi:[1,1,0]
	v_mul_f32_e32 v41, v99, v136
	v_pk_fma_f32 v[8:9], v[8:9], v[130:131], v[24:25]
	v_lshlrev_b64 v[56:57], 11, v[128:129]
	v_fma_f32 v40, v135, v40, -v41
	v_mov_b32_dpp v24, v8 quad_perm:[1,0,3,2] row_mask:0xf bank_mask:0xf bound_ctrl:1
	v_mov_b32_dpp v25, v9 quad_perm:[1,0,3,2] row_mask:0xf bank_mask:0xf bound_ctrl:1
	v_pk_add_f32 v[8:9], v[8:9], v[24:25]
	v_lshl_add_u64 v[56:57], v[64:65], 0, v[56:57]
	v_cvt_pk_bf16_f32 v40, v40, s0
	v_mov_b32_dpp v24, v8 quad_perm:[2,3,0,1] row_mask:0xf bank_mask:0xf bound_ctrl:1
	v_mov_b32_dpp v25, v9 quad_perm:[2,3,0,1] row_mask:0xf bank_mask:0xf bound_ctrl:1
	v_pk_add_f32 v[8:9], v[8:9], v[24:25]
	global_store_short v[56:57], v40, off
	v_mul_f32_e32 v40, v99, v133
	v_mov_b32_dpp v24, v8 row_half_mirror row_mask:0xf bank_mask:0xf bound_ctrl:1
	v_mov_b32_dpp v25, v9 row_half_mirror row_mask:0xf bank_mask:0xf bound_ctrl:1
	v_pk_add_f32 v[8:9], v[8:9], v[24:25]
	v_fma_f32 v40, v132, v130, -v40
	v_cvt_pk_bf16_f32 v40, v40, s0
	v_mov_b32_dpp v24, v8 row_mirror row_mask:0xf bank_mask:0xf bound_ctrl:1
	v_mov_b32_dpp v25, v9 row_mirror row_mask:0xf bank_mask:0xf bound_ctrl:1
	v_pk_add_f32 v[8:9], v[8:9], v[24:25]
	ds_bpermute_b32 v24, v199, v8
	ds_bpermute_b32 v25, v199, v9
	global_store_short v[56:57], v40, off offset:64
	s_and_saveexec_b64 s[0:1], s[2:3]
	s_cbranch_execz .LBB0_559
	v_lshlrev_b64 v[40:41], 7, v[128:129]
	v_lshl_add_u64 v[40:41], s[72:73], 0, v[40:41]
	s_waitcnt lgkmcnt(0)
	v_pk_add_f32 v[8:9], v[8:9], v[24:25]
	global_store_dwordx2 v[40:41], v[8:9], off
.LBB0_559:
	s_or_b64 exec, exec, s[0:1]
	s_waitcnt vmcnt(32)
	v_lshlrev_b32_e32 v9, 16, v187
	v_lshlrev_b32_e32 v8, 16, v186
	s_waitcnt lgkmcnt(0)
	v_pk_mul_f32 v[24:25], v[100:101], v[8:9]
	v_add_f32_e32 v42, v42, v209
	v_pk_mul_f32 v[40:41], v[24:25], v[24:25]
	v_add_f32_e32 v26, v26, v207
	v_add_f32_e32 v40, v40, v41
	v_add_f32_e32 v10, v10, v206
	s_nop 0
	v_add_f32_dpp v40, v40, v40 quad_perm:[1,0,3,2] row_mask:0xf bank_mask:0xf bound_ctrl:1
	s_nop 1
	v_add_f32_dpp v40, v40, v40 quad_perm:[2,3,0,1] row_mask:0xf bank_mask:0xf bound_ctrl:1
	s_nop 1
	v_add_f32_dpp v40, v40, v40 row_half_mirror row_mask:0xf bank_mask:0xf bound_ctrl:1
	s_nop 1
	v_add_f32_dpp v40, v40, v40 row_mirror row_mask:0xf bank_mask:0xf bound_ctrl:1
	ds_bpermute_b32 v41, v199, v40
	s_waitcnt lgkmcnt(0)
	v_add_f32_e32 v40, v40, v41
	v_mul_f32_e32 v41, 0x4f800000, v40
	v_cmp_gt_f32_e32 vcc, s75, v40
	s_nop 1
	v_cndmask_b32_e32 v40, v40, v41, vcc
	v_sqrt_f32_e32 v41, v40
	s_nop 0
	v_add_u32_e32 v56, -1, v41
	v_add_u32_e32 v57, 1, v41
	v_fma_f32 v99, -v56, v41, v40
	v_fma_f32 v128, -v57, v41, v40
	v_cmp_ge_f32_e64 s[0:1], 0, v99
	s_nop 1
	v_cndmask_b32_e64 v41, v41, v56, s[0:1]
	v_cmp_lt_f32_e64 s[0:1], 0, v128
	s_nop 1
	v_cndmask_b32_e64 v41, v41, v57, s[0:1]
	v_mul_f32_e32 v56, 0x37800000, v41
	v_cndmask_b32_e32 v41, v41, v56, vcc
	v_cmp_class_f32_e32 vcc, v40, v201
	v_add_f32_e32 v57, v58, v210
	s_nop 0
	v_cndmask_b32_e32 v40, v41, v40, vcc
	v_max_f32_e32 v138, 0x2b8cbccc, v40
	v_div_scale_f32 v40, s[0:1], v138, v138, 1.0
	v_rcp_f32_e32 v139, v40
	s_nop 0
	v_fma_f32 v56, -v40, v139, 1.0
	v_div_scale_f32 v41, vcc, 1.0, v138, 1.0
	v_fmac_f32_e32 v139, v56, v139
	v_mul_f32_e32 v140, v41, v139
	v_fma_f32 v56, -v40, v140, v41
	v_fmac_f32_e32 v140, v56, v139
	v_fma_f32 v141, -v40, v140, v41
	v_max_f32_e64 v142, -v57, 0
	s_nop 0
	s_nop 1
	v_mul_f32_e64 v58, |v57|, s76
	v_exp_f32_e32 v58, v58
	v_lshl_add_u64 v[128:129], s[54:55], 0, v[124:125]
	s_nop 0
	v_add_f32_e32 v40, 1.0, v58
	v_log_f32_e32 v40, v40
	s_nop 0
	v_mul_f32_e32 v40, 0x3f317218, v40
	v_add_f32_e32 v40, v142, v40
	v_sub_f32_e32 v40, -0.5, v40
	v_div_fmas_f32 v99, v141, v139, v140
	v_div_fixup_f32 v140, v99, v138, 1.0
	v_mul_f32_e32 v24, v24, v140
	v_max_f32_e64 v142, -v26, 0
	v_mul_f32_e32 v42, 0xbfb8aa3b, v42
	v_exp_f32_e32 v42, v42
	s_nop 0
	v_add_f32_e32 v42, 1.0, v42
	v_div_scale_f32 v56, s[0:1], v42, v42, 1.0
	v_rcp_f32_e32 v57, v56
	s_nop 1
	v_mul_f32_e32 v40, 0x3fb8aa3b, v40
	v_exp_f32_e32 v40, v40
	v_fma_f32 v41, -v56, v57, 1.0
	v_fmac_f32_e32 v57, v41, v57
	v_div_scale_f32 v41, vcc, 1.0, v42, 1.0
	v_mul_f32_e32 v58, v41, v57
	v_fma_f32 v99, -v56, v58, v41
	v_fmac_f32_e32 v58, v99, v57
	v_fma_f32 v41, -v56, v58, v41
	v_div_fmas_f32 v41, v41, v57, v58
	v_div_fixup_f32 v41, v41, v42, 1.0
	v_add_f32_e32 v42, -1.0, v41
	v_fma_f32 v42, v208, v42, 1.0
	v_mul_f32_e32 v8, v42, v8
	v_cvt_pk_bf16_f32 v42, v40, 0
	v_cvt_pk_bf16_f32 v58, v24, 0
	v_mul_f32_e32 v24, v41, v24
	v_lshl_add_u64 v[40:41], s[20:21], 0, v[124:125]
	v_cvt_pk_bf16_f32 v8, v8, 0
	v_cvt_pk_bf16_f32 v24, v24, 0
	global_store_short v[128:129], v42, off
	global_store_short v[126:127], v8, off
	global_store_short v[40:41], v58, off
	v_lshl_add_u64 v[40:41], s[18:19], 0, v[124:125]
	global_store_short v[40:41], v24, off
	v_lshlrev_b32_e32 v41, 16, v8
	v_lshlrev_b32_e32 v8, 16, v24
	v_lshlrev_b32_e32 v24, 16, v42
	v_mul_f32_e32 v42, 0xbfb8aa3b, v24
	v_fma_f32 v56, v24, s76, -v42
	v_fmac_f32_e32 v56, 0xb2a5705f, v24
	v_mul_f32_e32 v42, 0xbfb8aa3b, v24
	v_exp_f32_e32 v42, v42
	v_lshlrev_b32_e32 v40, 16, v185
	v_mov_b32_e32 v57, v40
	v_fma_f32 v141, v8, v40, 0
	v_pk_mul_f32 v[56:57], v[56:57], v[40:41]
	v_mov_b32_e32 v8, v42
	v_lshlrev_b32_e32 v58, 16, v58
	s_nop 1
	v_mul_f32_e64 v26, |v26|, s76
	v_exp_f32_e32 v26, v26
	s_nop 0
	v_add_f32_e32 v42, 1.0, v26
	v_add_f32_e32 v56, -1.0, v42
	v_sub_f32_e32 v99, v56, v42
	v_add_f32_e32 v99, 1.0, v99
	v_sub_f32_e32 v56, v26, v56
	v_add_f32_e32 v56, v56, v99
	v_frexp_mant_f32_e32 v99, v42
	v_cvt_f64_f32_e32 v[124:125], v42
	v_frexp_exp_i32_f64_e32 v124, v[124:125]
	v_cmp_gt_f32_e32 vcc, s81, v99
	s_nop 1
	v_subbrev_co_u32_e32 v134, vcc, 0, v124, vcc
	v_sub_u32_e32 v99, 0, v134
	v_ldexp_f32 v42, v42, v99
	v_ldexp_f32 v56, v56, v99
	v_add_f32_e32 v99, -1.0, v42
	v_add_f32_e32 v125, 1.0, v42
	v_add_f32_e32 v124, 1.0, v99
	v_add_f32_e32 v126, -1.0, v125
	v_sub_f32_e32 v124, v42, v124
	v_sub_f32_e32 v42, v42, v126
	v_add_f32_e32 v42, v56, v42
	v_add_f32_e32 v124, v56, v124
	v_add_f32_e32 v56, v125, v42
	v_rcp_f32_e32 v135, v56
	v_sub_f32_e32 v125, v125, v56
	v_add_f32_e32 v42, v42, v125
	v_add_f32_e32 v125, v99, v124
	v_mul_f32_e32 v136, v125, v135
	v_mul_f32_e32 v126, v56, v136
	v_fma_f32 v130, v136, v56, -v126
	v_sub_f32_e32 v99, v99, v125
	v_fmac_f32_e32 v130, v136, v42
	v_add_f32_e32 v99, v124, v99
	v_add_f32_e32 v124, v126, v130
	v_sub_f32_e32 v127, v125, v124
	v_pk_add_f32 v[132:133], v[124:125], v[126:127] neg_lo:[0,1] neg_hi:[0,1]
	v_mov_b32_e32 v131, v124
	v_pk_add_f32 v[124:125], v[132:133], v[130:131] neg_lo:[0,1] neg_hi:[0,1]
	v_add_f32_e32 v99, v99, v125
	v_add_f32_e32 v99, v124, v99
	v_add_f32_e32 v125, v127, v99
	v_mul_f32_e32 v137, v135, v125
	v_mul_f32_e32 v126, v56, v137
	v_fma_f32 v130, v137, v56, -v126
	v_fmac_f32_e32 v130, v137, v42
	v_add_f32_e32 v124, v126, v130
	v_sub_f32_e32 v42, v127, v125
	v_sub_f32_e32 v127, v125, v124
	v_pk_add_f32 v[132:133], v[124:125], v[126:127] neg_lo:[0,1] neg_hi:[0,1]
	v_mov_b32_e32 v131, v124
	v_add_f32_e32 v42, v99, v42
	v_pk_add_f32 v[124:125], v[132:133], v[130:131] neg_lo:[0,1] neg_hi:[0,1]
	v_add_f32_e32 v56, v136, v137
	v_add_f32_e32 v42, v42, v125
	v_add_f32_e32 v42, v124, v42
	v_add_f32_e32 v42, v127, v42
	v_sub_f32_e32 v99, v56, v136
	v_mul_f32_e32 v42, v135, v42
	v_sub_f32_e32 v99, v137, v99
	v_add_f32_e32 v42, v99, v42
	v_add_f32_e32 v125, v56, v42
	v_cvt_f32_i32_e32 v124, v134
	v_mul_f32_e32 v126, v125, v125
	v_fmamk_f32 v99, v126, 0x3e9b6dac, v202
	v_fmaak_f32 v99, v126, v99, 0x3f2aaada
	v_sub_f32_e32 v56, v125, v56
	v_ldexp_f32 v127, v125, 1
	v_mul_f32_e32 v125, v125, v126
	v_pk_mul_f32 v[130:131], v[124:125], v[98:99]
	v_sub_f32_e32 v42, v42, v56
	v_fma_f32 v126, v124, s82, -v130
	v_fmac_f32_e32 v126, 0xb102e308, v124
	v_pk_add_f32 v[124:125], v[130:131], v[126:127]
	v_ldexp_f32 v42, v42, 1
	v_sub_f32_e32 v56, v125, v127
	v_sub_f32_e32 v56, v131, v56
	v_add_f32_e32 v133, v42, v56
	v_mov_b32_e32 v132, v130
	v_pk_add_f32 v[130:131], v[124:125], v[130:131] neg_lo:[0,1] neg_hi:[0,1]
	v_pk_add_f32 v[134:135], v[124:125], v[132:133]
	v_mov_b32_e32 v127, v124
	v_mov_b32_e32 v131, v135
	v_pk_add_f32 v[136:137], v[126:127], v[130:131] neg_lo:[0,1] neg_hi:[0,1]
	v_pk_add_f32 v[126:127], v[126:127], v[130:131]
	v_mov_b32_e32 v132, v133
	v_pk_add_f32 v[130:131], v[126:127], v[124:125] op_sel:[1,0] op_sel_hi:[0,1] neg_lo:[0,1] neg_hi:[0,1]
	v_pk_add_f32 v[138:139], v[134:135], v[130:131] op_sel_hi:[1,0] neg_lo:[0,1] neg_hi:[0,1]
	v_mov_b32_e32 v134, v135
	v_mov_b32_e32 v135, v127
	v_pk_mov_b32 v[130:131], v[124:125], v[130:131] op_sel:[1,0]
	v_mov_b32_e32 v133, v124
	v_pk_add_f32 v[130:131], v[134:135], v[130:131] neg_lo:[0,1] neg_hi:[0,1]
	v_mov_b32_e32 v138, v136
	v_pk_add_f32 v[124:125], v[132:133], v[130:131] neg_lo:[0,1] neg_hi:[0,1]
	v_mov_b32_e32 v137, v127
	v_pk_add_f32 v[130:131], v[138:139], v[124:125]
	s_nop 0
	v_pk_add_f32 v[132:133], v[130:131], v[130:131] op_sel:[0,1] op_sel_hi:[1,0]
	s_nop 0
	v_pk_add_f32 v[126:127], v[126:127], v[132:133] op_sel:[1,0] op_sel_hi:[0,1]
	v_mov_b32_e32 v131, v126
	v_pk_add_f32 v[134:135], v[130:131], v[136:137] neg_lo:[0,1] neg_hi:[0,1]
	s_nop 1
	v_add_f32_e32 v42, 1.0, v26
	v_log_f32_e32 v42, v42
	s_nop 0
	v_mul_f32_e32 v26, 0x3f317218, v42
	v_add_f32_e32 v26, v142, v26
	v_sub_f32_e32 v26, -0.5, v26
	v_mul_f32_e32 v42, 0x3fb8aa3b, v26
	v_exp_f32_e32 v42, v42
	v_mov_b32_e32 v125, v8
	v_mov_b32_e32 v8, v42
	s_nop 0
	s_nop 1
	v_mul_f32_e32 v10, 0xbfb8aa3b, v10
	v_exp_f32_e32 v10, v10
	s_nop 0
	v_add_f32_e32 v10, 1.0, v10
	v_div_scale_f32 v24, s[0:1], v10, v10, 1.0
	v_rcp_f32_e32 v42, v24
	s_nop 0
	v_fma_f32 v26, -v24, v42, 1.0
	v_fmac_f32_e32 v42, v26, v42
	v_div_scale_f32 v26, vcc, 1.0, v10, 1.0
	v_mul_f32_e32 v56, v26, v42
	v_fma_f32 v99, -v24, v56, v26
	v_fmac_f32_e32 v56, v99, v42
	v_fma_f32 v24, -v24, v56, v26
	v_div_fmas_f32 v24, v24, v42, v56
	v_div_fixup_f32 v10, v24, v10, 1.0
	v_mul_f32_e32 v24, v25, v140
	v_add_f32_e32 v25, -1.0, v10
	v_fma_f32 v25, v205, v25, 1.0
	v_mul_f32_e32 v9, v25, v9
	v_cvt_pk_bf16_f32 v25, v8, 0
	v_mul_f32_e32 v8, v10, v24
	v_cvt_pk_bf16_f32 v26, v9, 0
	v_cvt_pk_bf16_f32 v42, v24, 0
	v_cvt_pk_bf16_f32 v10, v8, 0
	v_lshl_add_u64 v[8:9], s[20:21], 0, v[120:121]
	global_store_short v[128:129], v25, off offset:64
	global_store_short v[122:123], v26, off
	global_store_short v[8:9], v42, off
	v_lshl_add_u64 v[8:9], s[18:19], 0, v[120:121]
	global_store_short v[8:9], v10, off
	v_lshlrev_b32_e32 v8, 16, v10
	v_lshlrev_b32_e32 v10, 16, v25
	v_mul_f32_e32 v9, 0xbfb8aa3b, v10
	v_fma_f32 v24, v10, s76, -v9
	v_rndne_f32_e32 v25, v9
	v_fmac_f32_e32 v24, 0xb2a5705f, v10
	v_sub_f32_e32 v9, v9, v25
	v_add_f32_e32 v9, v9, v24
	v_exp_f32_e32 v24, v9
	v_lshlrev_b32_e32 v120, 16, v184
	v_lshlrev_b32_e32 v121, 16, v26
	v_mov_b32_e32 v9, v120
	v_fmac_f32_e32 v141, v8, v120
	v_pk_mul_f32 v[8:9], v[8:9], v[120:121]
	s_nop 0
	v_add_f32_dpp v24, v141, v141 quad_perm:[1,0,3,2] row_mask:0xf bank_mask:0xf bound_ctrl:1
	s_nop 1
	v_add_f32_dpp v24, v24, v24 quad_perm:[2,3,0,1] row_mask:0xf bank_mask:0xf bound_ctrl:1
	v_mov_b32_e32 v56, v41
	v_mov_b32_e32 v41, v68
	v_add_f32_dpp v24, v24, v24 row_half_mirror row_mask:0xf bank_mask:0xf bound_ctrl:1
	v_mul_f32_e32 v10, 0xbfb8aa3b, v10
	v_exp_f32_e32 v10, v10
	v_lshlrev_b32_e32 v26, 16, v42
	v_add_f32_dpp v24, v24, v24 row_mirror row_mask:0xf bank_mask:0xf bound_ctrl:1
	ds_bpermute_b32 v25, v199, v24
	v_mov_b32_e32 v8, v121
	v_mov_b32_e32 v121, v204
	s_waitcnt lgkmcnt(0)
	v_add_f32_e32 v42, v24, v25
	v_pk_fma_f32 v[24:25], v[56:57], v[40:41], 0 op_sel_hi:[1,1,0]
	v_mul_f32_e32 v41, v42, v58
	v_pk_fma_f32 v[8:9], v[8:9], v[120:121], v[24:25]
	v_mul_f32_e32 v26, v42, v26
	v_lshlrev_b64 v[56:57], 11, v[118:119]
	v_mov_b32_dpp v24, v8 quad_perm:[1,0,3,2] row_mask:0xf bank_mask:0xf bound_ctrl:1
	v_mov_b32_dpp v25, v9 quad_perm:[1,0,3,2] row_mask:0xf bank_mask:0xf bound_ctrl:1
	v_pk_add_f32 v[8:9], v[8:9], v[24:25]
	v_fma_f32 v40, v125, v40, -v41
	v_fma_f32 v10, v10, v120, -v26
	v_mov_b32_dpp v24, v8 quad_perm:[2,3,0,1] row_mask:0xf bank_mask:0xf bound_ctrl:1
	v_mov_b32_dpp v25, v9 quad_perm:[2,3,0,1] row_mask:0xf bank_mask:0xf bound_ctrl:1
	v_pk_add_f32 v[8:9], v[8:9], v[24:25]
	v_lshl_add_u64 v[56:57], v[64:65], 0, v[56:57]
	v_cvt_pk_bf16_f32 v40, v40, s0
	v_mov_b32_dpp v24, v8 row_half_mirror row_mask:0xf bank_mask:0xf bound_ctrl:1
	v_mov_b32_dpp v25, v9 row_half_mirror row_mask:0xf bank_mask:0xf bound_ctrl:1
	v_pk_add_f32 v[8:9], v[8:9], v[24:25]
	v_cvt_pk_bf16_f32 v10, v10, s0
	global_store_short v[56:57], v40, off
	v_mov_b32_dpp v24, v8 row_mirror row_mask:0xf bank_mask:0xf bound_ctrl:1
	v_mov_b32_dpp v25, v9 row_mirror row_mask:0xf bank_mask:0xf bound_ctrl:1
	v_pk_add_f32 v[8:9], v[8:9], v[24:25]
	ds_bpermute_b32 v24, v199, v8
	ds_bpermute_b32 v25, v199, v9
	global_store_short v[56:57], v10, off offset:64
	s_and_saveexec_b64 s[0:1], s[2:3]
	s_cbranch_execz .LBB0_561
	v_lshlrev_b64 v[40:41], 7, v[118:119]
	v_lshl_add_u64 v[40:41], s[72:73], 0, v[40:41]
	s_waitcnt lgkmcnt(0)
	v_pk_add_f32 v[8:9], v[8:9], v[24:25]
	global_store_dwordx2 v[40:41], v[8:9], off
.LBB0_561:
	s_or_b64 exec, exec, s[0:1]
	s_waitcnt vmcnt(40)
	v_lshlrev_b32_e32 v9, 16, v183
	v_lshlrev_b32_e32 v8, 16, v182
	s_waitcnt lgkmcnt(0)
	v_pk_mul_f32 v[24:25], v[100:101], v[8:9]
	v_add_f32_e32 v43, v43, v209
	v_pk_mul_f32 v[40:41], v[24:25], v[24:25]
	v_add_f32_e32 v11, v11, v206
	v_add_f32_e32 v10, v40, v41
	s_nop 1
	v_add_f32_dpp v10, v10, v10 quad_perm:[1,0,3,2] row_mask:0xf bank_mask:0xf bound_ctrl:1
	s_nop 1
	v_add_f32_dpp v10, v10, v10 quad_perm:[2,3,0,1] row_mask:0xf bank_mask:0xf bound_ctrl:1
	s_nop 1
	v_add_f32_dpp v10, v10, v10 row_half_mirror row_mask:0xf bank_mask:0xf bound_ctrl:1
	s_nop 1
	v_add_f32_dpp v10, v10, v10 row_mirror row_mask:0xf bank_mask:0xf bound_ctrl:1
	ds_bpermute_b32 v26, v199, v10
	s_waitcnt lgkmcnt(0)
	v_add_f32_e32 v10, v10, v26
	v_mul_f32_e32 v26, 0x4f800000, v10
	v_cmp_gt_f32_e32 vcc, s75, v10
	s_nop 1
	v_cndmask_b32_e32 v10, v10, v26, vcc
	v_sqrt_f32_e32 v26, v10
	s_nop 0
	v_add_u32_e32 v40, -1, v26
	v_add_u32_e32 v41, 1, v26
	v_fma_f32 v42, -v40, v26, v10
	v_fma_f32 v56, -v41, v26, v10
	v_cmp_ge_f32_e64 s[0:1], 0, v42
	s_nop 1
	v_cndmask_b32_e64 v26, v26, v40, s[0:1]
	v_cmp_lt_f32_e64 s[0:1], 0, v56
	v_add_f32_e32 v56, v59, v210
	s_nop 0
	v_cndmask_b32_e64 v26, v26, v41, s[0:1]
	v_mul_f32_e32 v40, 0x37800000, v26
	v_cndmask_b32_e32 v26, v26, v40, vcc
	v_cmp_class_f32_e32 vcc, v10, v201
	s_nop 1
	v_cndmask_b32_e32 v10, v26, v10, vcc
	v_max_f32_e32 v10, 0x2b8cbccc, v10
	v_div_scale_f32 v26, s[0:1], v10, v10, 1.0
	v_rcp_f32_e32 v42, v26
	s_nop 0
	v_fma_f32 v41, -v26, v42, 1.0
	v_div_scale_f32 v40, vcc, 1.0, v10, 1.0
	v_fmac_f32_e32 v42, v41, v42
	v_mul_f32_e32 v126, v40, v42
	v_fma_f32 v41, -v26, v126, v40
	v_fmac_f32_e32 v126, v41, v42
	v_fma_f32 v26, -v26, v126, v40
	v_max_f32_e64 v127, -v56, 0
	v_div_fmas_f32 v26, v26, v42, v126
	v_div_fixup_f32 v10, v26, v10, 1.0
	v_mul_f32_e64 v128, |v56|, s76
	v_exp_f32_e32 v128, v128
	v_mul_f32_e32 v24, v24, v10
	v_mul_f32_e32 v10, v25, v10
	v_cvt_pk_bf16_f32 v124, v24, 0
	s_nop 1
	v_add_f32_e32 v40, 1.0, v128
	v_log_f32_e32 v40, v40
	s_nop 0
	v_mul_f32_e32 v40, 0x3f317218, v40
	v_add_f32_e32 v40, v127, v40
	v_sub_f32_e32 v40, -0.5, v40
	v_mul_f32_e32 v41, 0x3fb8aa3b, v40
	v_exp_f32_e32 v41, v41
	s_nop 0
	v_mov_b32_e32 v26, v41
	s_nop 1
	v_mul_f32_e32 v41, 0xbfb8aa3b, v43
	v_exp_f32_e32 v41, v41
	s_nop 0
	v_add_f32_e32 v41, 1.0, v41
	v_div_scale_f32 v42, s[0:1], v41, v41, 1.0
	v_rcp_f32_e32 v43, v42
	s_nop 0
	v_fma_f32 v40, -v42, v43, 1.0
	v_fmac_f32_e32 v43, v40, v43
	v_div_scale_f32 v40, vcc, 1.0, v41, 1.0
	v_mul_f32_e32 v56, v40, v43
	v_fma_f32 v57, -v42, v56, v40
	v_fmac_f32_e32 v56, v57, v43
	v_fma_f32 v40, -v42, v56, v40
	v_div_fmas_f32 v40, v40, v43, v56
	v_div_fixup_f32 v40, v40, v41, 1.0
	v_add_f32_e32 v41, -1.0, v40
	v_fma_f32 v41, v208, v41, 1.0
	v_mul_f32_e32 v8, v41, v8
	v_cvt_pk_bf16_f32 v26, v26, 0
	v_mul_f32_e32 v24, v40, v24
	v_lshl_add_u64 v[56:57], s[54:55], 0, v[114:115]
	v_lshl_add_u64 v[40:41], s[20:21], 0, v[114:115]
	v_cvt_pk_bf16_f32 v8, v8, 0
	v_cvt_pk_bf16_f32 v24, v24, 0
	global_store_short v[56:57], v26, off
	global_store_short v[116:117], v8, off
	global_store_short v[40:41], v124, off
	v_lshl_add_u64 v[40:41], s[18:19], 0, v[114:115]
	global_store_short v[40:41], v24, off
	v_lshlrev_b32_e32 v41, 16, v8
	v_lshlrev_b32_e32 v8, 16, v24
	v_lshlrev_b32_e32 v24, 16, v26
	v_mul_f32_e32 v26, 0xbfb8aa3b, v24
	v_fma_f32 v42, v24, s76, -v26
	v_fmac_f32_e32 v42, 0xb2a5705f, v24
	v_mul_f32_e32 v26, 0xbfb8aa3b, v24
	v_exp_f32_e32 v26, v26
	v_lshlrev_b32_e32 v40, 16, v181
	v_fma_f32 v125, v8, v40, 0
	v_mov_b32_e32 v43, v40
	v_mov_b32_e32 v8, v26
	v_add_f32_e32 v26, v27, v207
	v_pk_mul_f32 v[42:43], v[42:43], v[40:41]
	v_max_f32_e64 v126, -v26, 0
	s_nop 1
	v_mul_f32_e64 v42, |v26|, s76
	v_exp_f32_e32 v42, v42
	s_nop 0
	v_add_f32_e32 v58, 1.0, v42
	v_add_f32_e32 v26, -1.0, v58
	v_sub_f32_e32 v27, v26, v58
	v_add_f32_e32 v27, 1.0, v27
	v_sub_f32_e32 v26, v42, v26
	v_add_f32_e32 v59, v26, v27
	v_frexp_mant_f32_e32 v99, v58
	v_cvt_f64_f32_e32 v[26:27], v58
	v_frexp_exp_i32_f64_e32 v26, v[26:27]
	v_cmp_gt_f32_e32 vcc, s81, v99
	s_nop 1
	v_subbrev_co_u32_e32 v118, vcc, 0, v26, vcc
	v_sub_u32_e32 v26, 0, v118
	v_ldexp_f32 v27, v58, v26
	v_add_f32_e32 v58, -1.0, v27
	v_add_f32_e32 v99, 1.0, v27
	v_ldexp_f32 v26, v59, v26
	v_add_f32_e32 v59, 1.0, v58
	v_add_f32_e32 v114, -1.0, v99
	v_sub_f32_e32 v59, v27, v59
	v_sub_f32_e32 v27, v27, v114
	v_add_f32_e32 v59, v26, v59
	v_add_f32_e32 v26, v26, v27
	v_add_f32_e32 v119, v99, v26
	v_rcp_f32_e32 v120, v119
	v_sub_f32_e32 v27, v99, v119
	v_add_f32_e32 v99, v26, v27
	v_add_f32_e32 v27, v58, v59
	v_mul_f32_e32 v122, v27, v120
	v_sub_f32_e32 v26, v58, v27
	v_mul_f32_e32 v58, v119, v122
	v_fma_f32 v114, v122, v119, -v58
	v_fmac_f32_e32 v114, v122, v99
	v_add_f32_e32 v121, v59, v26
	v_add_f32_e32 v26, v58, v114
	v_sub_f32_e32 v59, v27, v26
	v_pk_add_f32 v[116:117], v[26:27], v[58:59] neg_lo:[0,1] neg_hi:[0,1]
	v_mov_b32_e32 v115, v26
	v_pk_add_f32 v[26:27], v[116:117], v[114:115] neg_lo:[0,1] neg_hi:[0,1]
	v_add_f32_e32 v27, v121, v27
	v_add_f32_e32 v26, v26, v27
	v_add_f32_e32 v27, v59, v26
	v_mul_f32_e32 v121, v120, v27
	v_mul_f32_e32 v58, v119, v121
	v_fma_f32 v114, v121, v119, -v58
	v_fmac_f32_e32 v114, v121, v99
	v_sub_f32_e32 v59, v59, v27
	v_add_f32_e32 v99, v26, v59
	v_add_f32_e32 v26, v58, v114
	v_sub_f32_e32 v59, v27, v26
	v_pk_add_f32 v[116:117], v[26:27], v[58:59] neg_lo:[0,1] neg_hi:[0,1]
	v_mov_b32_e32 v115, v26
	v_pk_add_f32 v[26:27], v[116:117], v[114:115] neg_lo:[0,1] neg_hi:[0,1]
	s_nop 0
	v_add_f32_e32 v27, v99, v27
	v_add_f32_e32 v26, v26, v27
	v_add_f32_e32 v27, v122, v121
	v_add_f32_e32 v26, v59, v26
	v_sub_f32_e32 v58, v27, v122
	v_mul_f32_e32 v26, v120, v26
	v_sub_f32_e32 v58, v121, v58
	v_add_f32_e32 v58, v58, v26
	v_add_f32_e32 v114, v27, v58
	v_mul_f32_e32 v115, v114, v114
	v_fmamk_f32 v26, v115, 0x3e9b6dac, v202
	v_fmaak_f32 v99, v115, v26, 0x3f2aaada
	v_cvt_f32_i32_e32 v26, v118
	v_sub_f32_e32 v27, v114, v27
	v_sub_f32_e32 v27, v58, v27
	v_ldexp_f32 v116, v27, 1
	v_mul_f32_e32 v27, v114, v115
	v_ldexp_f32 v59, v114, 1
	v_pk_mul_f32 v[114:115], v[26:27], v[98:99]
	s_nop 0
	v_fma_f32 v58, v26, s82, -v114
	v_fmac_f32_e32 v58, 0xb102e308, v26
	v_pk_add_f32 v[26:27], v[114:115], v[58:59]
	s_nop 0
	v_sub_f32_e32 v59, v27, v59
	v_sub_f32_e32 v59, v115, v59
	v_add_f32_e32 v117, v116, v59
	v_mov_b32_e32 v116, v114
	v_pk_add_f32 v[114:115], v[26:27], v[114:115] neg_lo:[0,1] neg_hi:[0,1]
	v_pk_add_f32 v[118:119], v[26:27], v[116:117]
	v_mov_b32_e32 v59, v26
	v_mov_b32_e32 v115, v119
	v_pk_add_f32 v[120:121], v[58:59], v[114:115] neg_lo:[0,1] neg_hi:[0,1]
	v_pk_add_f32 v[58:59], v[58:59], v[114:115]
	v_mov_b32_e32 v116, v117
	v_pk_add_f32 v[114:115], v[58:59], v[26:27] op_sel:[1,0] op_sel_hi:[0,1] neg_lo:[0,1] neg_hi:[0,1]
	v_pk_add_f32 v[122:123], v[118:119], v[114:115] op_sel_hi:[1,0] neg_lo:[0,1] neg_hi:[0,1]
	v_mov_b32_e32 v118, v119
	v_mov_b32_e32 v119, v59
	v_pk_mov_b32 v[114:115], v[26:27], v[114:115] op_sel:[1,0]
	v_mov_b32_e32 v117, v26
	v_pk_add_f32 v[114:115], v[118:119], v[114:115] neg_lo:[0,1] neg_hi:[0,1]
	v_mov_b32_e32 v122, v120
	v_pk_add_f32 v[26:27], v[116:117], v[114:115] neg_lo:[0,1] neg_hi:[0,1]
	v_mov_b32_e32 v121, v59
	v_pk_add_f32 v[114:115], v[122:123], v[26:27]
	s_nop 0
	v_pk_add_f32 v[116:117], v[114:115], v[114:115] op_sel:[0,1] op_sel_hi:[1,0]
	s_nop 0
	v_pk_add_f32 v[58:59], v[58:59], v[116:117] op_sel:[1,0] op_sel_hi:[0,1]
	v_mov_b32_e32 v115, v58
	v_pk_add_f32 v[118:119], v[114:115], v[120:121] neg_lo:[0,1] neg_hi:[0,1]
	v_lshlrev_b32_e32 v114, 16, v124
	s_nop 0
	v_add_f32_e32 v26, 1.0, v42
	v_log_f32_e32 v26, v26
	s_nop 0
	v_mul_f32_e32 v26, 0x3f317218, v26
	v_add_f32_e32 v26, v126, v26
	v_sub_f32_e32 v26, -0.5, v26
	v_mul_f32_e32 v27, 0x3fb8aa3b, v26
	v_exp_f32_e32 v27, v27
	v_mov_b32_e32 v99, v8
	v_mov_b32_e32 v8, v27
	s_nop 0
	s_nop 1
	v_mul_f32_e32 v11, 0xbfb8aa3b, v11
	v_exp_f32_e32 v11, v11
	s_nop 0
	v_add_f32_e32 v11, 1.0, v11
	v_div_scale_f32 v24, s[0:1], v11, v11, 1.0
	v_rcp_f32_e32 v27, v24
	s_nop 0
	v_fma_f32 v26, -v24, v27, 1.0
	v_fmac_f32_e32 v27, v26, v27
	v_div_scale_f32 v26, vcc, 1.0, v11, 1.0
	v_mul_f32_e32 v42, v26, v27
	v_fma_f32 v58, -v24, v42, v26
	v_fmac_f32_e32 v42, v58, v27
	v_fma_f32 v24, -v24, v42, v26
	v_div_fmas_f32 v24, v24, v27, v42
	v_div_fixup_f32 v11, v24, v11, 1.0
	v_add_f32_e32 v24, -1.0, v11
	v_fma_f32 v24, v205, v24, 1.0
	v_mul_f32_e32 v9, v24, v9
	v_cvt_pk_bf16_f32 v26, v8, 0
	v_mul_f32_e32 v8, v11, v10
	v_cvt_pk_bf16_f32 v24, v9, 0
	v_cvt_pk_bf16_f32 v27, v10, 0
	v_cvt_pk_bf16_f32 v10, v8, 0
	v_lshl_add_u64 v[8:9], s[20:21], 0, v[110:111]
	global_store_short v[56:57], v26, off offset:64
	global_store_short v[112:113], v24, off
	global_store_short v[8:9], v27, off
	v_lshl_add_u64 v[8:9], s[18:19], 0, v[110:111]
	global_store_short v[8:9], v10, off
	v_lshlrev_b32_e32 v8, 16, v10
	v_lshlrev_b32_e32 v10, 16, v26
	v_mul_f32_e32 v9, 0xbfb8aa3b, v10
	v_fma_f32 v11, v10, s76, -v9
	v_rndne_f32_e32 v26, v9
	v_fmac_f32_e32 v11, 0xb2a5705f, v10
	v_sub_f32_e32 v9, v9, v26
	v_add_f32_e32 v9, v9, v11
	v_exp_f32_e32 v11, v9
	v_lshlrev_b32_e32 v25, 16, v24
	v_lshlrev_b32_e32 v24, 16, v180
	v_mov_b32_e32 v9, v24
	v_fmac_f32_e32 v125, v8, v24
	v_pk_mul_f32 v[8:9], v[8:9], v[24:25]
	s_nop 0
	v_add_f32_dpp v11, v125, v125 quad_perm:[1,0,3,2] row_mask:0xf bank_mask:0xf bound_ctrl:1
	s_nop 1
	v_add_f32_dpp v11, v11, v11 quad_perm:[2,3,0,1] row_mask:0xf bank_mask:0xf bound_ctrl:1
	v_mov_b32_e32 v42, v41
	v_mov_b32_e32 v41, v68
	v_add_f32_dpp v11, v11, v11 row_half_mirror row_mask:0xf bank_mask:0xf bound_ctrl:1
	v_mul_f32_e32 v56, 0xbfb8aa3b, v10
	v_exp_f32_e32 v56, v56
	v_mov_b32_e32 v8, v25
	v_add_f32_dpp v11, v11, v11 row_mirror row_mask:0xf bank_mask:0xf bound_ctrl:1
	ds_bpermute_b32 v26, v199, v11
	v_mov_b32_e32 v25, v204
	v_lshlrev_b32_e32 v57, 16, v27
	s_waitcnt lgkmcnt(0)
	v_add_f32_e32 v58, v11, v26
	v_pk_fma_f32 v[10:11], v[42:43], v[40:41], 0 op_sel_hi:[1,1,0]
	v_lshlrev_b64 v[26:27], 11, v[108:109]
	v_pk_fma_f32 v[8:9], v[8:9], v[24:25], v[10:11]
	v_mul_f32_e32 v25, v58, v114
	v_fma_f32 v25, v99, v40, -v25
	v_mov_b32_dpp v10, v8 quad_perm:[1,0,3,2] row_mask:0xf bank_mask:0xf bound_ctrl:1
	v_mov_b32_dpp v11, v9 quad_perm:[1,0,3,2] row_mask:0xf bank_mask:0xf bound_ctrl:1
	v_pk_add_f32 v[8:9], v[8:9], v[10:11]
	v_lshl_add_u64 v[26:27], v[64:65], 0, v[26:27]
	v_cvt_pk_bf16_f32 v25, v25, s0
	v_mov_b32_dpp v10, v8 quad_perm:[2,3,0,1] row_mask:0xf bank_mask:0xf bound_ctrl:1
	v_mov_b32_dpp v11, v9 quad_perm:[2,3,0,1] row_mask:0xf bank_mask:0xf bound_ctrl:1
	v_pk_add_f32 v[8:9], v[8:9], v[10:11]
	global_store_short v[26:27], v25, off
	v_mul_f32_e32 v25, v58, v57
	v_mov_b32_dpp v10, v8 row_half_mirror row_mask:0xf bank_mask:0xf bound_ctrl:1
	v_mov_b32_dpp v11, v9 row_half_mirror row_mask:0xf bank_mask:0xf bound_ctrl:1
	v_pk_add_f32 v[8:9], v[8:9], v[10:11]
	v_fma_f32 v24, v56, v24, -v25
	v_cvt_pk_bf16_f32 v24, v24, s0
	v_mov_b32_dpp v10, v8 row_mirror row_mask:0xf bank_mask:0xf bound_ctrl:1
	v_mov_b32_dpp v11, v9 row_mirror row_mask:0xf bank_mask:0xf bound_ctrl:1
	v_pk_add_f32 v[8:9], v[8:9], v[10:11]
	ds_bpermute_b32 v10, v199, v8
	ds_bpermute_b32 v11, v199, v9
	global_store_short v[26:27], v24, off offset:64
	s_and_saveexec_b64 s[0:1], s[2:3]
	s_cbranch_execz .LBB0_563
	v_lshlrev_b64 v[24:25], 7, v[108:109]
	v_lshl_add_u64 v[24:25], s[72:73], 0, v[24:25]
	s_waitcnt lgkmcnt(0)
	v_pk_add_f32 v[8:9], v[8:9], v[10:11]
	global_store_dwordx2 v[24:25], v[8:9], off
.LBB0_563:
	s_or_b64 exec, exec, s[0:1]
	s_waitcnt vmcnt(48)
	v_lshlrev_b32_e32 v9, 16, v179
	v_lshlrev_b32_e32 v8, 16, v178
	s_waitcnt lgkmcnt(0)
	v_pk_mul_f32 v[10:11], v[100:101], v[8:9]
	v_add_f32_e32 v12, v12, v206
	v_pk_mul_f32 v[24:25], v[10:11], v[10:11]
	s_nop 0
	v_add_f32_e32 v24, v24, v25
	s_nop 1
	v_add_f32_dpp v24, v24, v24 quad_perm:[1,0,3,2] row_mask:0xf bank_mask:0xf bound_ctrl:1
	s_nop 1
	v_add_f32_dpp v24, v24, v24 quad_perm:[2,3,0,1] row_mask:0xf bank_mask:0xf bound_ctrl:1
	s_nop 1
	v_add_f32_dpp v24, v24, v24 row_half_mirror row_mask:0xf bank_mask:0xf bound_ctrl:1
	s_nop 1
	v_add_f32_dpp v24, v24, v24 row_mirror row_mask:0xf bank_mask:0xf bound_ctrl:1
	ds_bpermute_b32 v25, v199, v24
	s_waitcnt lgkmcnt(0)
	v_add_f32_e32 v24, v24, v25
	v_mul_f32_e32 v25, 0x4f800000, v24
	v_cmp_gt_f32_e32 vcc, s75, v24
	s_nop 1
	v_cndmask_b32_e32 v24, v24, v25, vcc
	v_sqrt_f32_e32 v25, v24
	s_nop 0
	v_add_u32_e32 v26, -1, v25
	v_add_u32_e32 v27, 1, v25
	v_fma_f32 v40, -v26, v25, v24
	v_fma_f32 v41, -v27, v25, v24
	v_cmp_ge_f32_e64 s[0:1], 0, v40
	s_nop 1
	v_cndmask_b32_e64 v25, v25, v26, s[0:1]
	v_cmp_lt_f32_e64 s[0:1], 0, v41
	s_nop 1
	v_cndmask_b32_e64 v25, v25, v27, s[0:1]
	v_mul_f32_e32 v26, 0x37800000, v25
	v_cndmask_b32_e32 v25, v25, v26, vcc
	v_cmp_class_f32_e32 vcc, v24, v201
	v_add_f32_e32 v27, v60, v210
	s_nop 0
	v_cndmask_b32_e32 v24, v25, v24, vcc
	v_max_f32_e32 v110, 0x2b8cbccc, v24
	v_div_scale_f32 v24, s[0:1], v110, v110, 1.0
	v_rcp_f32_e32 v111, v24
	s_nop 0
	v_fma_f32 v26, -v24, v111, 1.0
	v_div_scale_f32 v25, vcc, 1.0, v110, 1.0
	v_fmac_f32_e32 v111, v26, v111
	v_mul_f32_e32 v112, v25, v111
	v_fma_f32 v26, -v24, v112, v25
	v_fmac_f32_e32 v112, v26, v111
	v_fma_f32 v60, -v24, v112, v25
	v_max_f32_e64 v113, -v27, 0
	s_nop 0
	s_nop 1
	v_mul_f32_e64 v114, |v27|, s76
	v_exp_f32_e32 v114, v114
	s_nop 1
	v_add_f32_e32 v24, 1.0, v114
	v_log_f32_e32 v24, v24
	s_nop 0
	v_mul_f32_e32 v24, 0x3f317218, v24
	v_add_f32_e32 v24, v113, v24
	v_sub_f32_e32 v24, -0.5, v24
	v_add_f32_e32 v27, v44, v209
	v_div_fmas_f32 v42, v60, v111, v112
	v_div_fixup_f32 v44, v42, v110, 1.0
	v_mul_f32_e32 v10, v10, v44
	v_cvt_pk_bf16_f32 v60, v10, 0
	v_mul_f32_e32 v26, 0xbfb8aa3b, v27
	v_exp_f32_e32 v26, v26
	s_nop 0
	v_add_f32_e32 v26, 1.0, v26
	v_div_scale_f32 v27, s[0:1], v26, v26, 1.0
	v_rcp_f32_e32 v40, v27
	v_mul_f32_e32 v11, v11, v44
	s_nop 0
	s_nop 1
	v_mul_f32_e32 v24, 0x3fb8aa3b, v24
	v_exp_f32_e32 v24, v24
	v_fma_f32 v25, -v27, v40, 1.0
	v_fmac_f32_e32 v40, v25, v40
	v_div_scale_f32 v25, vcc, 1.0, v26, 1.0
	v_mul_f32_e32 v41, v25, v40
	v_fma_f32 v42, -v27, v41, v25
	v_fmac_f32_e32 v41, v42, v40
	v_fma_f32 v25, -v27, v41, v25
	v_div_fmas_f32 v25, v25, v40, v41
	v_div_fixup_f32 v25, v25, v26, 1.0
	v_add_f32_e32 v26, -1.0, v25
	v_fma_f32 v26, v208, v26, 1.0
	v_mul_f32_e32 v8, v26, v8
	v_cvt_pk_bf16_f32 v26, v24, 0
	v_mul_f32_e32 v10, v25, v10
	v_lshl_add_u64 v[40:41], s[54:55], 0, v[104:105]
	v_lshl_add_u64 v[24:25], s[20:21], 0, v[104:105]
	v_cvt_pk_bf16_f32 v8, v8, 0
	v_cvt_pk_bf16_f32 v10, v10, 0
	global_store_short v[40:41], v26, off
	global_store_short v[106:107], v8, off
	global_store_short v[24:25], v60, off
	v_lshl_add_u64 v[24:25], s[18:19], 0, v[104:105]
	global_store_short v[24:25], v10, off
	v_lshlrev_b32_e32 v25, 16, v8
	v_lshlrev_b32_e32 v8, 16, v10
	v_lshlrev_b32_e32 v10, 16, v26
	v_mul_f32_e32 v26, 0xbfb8aa3b, v10
	v_fma_f32 v27, v10, s76, -v26
	v_rndne_f32_e32 v42, v26
	v_fmac_f32_e32 v27, 0xb2a5705f, v10
	v_sub_f32_e32 v26, v26, v42
	s_waitcnt vmcnt(51)
	v_lshlrev_b32_e32 v24, 16, v177
	v_add_f32_e32 v26, v26, v27
	v_mul_f32_e32 v43, 0xbfb8aa3b, v10
	v_exp_f32_e32 v43, v43
	v_mov_b32_e32 v27, v24
	v_pk_mul_f32 v[26:27], v[26:27], v[24:25]
	v_fma_f32 v112, v8, v24, 0
	v_add_f32_e32 v26, v28, v207
	v_mov_b32_e32 v8, v43
	v_max_f32_e64 v113, -v26, 0
	s_nop 1
	v_mul_f32_e64 v26, |v26|, s76
	v_exp_f32_e32 v26, v26
	s_nop 0
	v_add_f32_e32 v28, 1.0, v26
	v_add_f32_e32 v42, -1.0, v28
	v_sub_f32_e32 v43, v42, v28
	v_add_f32_e32 v43, 1.0, v43
	v_sub_f32_e32 v42, v26, v42
	v_add_f32_e32 v56, v42, v43
	v_frexp_mant_f32_e32 v57, v28
	v_cvt_f64_f32_e32 v[42:43], v28
	v_frexp_exp_i32_f64_e32 v42, v[42:43]
	v_cmp_gt_f32_e32 vcc, s81, v57
	s_nop 1
	v_subbrev_co_u32_e32 v106, vcc, 0, v42, vcc
	v_sub_u32_e32 v42, 0, v106
	v_ldexp_f32 v28, v28, v42
	v_ldexp_f32 v42, v56, v42
	v_add_f32_e32 v56, -1.0, v28
	v_add_f32_e32 v43, 1.0, v56
	v_sub_f32_e32 v43, v28, v43
	v_add_f32_e32 v57, v42, v43
	v_add_f32_e32 v43, 1.0, v28
	v_add_f32_e32 v58, -1.0, v43
	v_sub_f32_e32 v28, v28, v58
	v_add_f32_e32 v28, v42, v28
	v_add_f32_e32 v99, v43, v28
	v_rcp_f32_e32 v107, v99
	v_sub_f32_e32 v42, v43, v99
	v_add_f32_e32 v43, v56, v57
	v_add_f32_e32 v28, v28, v42
	v_mul_f32_e32 v109, v43, v107
	v_sub_f32_e32 v42, v56, v43
	v_mul_f32_e32 v56, v99, v109
	v_fma_f32 v58, v109, v99, -v56
	v_fmac_f32_e32 v58, v109, v28
	v_add_f32_e32 v108, v57, v42
	v_add_f32_e32 v42, v56, v58
	v_sub_f32_e32 v57, v43, v42
	v_pk_add_f32 v[104:105], v[42:43], v[56:57] neg_lo:[0,1] neg_hi:[0,1]
	v_mov_b32_e32 v59, v42
	v_pk_add_f32 v[42:43], v[104:105], v[58:59] neg_lo:[0,1] neg_hi:[0,1]
	v_add_f32_e32 v43, v108, v43
	v_add_f32_e32 v42, v42, v43
	v_add_f32_e32 v43, v57, v42
	v_mul_f32_e32 v108, v107, v43
	v_mul_f32_e32 v56, v99, v108
	v_fma_f32 v58, v108, v99, -v56
	v_fmac_f32_e32 v58, v108, v28
	v_sub_f32_e32 v28, v57, v43
	v_add_f32_e32 v28, v42, v28
	v_add_f32_e32 v42, v56, v58
	v_sub_f32_e32 v57, v43, v42
	v_pk_add_f32 v[104:105], v[42:43], v[56:57] neg_lo:[0,1] neg_hi:[0,1]
	v_mov_b32_e32 v59, v42
	v_pk_add_f32 v[42:43], v[104:105], v[58:59] neg_lo:[0,1] neg_hi:[0,1]
	s_nop 0
	v_add_f32_e32 v28, v28, v43
	v_add_f32_e32 v28, v42, v28
	v_add_f32_e32 v43, v109, v108
	v_add_f32_e32 v28, v57, v28
	v_sub_f32_e32 v42, v43, v109
	v_mul_f32_e32 v28, v107, v28
	v_sub_f32_e32 v42, v108, v42
	v_add_f32_e32 v28, v42, v28
	v_add_f32_e32 v56, v43, v28
	v_mul_f32_e32 v58, v56, v56
	v_fmamk_f32 v42, v58, 0x3e9b6dac, v202
	v_fmaak_f32 v99, v58, v42, 0x3f2aaada
	v_cvt_f32_i32_e32 v42, v106
	v_sub_f32_e32 v43, v56, v43
	v_sub_f32_e32 v28, v28, v43
	v_mul_f32_e32 v43, v56, v58
	v_pk_mul_f32 v[58:59], v[42:43], v[98:99]
	v_ldexp_f32 v57, v56, 1
	v_fma_f32 v56, v42, s82, -v58
	v_fmac_f32_e32 v56, 0xb102e308, v42
	v_pk_add_f32 v[42:43], v[58:59], v[56:57]
	v_ldexp_f32 v28, v28, 1
	v_sub_f32_e32 v57, v43, v57
	v_sub_f32_e32 v57, v59, v57
	v_add_f32_e32 v105, v28, v57
	v_mov_b32_e32 v104, v58
	v_pk_add_f32 v[58:59], v[42:43], v[58:59] neg_lo:[0,1] neg_hi:[0,1]
	v_pk_add_f32 v[106:107], v[42:43], v[104:105]
	v_mov_b32_e32 v57, v42
	v_mov_b32_e32 v59, v107
	v_pk_add_f32 v[108:109], v[56:57], v[58:59] neg_lo:[0,1] neg_hi:[0,1]
	v_pk_add_f32 v[56:57], v[56:57], v[58:59]
	v_mov_b32_e32 v104, v105
	v_pk_add_f32 v[58:59], v[56:57], v[42:43] op_sel:[1,0] op_sel_hi:[0,1] neg_lo:[0,1] neg_hi:[0,1]
	v_pk_add_f32 v[110:111], v[106:107], v[58:59] op_sel_hi:[1,0] neg_lo:[0,1] neg_hi:[0,1]
	v_mov_b32_e32 v106, v107
	v_mov_b32_e32 v107, v57
	v_pk_mov_b32 v[58:59], v[42:43], v[58:59] op_sel:[1,0]
	v_mov_b32_e32 v105, v42
	v_pk_add_f32 v[58:59], v[106:107], v[58:59] neg_lo:[0,1] neg_hi:[0,1]
	v_mov_b32_e32 v110, v108
	v_pk_add_f32 v[42:43], v[104:105], v[58:59] neg_lo:[0,1] neg_hi:[0,1]
	v_mov_b32_e32 v109, v57
	v_pk_add_f32 v[58:59], v[110:111], v[42:43]
	s_nop 0
	v_pk_add_f32 v[104:105], v[58:59], v[58:59] op_sel:[0,1] op_sel_hi:[1,0]
	s_nop 0
	v_pk_add_f32 v[56:57], v[56:57], v[104:105] op_sel:[1,0] op_sel_hi:[0,1]
	v_mov_b32_e32 v59, v56
	v_pk_add_f32 v[106:107], v[58:59], v[108:109] neg_lo:[0,1] neg_hi:[0,1]
	v_lshlrev_b32_e32 v58, 16, v60
	s_nop 0
	v_add_f32_e32 v28, 1.0, v26
	v_log_f32_e32 v28, v28
	s_nop 0
	v_mul_f32_e32 v26, 0x3f317218, v28
	v_add_f32_e32 v26, v113, v26
	v_sub_f32_e32 v26, -0.5, v26
	v_mul_f32_e32 v28, 0x3fb8aa3b, v26
	v_exp_f32_e32 v28, v28
	v_mov_b32_e32 v57, v8
	v_mov_b32_e32 v8, v28
	s_nop 0
	s_nop 1
	v_mul_f32_e32 v10, 0xbfb8aa3b, v12
	v_exp_f32_e32 v10, v10
	s_nop 0
	v_add_f32_e32 v10, 1.0, v10
	v_div_scale_f32 v12, s[0:1], v10, v10, 1.0
	v_rcp_f32_e32 v28, v12
	s_nop 0
	v_fma_f32 v26, -v12, v28, 1.0
	v_fmac_f32_e32 v28, v26, v28
	v_div_scale_f32 v26, vcc, 1.0, v10, 1.0
	v_mul_f32_e32 v42, v26, v28
	v_fma_f32 v43, -v12, v42, v26
	v_fmac_f32_e32 v42, v43, v28
	v_fma_f32 v12, -v12, v42, v26
	v_div_fmas_f32 v12, v12, v28, v42
	v_div_fixup_f32 v10, v12, v10, 1.0
	v_add_f32_e32 v12, -1.0, v10
	v_fma_f32 v12, v205, v12, 1.0
	v_mul_f32_e32 v9, v12, v9
	v_cvt_pk_bf16_f32 v12, v8, 0
	v_mul_f32_e32 v8, v10, v11
	v_cvt_pk_bf16_f32 v26, v9, 0
	v_cvt_pk_bf16_f32 v28, v11, 0
	v_cvt_pk_bf16_f32 v10, v8, 0
	v_lshl_add_u64 v[8:9], s[20:21], 0, v[66:67]
	global_store_short v[40:41], v12, off offset:64
	global_store_short v[102:103], v26, off
	global_store_short v[8:9], v28, off
	v_lshl_add_u64 v[8:9], s[18:19], 0, v[66:67]
	global_store_short v[8:9], v10, off
	v_lshlrev_b32_e32 v8, 16, v10
	v_lshlrev_b32_e32 v10, 16, v12
	v_mul_f32_e32 v9, 0xbfb8aa3b, v10
	v_fma_f32 v11, v10, s76, -v9
	v_rndne_f32_e32 v12, v9
	v_fmac_f32_e32 v11, 0xb2a5705f, v10
	v_sub_f32_e32 v9, v9, v12
	v_add_f32_e32 v9, v9, v11
	v_exp_f32_e32 v11, v9
	s_waitcnt vmcnt(54)
	v_lshlrev_b32_e32 v40, 16, v176
	v_lshlrev_b32_e32 v41, 16, v26
	v_mov_b32_e32 v9, v40
	v_fmac_f32_e32 v112, v8, v40
	v_pk_mul_f32 v[8:9], v[8:9], v[40:41]
	s_nop 0
	v_add_f32_dpp v11, v112, v112 quad_perm:[1,0,3,2] row_mask:0xf bank_mask:0xf bound_ctrl:1
	s_nop 1
	v_add_f32_dpp v11, v11, v11 quad_perm:[2,3,0,1] row_mask:0xf bank_mask:0xf bound_ctrl:1
	v_mov_b32_e32 v26, v25
	v_mov_b32_e32 v25, v68
	v_add_f32_dpp v11, v11, v11 row_half_mirror row_mask:0xf bank_mask:0xf bound_ctrl:1
	v_mul_f32_e32 v42, 0xbfb8aa3b, v10
	v_exp_f32_e32 v42, v42
	v_mov_b32_e32 v8, v41
	v_add_f32_dpp v11, v11, v11 row_mirror row_mask:0xf bank_mask:0xf bound_ctrl:1
	ds_bpermute_b32 v12, v199, v11
	v_mov_b32_e32 v41, v204
	v_lshlrev_b32_e32 v28, 16, v28
	s_waitcnt lgkmcnt(0)
	v_add_f32_e32 v12, v11, v12
	v_pk_fma_f32 v[10:11], v[26:27], v[24:25], 0 op_sel_hi:[1,1,0]
	v_mul_f32_e32 v25, v12, v58
	v_pk_fma_f32 v[8:9], v[8:9], v[40:41], v[10:11]
	v_mul_f32_e32 v12, v12, v28
	v_lshlrev_b64 v[26:27], 11, v[54:55]
	v_mov_b32_dpp v10, v8 quad_perm:[1,0,3,2] row_mask:0xf bank_mask:0xf bound_ctrl:1
	v_mov_b32_dpp v11, v9 quad_perm:[1,0,3,2] row_mask:0xf bank_mask:0xf bound_ctrl:1
	v_pk_add_f32 v[8:9], v[8:9], v[10:11]
	v_fma_f32 v24, v57, v24, -v25
	v_fma_f32 v12, v42, v40, -v12
	v_mov_b32_dpp v10, v8 quad_perm:[2,3,0,1] row_mask:0xf bank_mask:0xf bound_ctrl:1
	v_mov_b32_dpp v11, v9 quad_perm:[2,3,0,1] row_mask:0xf bank_mask:0xf bound_ctrl:1
	v_pk_add_f32 v[8:9], v[8:9], v[10:11]
	v_lshl_add_u64 v[26:27], v[64:65], 0, v[26:27]
	v_cvt_pk_bf16_f32 v24, v24, s0
	v_mov_b32_dpp v10, v8 row_half_mirror row_mask:0xf bank_mask:0xf bound_ctrl:1
	v_mov_b32_dpp v11, v9 row_half_mirror row_mask:0xf bank_mask:0xf bound_ctrl:1
	v_pk_add_f32 v[8:9], v[8:9], v[10:11]
	v_cvt_pk_bf16_f32 v12, v12, s0
	global_store_short v[26:27], v24, off
	v_mov_b32_dpp v10, v8 row_mirror row_mask:0xf bank_mask:0xf bound_ctrl:1
	v_mov_b32_dpp v11, v9 row_mirror row_mask:0xf bank_mask:0xf bound_ctrl:1
	v_pk_add_f32 v[8:9], v[8:9], v[10:11]
	ds_bpermute_b32 v10, v199, v8
	ds_bpermute_b32 v11, v199, v9
	global_store_short v[26:27], v12, off offset:64
	s_and_saveexec_b64 s[0:1], s[2:3]
	s_cbranch_execz .LBB0_565
	v_lshlrev_b64 v[24:25], 7, v[54:55]
	v_lshl_add_u64 v[24:25], s[72:73], 0, v[24:25]
	s_waitcnt lgkmcnt(0)
	v_pk_add_f32 v[8:9], v[8:9], v[10:11]
	global_store_dwordx2 v[24:25], v[8:9], off
.LBB0_565:
	s_or_b64 exec, exec, s[0:1]
	v_lshlrev_b32_e32 v9, 16, v175
	v_lshlrev_b32_e32 v8, 16, v174
	s_waitcnt lgkmcnt(0)
	v_pk_mul_f32 v[10:11], v[100:101], v[8:9]
	v_add_f32_e32 v13, v13, v206
	v_pk_mul_f32 v[24:25], v[10:11], v[10:11]
	s_nop 0
	v_add_f32_e32 v12, v24, v25
	s_nop 1
	v_add_f32_dpp v12, v12, v12 quad_perm:[1,0,3,2] row_mask:0xf bank_mask:0xf bound_ctrl:1
	s_nop 1
	v_add_f32_dpp v12, v12, v12 quad_perm:[2,3,0,1] row_mask:0xf bank_mask:0xf bound_ctrl:1
	s_nop 1
	v_add_f32_dpp v12, v12, v12 row_half_mirror row_mask:0xf bank_mask:0xf bound_ctrl:1
	s_nop 1
	v_add_f32_dpp v12, v12, v12 row_mirror row_mask:0xf bank_mask:0xf bound_ctrl:1
	ds_bpermute_b32 v24, v199, v12
	s_waitcnt lgkmcnt(0)
	v_add_f32_e32 v12, v12, v24
	v_mul_f32_e32 v24, 0x4f800000, v12
	v_cmp_gt_f32_e32 vcc, s75, v12
	s_nop 1
	v_cndmask_b32_e32 v12, v12, v24, vcc
	v_sqrt_f32_e32 v24, v12
	s_nop 0
	v_add_u32_e32 v25, -1, v24
	v_add_u32_e32 v26, 1, v24
	v_fma_f32 v27, -v25, v24, v12
	v_fma_f32 v28, -v26, v24, v12
	v_cmp_ge_f32_e64 s[0:1], 0, v27
	v_add_f32_e32 v27, v61, v210
	s_nop 0
	v_cndmask_b32_e64 v24, v24, v25, s[0:1]
	v_cmp_lt_f32_e64 s[0:1], 0, v28
	s_nop 1
	v_cndmask_b32_e64 v24, v24, v26, s[0:1]
	v_mul_f32_e32 v25, 0x37800000, v24
	v_cndmask_b32_e32 v24, v24, v25, vcc
	v_cmp_class_f32_e32 vcc, v12, v201
	s_nop 1
	v_cndmask_b32_e32 v12, v24, v12, vcc
	v_max_f32_e32 v12, 0x2b8cbccc, v12
	v_div_scale_f32 v24, s[0:1], v12, v12, 1.0
	v_rcp_f32_e32 v28, v24
	v_div_scale_f32 v25, vcc, 1.0, v12, 1.0
	v_fma_f32 v26, -v24, v28, 1.0
	v_fmac_f32_e32 v28, v26, v28
	v_mul_f32_e32 v44, v25, v28
	v_fma_f32 v26, -v24, v44, v25
	v_fmac_f32_e32 v44, v26, v28
	v_fma_f32 v60, -v24, v44, v25
	v_max_f32_e64 v61, -v27, 0
	v_div_fmas_f32 v28, v60, v28, v44
	v_div_fixup_f32 v12, v28, v12, 1.0
	v_mul_f32_e32 v10, v10, v12
	v_mul_f32_e64 v66, |v27|, s76
	v_exp_f32_e32 v66, v66
	v_mul_f32_e32 v11, v11, v12
	s_nop 0
	v_cvt_pk_bf16_f32 v58, v10, 0
	s_nop 1
	v_add_f32_e32 v24, 1.0, v66
	v_log_f32_e32 v24, v24
	s_nop 0
	v_mul_f32_e32 v24, 0x3f317218, v24
	v_add_f32_e32 v24, v61, v24
	v_sub_f32_e32 v24, -0.5, v24
	v_add_f32_e32 v27, v45, v209
	s_nop 1
	v_mul_f32_e32 v26, 0xbfb8aa3b, v27
	v_exp_f32_e32 v26, v26
	s_nop 0
	v_add_f32_e32 v26, 1.0, v26
	v_div_scale_f32 v27, s[0:1], v26, v26, 1.0
	v_rcp_f32_e32 v28, v27
	s_nop 1
	v_mul_f32_e32 v24, 0x3fb8aa3b, v24
	v_exp_f32_e32 v24, v24
	v_fma_f32 v25, -v27, v28, 1.0
	v_fmac_f32_e32 v28, v25, v28
	v_div_scale_f32 v25, vcc, 1.0, v26, 1.0
	v_mul_f32_e32 v40, v25, v28
	v_fma_f32 v41, -v27, v40, v25
	v_fmac_f32_e32 v40, v41, v28
	v_fma_f32 v25, -v27, v40, v25
	v_div_fmas_f32 v25, v25, v28, v40
	v_div_fixup_f32 v25, v25, v26, 1.0
	v_add_f32_e32 v26, -1.0, v25
	v_fma_f32 v26, v208, v26, 1.0
	v_mul_f32_e32 v8, v26, v8
	v_cvt_pk_bf16_f32 v26, v24, 0
	v_mul_f32_e32 v10, v25, v10
	v_lshl_add_u64 v[40:41], s[54:55], 0, v[50:51]
	v_lshl_add_u64 v[24:25], s[20:21], 0, v[50:51]
	v_cvt_pk_bf16_f32 v8, v8, 0
	v_cvt_pk_bf16_f32 v10, v10, 0
	global_store_short v[40:41], v26, off
	global_store_short v[52:53], v8, off
	global_store_short v[24:25], v58, off
	v_lshl_add_u64 v[24:25], s[18:19], 0, v[50:51]
	global_store_short v[24:25], v10, off
	v_lshlrev_b32_e32 v25, 16, v8
	v_lshlrev_b32_e32 v8, 16, v10
	v_lshlrev_b32_e32 v10, 16, v26
	v_mul_f32_e32 v26, 0xbfb8aa3b, v10
	v_fma_f32 v27, v10, s76, -v26
	v_rndne_f32_e32 v28, v26
	v_fmac_f32_e32 v27, 0xb2a5705f, v10
	v_sub_f32_e32 v26, v26, v28
	v_add_f32_e32 v26, v26, v27
	s_waitcnt vmcnt(59)
	v_lshlrev_b32_e32 v24, 16, v173
	v_mul_f32_e32 v42, 0xbfb8aa3b, v10
	v_exp_f32_e32 v42, v42
	v_mov_b32_e32 v27, v24
	v_pk_mul_f32 v[26:27], v[26:27], v[24:25]
	v_fma_f32 v59, v8, v24, 0
	v_add_f32_e32 v26, v29, v207
	v_mov_b32_e32 v8, v42
	v_max_f32_e64 v60, -v26, 0
	s_nop 1
	v_mul_f32_e64 v26, |v26|, s76
	v_exp_f32_e32 v26, v26
	s_nop 0
	v_add_f32_e32 v42, 1.0, v26
	v_add_f32_e32 v28, -1.0, v42
	v_sub_f32_e32 v29, v28, v42
	v_add_f32_e32 v29, 1.0, v29
	v_sub_f32_e32 v28, v26, v28
	v_add_f32_e32 v43, v28, v29
	v_frexp_mant_f32_e32 v44, v42
	v_cvt_f64_f32_e32 v[28:29], v42
	v_frexp_exp_i32_f64_e32 v28, v[28:29]
	v_cmp_gt_f32_e32 vcc, s81, v44
	s_nop 1
	v_subbrev_co_u32_e32 v52, vcc, 0, v28, vcc
	v_sub_u32_e32 v28, 0, v52
	v_ldexp_f32 v29, v42, v28
	v_add_f32_e32 v42, -1.0, v29
	v_add_f32_e32 v44, 1.0, v29
	v_ldexp_f32 v28, v43, v28
	v_add_f32_e32 v43, 1.0, v42
	v_add_f32_e32 v45, -1.0, v44
	v_sub_f32_e32 v43, v29, v43
	v_sub_f32_e32 v29, v29, v45
	v_add_f32_e32 v43, v28, v43
	v_add_f32_e32 v28, v28, v29
	v_add_f32_e32 v53, v44, v28
	v_rcp_f32_e32 v55, v53
	v_sub_f32_e32 v29, v44, v53
	v_add_f32_e32 v54, v28, v29
	v_add_f32_e32 v29, v42, v43
	v_mul_f32_e32 v57, v29, v55
	v_sub_f32_e32 v28, v42, v29
	v_mul_f32_e32 v42, v53, v57
	v_fma_f32 v44, v57, v53, -v42
	v_fmac_f32_e32 v44, v57, v54
	v_add_f32_e32 v56, v43, v28
	v_add_f32_e32 v28, v42, v44
	v_sub_f32_e32 v43, v29, v28
	v_pk_add_f32 v[50:51], v[28:29], v[42:43] neg_lo:[0,1] neg_hi:[0,1]
	v_mov_b32_e32 v45, v28
	v_pk_add_f32 v[28:29], v[50:51], v[44:45] neg_lo:[0,1] neg_hi:[0,1]
	v_add_f32_e32 v29, v56, v29
	v_add_f32_e32 v28, v28, v29
	v_add_f32_e32 v29, v43, v28
	v_mul_f32_e32 v56, v55, v29
	v_mul_f32_e32 v42, v53, v56
	v_fma_f32 v44, v56, v53, -v42
	v_fmac_f32_e32 v44, v56, v54
	v_sub_f32_e32 v43, v43, v29
	v_add_f32_e32 v53, v28, v43
	v_add_f32_e32 v28, v42, v44
	v_sub_f32_e32 v43, v29, v28
	v_pk_add_f32 v[50:51], v[28:29], v[42:43] neg_lo:[0,1] neg_hi:[0,1]
	v_mov_b32_e32 v45, v28
	v_pk_add_f32 v[28:29], v[50:51], v[44:45] neg_lo:[0,1] neg_hi:[0,1]
	s_nop 0
	v_add_f32_e32 v29, v53, v29
	v_add_f32_e32 v28, v28, v29
	v_add_f32_e32 v29, v57, v56
	v_add_f32_e32 v28, v43, v28
	v_sub_f32_e32 v42, v29, v57
	v_mul_f32_e32 v28, v55, v28
	v_sub_f32_e32 v42, v56, v42
	v_add_f32_e32 v42, v42, v28
	v_add_f32_e32 v44, v29, v42
	v_mul_f32_e32 v45, v44, v44
	v_fmamk_f32 v28, v45, 0x3e9b6dac, v202
	v_fmaak_f32 v99, v45, v28, 0x3f2aaada
	v_cvt_f32_i32_e32 v28, v52
	v_sub_f32_e32 v29, v44, v29
	v_sub_f32_e32 v29, v42, v29
	v_ldexp_f32 v50, v29, 1
	v_mul_f32_e32 v29, v44, v45
	v_ldexp_f32 v43, v44, 1
	v_pk_mul_f32 v[44:45], v[28:29], v[98:99]
	s_nop 0
	v_fma_f32 v42, v28, s82, -v44
	v_fmac_f32_e32 v42, 0xb102e308, v28
	v_pk_add_f32 v[28:29], v[44:45], v[42:43]
	s_nop 0
	v_sub_f32_e32 v43, v29, v43
	v_sub_f32_e32 v43, v45, v43
	v_add_f32_e32 v51, v50, v43
	v_mov_b32_e32 v50, v44
	v_pk_add_f32 v[44:45], v[28:29], v[44:45] neg_lo:[0,1] neg_hi:[0,1]
	v_pk_add_f32 v[52:53], v[28:29], v[50:51]
	v_mov_b32_e32 v43, v28
	v_mov_b32_e32 v45, v53
	v_pk_add_f32 v[54:55], v[42:43], v[44:45] neg_lo:[0,1] neg_hi:[0,1]
	v_pk_add_f32 v[42:43], v[42:43], v[44:45]
	v_mov_b32_e32 v50, v51
	v_pk_add_f32 v[44:45], v[42:43], v[28:29] op_sel:[1,0] op_sel_hi:[0,1] neg_lo:[0,1] neg_hi:[0,1]
	v_pk_add_f32 v[56:57], v[52:53], v[44:45] op_sel_hi:[1,0] neg_lo:[0,1] neg_hi:[0,1]
	v_mov_b32_e32 v52, v53
	v_mov_b32_e32 v53, v43
	v_pk_mov_b32 v[44:45], v[28:29], v[44:45] op_sel:[1,0]
	v_mov_b32_e32 v51, v28
	v_pk_add_f32 v[44:45], v[52:53], v[44:45] neg_lo:[0,1] neg_hi:[0,1]
	v_mov_b32_e32 v56, v54
	v_pk_add_f32 v[28:29], v[50:51], v[44:45] neg_lo:[0,1] neg_hi:[0,1]
	v_mov_b32_e32 v55, v43
	v_pk_add_f32 v[44:45], v[56:57], v[28:29]
	s_nop 0
	v_pk_add_f32 v[50:51], v[44:45], v[44:45] op_sel:[0,1] op_sel_hi:[1,0]
	s_nop 0
	v_pk_add_f32 v[42:43], v[42:43], v[50:51] op_sel:[1,0] op_sel_hi:[0,1]
	v_mov_b32_e32 v45, v42
	v_pk_add_f32 v[52:53], v[44:45], v[54:55] neg_lo:[0,1] neg_hi:[0,1]
	v_lshlrev_b32_e32 v45, 16, v58
	s_nop 0
	v_add_f32_e32 v28, 1.0, v26
	v_log_f32_e32 v28, v28
	s_nop 0
	v_mul_f32_e32 v26, 0x3f317218, v28
	v_add_f32_e32 v26, v60, v26
	v_sub_f32_e32 v26, -0.5, v26
	v_mul_f32_e32 v28, 0x3fb8aa3b, v26
	v_exp_f32_e32 v28, v28
	v_mov_b32_e32 v44, v8
	v_mov_b32_e32 v8, v28
	s_nop 0
	s_nop 1
	v_mul_f32_e32 v10, 0xbfb8aa3b, v13
	v_exp_f32_e32 v10, v10
	s_nop 0
	v_add_f32_e32 v10, 1.0, v10
	v_div_scale_f32 v13, s[0:1], v10, v10, 1.0
	v_rcp_f32_e32 v28, v13
	s_nop 0
	v_fma_f32 v26, -v13, v28, 1.0
	v_fmac_f32_e32 v28, v26, v28
	v_div_scale_f32 v26, vcc, 1.0, v10, 1.0
	v_mul_f32_e32 v29, v26, v28
	v_fma_f32 v42, -v13, v29, v26
	v_fmac_f32_e32 v29, v42, v28
	v_fma_f32 v13, -v13, v29, v26
	v_div_fmas_f32 v13, v13, v28, v29
	v_div_fixup_f32 v10, v13, v10, 1.0
	v_add_f32_e32 v12, -1.0, v10
	v_fma_f32 v12, v205, v12, 1.0
	v_mul_f32_e32 v9, v12, v9
	v_cvt_pk_bf16_f32 v26, v8, 0
	v_mul_f32_e32 v8, v10, v11
	v_cvt_pk_bf16_f32 v12, v9, 0
	v_cvt_pk_bf16_f32 v28, v11, 0
	v_cvt_pk_bf16_f32 v10, v8, 0
	v_lshl_add_u64 v[8:9], s[20:21], 0, v[38:39]
	global_store_short v[40:41], v26, off offset:64
	global_store_short v[48:49], v12, off
	global_store_short v[8:9], v28, off
	v_lshl_add_u64 v[8:9], s[18:19], 0, v[38:39]
	global_store_short v[8:9], v10, off
	v_lshlrev_b32_e32 v8, 16, v10
	v_lshlrev_b32_e32 v10, 16, v26
	v_mul_f32_e32 v9, 0xbfb8aa3b, v10
	v_fma_f32 v11, v10, s76, -v9
	v_rndne_f32_e32 v26, v9
	v_fmac_f32_e32 v11, 0xb2a5705f, v10
	v_sub_f32_e32 v9, v9, v26
	v_add_f32_e32 v9, v9, v11
	v_exp_f32_e32 v11, v9
	v_lshlrev_b32_e32 v13, 16, v12
	s_waitcnt vmcnt(62)
	v_lshlrev_b32_e32 v12, 16, v172
	v_mov_b32_e32 v9, v12
	v_fmac_f32_e32 v59, v8, v12
	v_pk_mul_f32 v[8:9], v[8:9], v[12:13]
	s_nop 0
	v_add_f32_dpp v11, v59, v59 quad_perm:[1,0,3,2] row_mask:0xf bank_mask:0xf bound_ctrl:1
	s_nop 1
	v_add_f32_dpp v11, v11, v11 quad_perm:[2,3,0,1] row_mask:0xf bank_mask:0xf bound_ctrl:1
	v_lshlrev_b32_e32 v28, 16, v28
	v_mul_f32_e32 v29, 0xbfb8aa3b, v10
	v_exp_f32_e32 v29, v29
	v_add_f32_dpp v11, v11, v11 row_half_mirror row_mask:0xf bank_mask:0xf bound_ctrl:1
	v_mov_b32_e32 v8, v13
	v_mov_b32_e32 v13, v204
	v_add_f32_dpp v11, v11, v11 row_mirror row_mask:0xf bank_mask:0xf bound_ctrl:1
	ds_bpermute_b32 v26, v199, v11
	s_waitcnt lgkmcnt(0)
	v_add_f32_e32 v38, v11, v26
	v_mov_b32_e32 v26, v25
	v_mov_b32_e32 v25, v68
	v_pk_fma_f32 v[10:11], v[26:27], v[24:25], 0 op_sel_hi:[1,1,0]
	v_lshlrev_b64 v[26:27], 11, v[36:37]
	v_pk_fma_f32 v[8:9], v[8:9], v[12:13], v[10:11]
	v_mul_f32_e32 v13, v38, v45
	v_fma_f32 v13, v44, v24, -v13
	v_mov_b32_dpp v10, v8 quad_perm:[1,0,3,2] row_mask:0xf bank_mask:0xf bound_ctrl:1
	v_mov_b32_dpp v11, v9 quad_perm:[1,0,3,2] row_mask:0xf bank_mask:0xf bound_ctrl:1
	v_pk_add_f32 v[8:9], v[8:9], v[10:11]
	v_lshl_add_u64 v[26:27], v[64:65], 0, v[26:27]
	v_cvt_pk_bf16_f32 v13, v13, s0
	v_mov_b32_dpp v10, v8 quad_perm:[2,3,0,1] row_mask:0xf bank_mask:0xf bound_ctrl:1
	v_mov_b32_dpp v11, v9 quad_perm:[2,3,0,1] row_mask:0xf bank_mask:0xf bound_ctrl:1
	v_pk_add_f32 v[8:9], v[8:9], v[10:11]
	global_store_short v[26:27], v13, off
	v_mul_f32_e32 v13, v38, v28
	v_mov_b32_dpp v10, v8 row_half_mirror row_mask:0xf bank_mask:0xf bound_ctrl:1
	v_mov_b32_dpp v11, v9 row_half_mirror row_mask:0xf bank_mask:0xf bound_ctrl:1
	v_pk_add_f32 v[8:9], v[8:9], v[10:11]
	v_fma_f32 v12, v29, v12, -v13
	v_cvt_pk_bf16_f32 v12, v12, s0
	v_mov_b32_dpp v10, v8 row_mirror row_mask:0xf bank_mask:0xf bound_ctrl:1
	v_mov_b32_dpp v11, v9 row_mirror row_mask:0xf bank_mask:0xf bound_ctrl:1
	v_pk_add_f32 v[8:9], v[8:9], v[10:11]
	ds_bpermute_b32 v10, v199, v8
	ds_bpermute_b32 v11, v199, v9
	global_store_short v[26:27], v12, off offset:64
	s_and_saveexec_b64 s[0:1], s[2:3]
	s_cbranch_execz .LBB0_567
	v_lshlrev_b64 v[12:13], 7, v[36:37]
	v_lshl_add_u64 v[12:13], s[72:73], 0, v[12:13]
	s_waitcnt lgkmcnt(0)
	v_pk_add_f32 v[8:9], v[8:9], v[10:11]
	global_store_dwordx2 v[12:13], v[8:9], off
.LBB0_567:
	s_or_b64 exec, exec, s[0:1]
	v_lshlrev_b32_e32 v9, 16, v171
	v_lshlrev_b32_e32 v8, 16, v170
	s_waitcnt lgkmcnt(0)
	v_pk_mul_f32 v[10:11], v[100:101], v[8:9]
	v_add_f32_e32 v14, v14, v206
	v_pk_mul_f32 v[12:13], v[10:11], v[10:11]
	s_nop 0
	v_add_f32_e32 v12, v12, v13
	s_nop 1
	v_add_f32_dpp v12, v12, v12 quad_perm:[1,0,3,2] row_mask:0xf bank_mask:0xf bound_ctrl:1
	s_nop 1
	v_add_f32_dpp v12, v12, v12 quad_perm:[2,3,0,1] row_mask:0xf bank_mask:0xf bound_ctrl:1
	s_nop 1
	v_add_f32_dpp v12, v12, v12 row_half_mirror row_mask:0xf bank_mask:0xf bound_ctrl:1
	s_nop 1
	v_add_f32_dpp v12, v12, v12 row_mirror row_mask:0xf bank_mask:0xf bound_ctrl:1
	ds_bpermute_b32 v13, v199, v12
	s_waitcnt lgkmcnt(0)
	v_add_f32_e32 v12, v12, v13
	v_mul_f32_e32 v13, 0x4f800000, v12
	v_cmp_gt_f32_e32 vcc, s75, v12
	s_nop 1
	v_cndmask_b32_e32 v12, v12, v13, vcc
	v_sqrt_f32_e32 v13, v12
	s_nop 0
	v_add_u32_e32 v24, -1, v13
	v_add_u32_e32 v25, 1, v13
	v_fma_f32 v26, -v24, v13, v12
	v_fma_f32 v27, -v25, v13, v12
	v_cmp_ge_f32_e64 s[0:1], 0, v26
	s_nop 1
	v_cndmask_b32_e64 v13, v13, v24, s[0:1]
	v_cmp_lt_f32_e64 s[0:1], 0, v27
	s_nop 1
	v_cndmask_b32_e64 v13, v13, v25, s[0:1]
	v_mul_f32_e32 v24, 0x37800000, v13
	v_cndmask_b32_e32 v13, v13, v24, vcc
	v_cmp_class_f32_e32 vcc, v12, v201
	v_add_f32_e32 v25, v62, v210
	s_nop 0
	v_cndmask_b32_e32 v12, v13, v12, vcc
	v_max_f32_e32 v42, 0x2b8cbccc, v12
	v_div_scale_f32 v12, s[0:1], v42, v42, 1.0
	v_rcp_f32_e32 v43, v12
	s_nop 0
	v_fma_f32 v24, -v12, v43, 1.0
	v_div_scale_f32 v13, vcc, 1.0, v42, 1.0
	v_fmac_f32_e32 v43, v24, v43
	v_mul_f32_e32 v44, v13, v43
	v_fma_f32 v24, -v12, v44, v13
	v_fmac_f32_e32 v44, v24, v43
	v_fma_f32 v45, -v12, v44, v13
	v_max_f32_e64 v48, -v25, 0
	s_nop 0
	s_nop 1
	v_mul_f32_e64 v49, |v25|, s76
	v_exp_f32_e32 v49, v49
	s_nop 1
	v_add_f32_e32 v12, 1.0, v49
	v_log_f32_e32 v12, v12
	s_nop 0
	v_mul_f32_e32 v12, 0x3f317218, v12
	v_add_f32_e32 v12, v48, v12
	v_sub_f32_e32 v12, -0.5, v12
	v_add_f32_e32 v25, v46, v209
	v_div_fmas_f32 v28, v45, v43, v44
	v_div_fixup_f32 v44, v28, v42, 1.0
	v_mul_f32_e32 v10, v10, v44
	v_cvt_pk_bf16_f32 v45, v10, 0
	v_mul_f32_e32 v24, 0xbfb8aa3b, v25
	v_exp_f32_e32 v24, v24
	s_nop 0
	v_add_f32_e32 v24, 1.0, v24
	v_div_scale_f32 v25, s[0:1], v24, v24, 1.0
	v_rcp_f32_e32 v26, v25
	v_mul_f32_e32 v11, v11, v44
	s_nop 0
	s_nop 1
	v_mul_f32_e32 v12, 0x3fb8aa3b, v12
	v_exp_f32_e32 v12, v12
	v_fma_f32 v13, -v25, v26, 1.0
	v_fmac_f32_e32 v26, v13, v26
	v_div_scale_f32 v13, vcc, 1.0, v24, 1.0
	v_mul_f32_e32 v27, v13, v26
	v_fma_f32 v28, -v25, v27, v13
	v_fmac_f32_e32 v27, v28, v26
	v_fma_f32 v13, -v25, v27, v13
	v_div_fmas_f32 v13, v13, v26, v27
	v_div_fixup_f32 v13, v13, v24, 1.0
	v_add_f32_e32 v24, -1.0, v13
	v_fma_f32 v24, v208, v24, 1.0
	v_mul_f32_e32 v8, v24, v8
	v_cvt_pk_bf16_f32 v24, v12, 0
	v_mul_f32_e32 v10, v13, v10
	v_lshl_add_u64 v[26:27], s[54:55], 0, v[32:33]
	v_lshl_add_u64 v[12:13], s[20:21], 0, v[32:33]
	v_cvt_pk_bf16_f32 v8, v8, 0
	v_cvt_pk_bf16_f32 v10, v10, 0
	global_store_short v[26:27], v24, off
	global_store_short v[34:35], v8, off
	global_store_short v[12:13], v45, off
	v_lshl_add_u64 v[12:13], s[18:19], 0, v[32:33]
	global_store_short v[12:13], v10, off
	v_lshlrev_b32_e32 v13, 16, v8
	v_lshlrev_b32_e32 v8, 16, v10
	v_lshlrev_b32_e32 v10, 16, v24
	v_mul_f32_e32 v24, 0xbfb8aa3b, v10
	v_fma_f32 v25, v10, s76, -v24
	v_rndne_f32_e32 v28, v24
	v_fmac_f32_e32 v25, 0xb2a5705f, v10
	v_sub_f32_e32 v24, v24, v28
	v_add_f32_e32 v24, v24, v25
	s_waitcnt vmcnt(62)
	v_lshlrev_b32_e32 v12, 16, v169
	v_mul_f32_e32 v29, 0xbfb8aa3b, v10
	v_exp_f32_e32 v29, v29
	v_mov_b32_e32 v25, v12
	v_pk_mul_f32 v[24:25], v[24:25], v[12:13]
	v_fma_f32 v46, v8, v12, 0
	v_add_f32_e32 v24, v30, v207
	v_mov_b32_e32 v8, v29
	v_max_f32_e64 v30, -v24, 0
	s_nop 1
	v_mul_f32_e64 v24, |v24|, s76
	v_exp_f32_e32 v24, v24
	s_nop 0
	v_add_f32_e32 v32, 1.0, v24
	v_add_f32_e32 v28, -1.0, v32
	v_sub_f32_e32 v29, v28, v32
	v_add_f32_e32 v29, 1.0, v29
	v_sub_f32_e32 v28, v24, v28
	v_add_f32_e32 v33, v28, v29
	v_frexp_mant_f32_e32 v34, v32
	v_cvt_f64_f32_e32 v[28:29], v32
	v_frexp_exp_i32_f64_e32 v28, v[28:29]
	v_cmp_gt_f32_e32 vcc, s81, v34
	s_nop 1
	v_subbrev_co_u32_e32 v38, vcc, 0, v28, vcc
	v_sub_u32_e32 v28, 0, v38
	v_ldexp_f32 v29, v32, v28
	v_add_f32_e32 v32, -1.0, v29
	v_add_f32_e32 v34, 1.0, v29
	v_ldexp_f32 v28, v33, v28
	v_add_f32_e32 v33, 1.0, v32
	v_add_f32_e32 v35, -1.0, v34
	v_sub_f32_e32 v33, v29, v33
	v_sub_f32_e32 v29, v29, v35
	v_add_f32_e32 v33, v28, v33
	v_add_f32_e32 v28, v28, v29
	v_add_f32_e32 v39, v34, v28
	v_rcp_f32_e32 v41, v39
	v_sub_f32_e32 v29, v34, v39
	v_add_f32_e32 v40, v28, v29
	v_add_f32_e32 v29, v32, v33
	v_mul_f32_e32 v43, v29, v41
	v_sub_f32_e32 v28, v32, v29
	v_mul_f32_e32 v32, v39, v43
	v_fma_f32 v34, v43, v39, -v32
	v_fmac_f32_e32 v34, v43, v40
	v_add_f32_e32 v42, v33, v28
	v_add_f32_e32 v28, v32, v34
	v_sub_f32_e32 v33, v29, v28
	v_pk_add_f32 v[36:37], v[28:29], v[32:33] neg_lo:[0,1] neg_hi:[0,1]
	v_mov_b32_e32 v35, v28
	v_pk_add_f32 v[28:29], v[36:37], v[34:35] neg_lo:[0,1] neg_hi:[0,1]
	v_add_f32_e32 v29, v42, v29
	v_add_f32_e32 v28, v28, v29
	v_add_f32_e32 v29, v33, v28
	v_mul_f32_e32 v42, v41, v29
	v_mul_f32_e32 v32, v39, v42
	v_fma_f32 v34, v42, v39, -v32
	v_fmac_f32_e32 v34, v42, v40
	v_sub_f32_e32 v33, v33, v29
	v_add_f32_e32 v39, v28, v33
	v_add_f32_e32 v28, v32, v34
	v_sub_f32_e32 v33, v29, v28
	v_pk_add_f32 v[36:37], v[28:29], v[32:33] neg_lo:[0,1] neg_hi:[0,1]
	v_mov_b32_e32 v35, v28
	v_pk_add_f32 v[28:29], v[36:37], v[34:35] neg_lo:[0,1] neg_hi:[0,1]
	s_nop 0
	v_add_f32_e32 v29, v39, v29
	v_add_f32_e32 v28, v28, v29
	v_add_f32_e32 v29, v43, v42
	v_add_f32_e32 v28, v33, v28
	v_sub_f32_e32 v32, v29, v43
	v_mul_f32_e32 v28, v41, v28
	v_sub_f32_e32 v32, v42, v32
	v_add_f32_e32 v32, v32, v28
	v_add_f32_e32 v34, v29, v32
	v_mul_f32_e32 v35, v34, v34
	v_fmamk_f32 v28, v35, 0x3e9b6dac, v202
	v_fmaak_f32 v99, v35, v28, 0x3f2aaada
	v_cvt_f32_i32_e32 v28, v38
	v_sub_f32_e32 v29, v34, v29
	v_sub_f32_e32 v29, v32, v29
	v_ldexp_f32 v36, v29, 1
	v_mul_f32_e32 v29, v34, v35
	v_ldexp_f32 v33, v34, 1
	v_pk_mul_f32 v[34:35], v[28:29], v[98:99]
	s_nop 0
	v_fma_f32 v32, v28, s82, -v34
	v_fmac_f32_e32 v32, 0xb102e308, v28
	v_pk_add_f32 v[28:29], v[34:35], v[32:33]
	s_nop 0
	v_sub_f32_e32 v33, v29, v33
	v_sub_f32_e32 v33, v35, v33
	v_add_f32_e32 v37, v36, v33
	v_mov_b32_e32 v36, v34
	v_pk_add_f32 v[34:35], v[28:29], v[34:35] neg_lo:[0,1] neg_hi:[0,1]
	v_pk_add_f32 v[38:39], v[28:29], v[36:37]
	v_mov_b32_e32 v33, v28
	v_mov_b32_e32 v35, v39
	v_pk_add_f32 v[40:41], v[32:33], v[34:35] neg_lo:[0,1] neg_hi:[0,1]
	v_pk_add_f32 v[32:33], v[32:33], v[34:35]
	v_mov_b32_e32 v36, v37
	v_pk_add_f32 v[34:35], v[32:33], v[28:29] op_sel:[1,0] op_sel_hi:[0,1] neg_lo:[0,1] neg_hi:[0,1]
	v_pk_add_f32 v[42:43], v[38:39], v[34:35] op_sel_hi:[1,0] neg_lo:[0,1] neg_hi:[0,1]
	v_mov_b32_e32 v38, v39
	v_mov_b32_e32 v39, v33
	v_pk_mov_b32 v[34:35], v[28:29], v[34:35] op_sel:[1,0]
	v_mov_b32_e32 v37, v28
	v_pk_add_f32 v[34:35], v[38:39], v[34:35] neg_lo:[0,1] neg_hi:[0,1]
	v_mov_b32_e32 v42, v40
	v_pk_add_f32 v[28:29], v[36:37], v[34:35] neg_lo:[0,1] neg_hi:[0,1]
	v_mov_b32_e32 v41, v33
	v_pk_add_f32 v[34:35], v[42:43], v[28:29]
	s_nop 0
	v_pk_add_f32 v[36:37], v[34:35], v[34:35] op_sel:[0,1] op_sel_hi:[1,0]
	s_nop 0
	v_pk_add_f32 v[32:33], v[32:33], v[36:37] op_sel:[1,0] op_sel_hi:[0,1]
	v_mov_b32_e32 v35, v32
	v_pk_add_f32 v[38:39], v[34:35], v[40:41] neg_lo:[0,1] neg_hi:[0,1]
	v_lshlrev_b32_e32 v34, 16, v45
	s_nop 0
	v_add_f32_e32 v28, 1.0, v24
	v_log_f32_e32 v28, v28
	s_nop 0
	v_mul_f32_e32 v24, 0x3f317218, v28
	v_add_f32_e32 v24, v30, v24
	v_sub_f32_e32 v24, -0.5, v24
	v_mul_f32_e32 v28, 0x3fb8aa3b, v24
	v_exp_f32_e32 v28, v28
	v_mov_b32_e32 v33, v8
	v_mov_b32_e32 v8, v28
	s_nop 0
	s_nop 1
	v_mul_f32_e32 v10, 0xbfb8aa3b, v14
	v_exp_f32_e32 v10, v10
	s_nop 0
	v_add_f32_e32 v10, 1.0, v10
	v_div_scale_f32 v14, s[0:1], v10, v10, 1.0
	v_rcp_f32_e32 v28, v14
	s_nop 0
	v_fma_f32 v24, -v14, v28, 1.0
	v_fmac_f32_e32 v28, v24, v28
	v_div_scale_f32 v24, vcc, 1.0, v10, 1.0
	v_mul_f32_e32 v29, v24, v28
	v_fma_f32 v30, -v14, v29, v24
	v_fmac_f32_e32 v29, v30, v28
	v_fma_f32 v14, -v14, v29, v24
	v_div_fmas_f32 v14, v14, v28, v29
	v_div_fixup_f32 v10, v14, v10, 1.0
	v_add_f32_e32 v14, -1.0, v10
	v_fma_f32 v14, v205, v14, 1.0
	v_mul_f32_e32 v9, v14, v9
	v_cvt_pk_bf16_f32 v14, v8, 0
	v_mul_f32_e32 v8, v10, v11
	v_cvt_pk_bf16_f32 v24, v9, 0
	v_cvt_pk_bf16_f32 v28, v11, 0
	v_cvt_pk_bf16_f32 v10, v8, 0
	v_lshl_add_u64 v[8:9], s[20:21], 0, v[20:21]
	global_store_short v[26:27], v14, off offset:64
	global_store_short v[22:23], v24, off
	global_store_short v[8:9], v28, off
	v_lshl_add_u64 v[8:9], s[18:19], 0, v[20:21]
	global_store_short v[8:9], v10, off
	v_lshlrev_b32_e32 v8, 16, v10
	v_lshlrev_b32_e32 v10, 16, v14
	v_mul_f32_e32 v9, 0xbfb8aa3b, v10
	v_fma_f32 v11, v10, s76, -v9
	v_rndne_f32_e32 v14, v9
	v_fmac_f32_e32 v11, 0xb2a5705f, v10
	v_sub_f32_e32 v9, v9, v14
	v_add_f32_e32 v9, v9, v11
	v_exp_f32_e32 v11, v9
	v_lshlrev_b32_e32 v20, 16, v168
	v_lshlrev_b32_e32 v21, 16, v24
	v_mov_b32_e32 v9, v20
	v_fmac_f32_e32 v46, v8, v20
	v_pk_mul_f32 v[8:9], v[8:9], v[20:21]
	s_nop 0
	v_add_f32_dpp v11, v46, v46 quad_perm:[1,0,3,2] row_mask:0xf bank_mask:0xf bound_ctrl:1
	s_nop 1
	v_add_f32_dpp v11, v11, v11 quad_perm:[2,3,0,1] row_mask:0xf bank_mask:0xf bound_ctrl:1
	v_mov_b32_e32 v24, v13
	v_mov_b32_e32 v13, v68
	v_add_f32_dpp v11, v11, v11 row_half_mirror row_mask:0xf bank_mask:0xf bound_ctrl:1
	v_mul_f32_e32 v26, 0xbfb8aa3b, v10
	v_exp_f32_e32 v26, v26
	v_mov_b32_e32 v8, v21
	v_add_f32_dpp v11, v11, v11 row_mirror row_mask:0xf bank_mask:0xf bound_ctrl:1
	ds_bpermute_b32 v14, v199, v11
	v_mov_b32_e32 v21, v204
	v_lshlrev_b64 v[22:23], 11, v[18:19]
	v_lshlrev_b32_e32 v27, 16, v28
	v_lshl_add_u64 v[22:23], v[64:65], 0, v[22:23]
	s_waitcnt lgkmcnt(0)
	v_add_f32_e32 v14, v11, v14
	v_pk_fma_f32 v[10:11], v[24:25], v[12:13], 0 op_sel_hi:[1,1,0]
	v_mul_f32_e32 v13, v14, v34
	v_pk_fma_f32 v[8:9], v[8:9], v[20:21], v[10:11]
	v_fma_f32 v12, v33, v12, -v13
	v_cvt_pk_bf16_f32 v12, v12, s0
	v_mov_b32_dpp v10, v8 quad_perm:[1,0,3,2] row_mask:0xf bank_mask:0xf bound_ctrl:1
	v_mov_b32_dpp v11, v9 quad_perm:[1,0,3,2] row_mask:0xf bank_mask:0xf bound_ctrl:1
	v_pk_add_f32 v[8:9], v[8:9], v[10:11]
	global_store_short v[22:23], v12, off
	v_mul_f32_e32 v12, v14, v27
	v_mov_b32_dpp v10, v8 quad_perm:[2,3,0,1] row_mask:0xf bank_mask:0xf bound_ctrl:1
	v_mov_b32_dpp v11, v9 quad_perm:[2,3,0,1] row_mask:0xf bank_mask:0xf bound_ctrl:1
	v_pk_add_f32 v[8:9], v[8:9], v[10:11]
	v_fma_f32 v12, v26, v20, -v12
	v_cvt_pk_bf16_f32 v12, v12, s0
	v_mov_b32_dpp v10, v8 row_half_mirror row_mask:0xf bank_mask:0xf bound_ctrl:1
	v_mov_b32_dpp v11, v9 row_half_mirror row_mask:0xf bank_mask:0xf bound_ctrl:1
	v_pk_add_f32 v[8:9], v[8:9], v[10:11]
	global_store_short v[22:23], v12, off offset:64
	s_nop 0
	v_mov_b32_dpp v10, v8 row_mirror row_mask:0xf bank_mask:0xf bound_ctrl:1
	v_mov_b32_dpp v11, v9 row_mirror row_mask:0xf bank_mask:0xf bound_ctrl:1
	v_pk_add_f32 v[8:9], v[8:9], v[10:11]
	ds_bpermute_b32 v10, v199, v8
	ds_bpermute_b32 v11, v199, v9
	s_and_saveexec_b64 s[0:1], s[2:3]
	s_cbranch_execz .LBB0_569
	v_lshlrev_b64 v[12:13], 7, v[18:19]
	v_lshl_add_u64 v[12:13], s[72:73], 0, v[12:13]
	s_waitcnt lgkmcnt(0)
	v_pk_add_f32 v[8:9], v[8:9], v[10:11]
	global_store_dwordx2 v[12:13], v[8:9], off
.LBB0_569:
	s_or_b64 exec, exec, s[0:1]
	v_lshlrev_b32_e32 v9, 16, v167
	v_lshlrev_b32_e32 v8, 16, v166
	s_waitcnt lgkmcnt(0)
	v_pk_mul_f32 v[10:11], v[100:101], v[8:9]
	v_add_f32_e32 v15, v15, v206
	v_pk_mul_f32 v[12:13], v[10:11], v[10:11]
	s_nop 0
	v_add_f32_e32 v12, v12, v13
	s_nop 1
	v_add_f32_dpp v12, v12, v12 quad_perm:[1,0,3,2] row_mask:0xf bank_mask:0xf bound_ctrl:1
	s_nop 1
	v_add_f32_dpp v12, v12, v12 quad_perm:[2,3,0,1] row_mask:0xf bank_mask:0xf bound_ctrl:1
	s_nop 1
	v_add_f32_dpp v12, v12, v12 row_half_mirror row_mask:0xf bank_mask:0xf bound_ctrl:1
	s_nop 1
	v_add_f32_dpp v12, v12, v12 row_mirror row_mask:0xf bank_mask:0xf bound_ctrl:1
	ds_bpermute_b32 v13, v199, v12
	s_waitcnt lgkmcnt(0)
	v_add_f32_e32 v12, v12, v13
	v_mul_f32_e32 v13, 0x4f800000, v12
	v_cmp_gt_f32_e32 vcc, s75, v12
	s_nop 1
	v_cndmask_b32_e32 v12, v12, v13, vcc
	v_sqrt_f32_e32 v13, v12
	s_nop 0
	v_add_u32_e32 v14, -1, v13
	v_add_u32_e32 v18, 1, v13
	v_fma_f32 v19, -v14, v13, v12
	v_fma_f32 v20, -v18, v13, v12
	v_cmp_ge_f32_e64 s[0:1], 0, v19
	v_add_f32_e32 v19, v63, v210
	v_max_f32_e64 v34, -v19, 0
	v_cndmask_b32_e64 v13, v13, v14, s[0:1]
	v_cmp_lt_f32_e64 s[0:1], 0, v20
	s_nop 1
	v_cndmask_b32_e64 v13, v13, v18, s[0:1]
	v_mul_f32_e32 v14, 0x37800000, v13
	v_cndmask_b32_e32 v13, v13, v14, vcc
	v_cmp_class_f32_e32 vcc, v12, v201
	s_nop 1
	v_cndmask_b32_e32 v12, v13, v12, vcc
	v_max_f32_e32 v14, 0x2b8cbccc, v12
	v_div_scale_f32 v12, s[0:1], v14, v14, 1.0
	v_rcp_f32_e32 v30, v12
	v_div_scale_f32 v13, vcc, 1.0, v14, 1.0
	v_fma_f32 v18, -v12, v30, 1.0
	v_fmac_f32_e32 v30, v18, v30
	v_mul_f32_e32 v32, v13, v30
	v_fma_f32 v18, -v12, v32, v13
	v_fmac_f32_e32 v32, v18, v30
	v_fma_f32 v33, -v12, v32, v13
	s_nop 1
	v_mul_f32_e64 v35, |v19|, s76
	v_exp_f32_e32 v35, v35
	s_nop 1
	v_add_f32_e32 v12, 1.0, v35
	v_log_f32_e32 v12, v12
	s_nop 0
	v_mul_f32_e32 v12, 0x3f317218, v12
	v_add_f32_e32 v12, v34, v12
	v_sub_f32_e32 v12, -0.5, v12
	v_add_f32_e32 v19, v47, v209
	v_div_fmas_f32 v22, v33, v30, v32
	v_div_fixup_f32 v14, v22, v14, 1.0
	v_mul_f32_e32 v10, v10, v14
	v_cvt_pk_bf16_f32 v32, v10, 0
	v_mul_f32_e32 v18, 0xbfb8aa3b, v19
	v_exp_f32_e32 v18, v18
	s_nop 0
	v_add_f32_e32 v18, 1.0, v18
	v_div_scale_f32 v19, s[0:1], v18, v18, 1.0
	v_rcp_f32_e32 v20, v19
	v_mul_f32_e32 v11, v11, v14
	v_cvt_pk_bf16_f32 v14, v11, 0
	s_nop 1
	v_mul_f32_e32 v12, 0x3fb8aa3b, v12
	v_exp_f32_e32 v12, v12
	v_fma_f32 v13, -v19, v20, 1.0
	v_fmac_f32_e32 v20, v13, v20
	v_div_scale_f32 v13, vcc, 1.0, v18, 1.0
	v_mul_f32_e32 v21, v13, v20
	v_fma_f32 v22, -v19, v21, v13
	v_fmac_f32_e32 v21, v22, v20
	v_fma_f32 v13, -v19, v21, v13
	v_div_fmas_f32 v13, v13, v20, v21
	v_div_fixup_f32 v13, v13, v18, 1.0
	v_add_f32_e32 v18, -1.0, v13
	v_fma_f32 v18, v208, v18, 1.0
	v_mul_f32_e32 v8, v18, v8
	v_mul_f32_e32 v10, v13, v10
	v_cvt_pk_bf16_f32 v20, v12, 0
	v_cvt_pk_bf16_f32 v8, v8, 0
	v_cvt_pk_bf16_f32 v10, v10, 0
	v_lshl_add_u64 v[18:19], s[54:55], 0, v[6:7]
	v_lshl_add_u64 v[12:13], s[20:21], 0, v[6:7]
	v_lshl_add_u64 v[6:7], s[18:19], 0, v[6:7]
	global_store_short v[18:19], v20, off
	global_store_short v[16:17], v8, off
	global_store_short v[6:7], v10, off
	v_lshlrev_b32_e32 v7, 16, v8
	v_lshlrev_b32_e32 v8, 16, v10
	v_lshlrev_b32_e32 v10, 16, v20
	global_store_short v[12:13], v32, off
	v_mul_f32_e32 v12, 0xbfb8aa3b, v10
	v_fma_f32 v13, v10, s76, -v12
	v_rndne_f32_e32 v16, v12
	v_fmac_f32_e32 v13, 0xb2a5705f, v10
	v_sub_f32_e32 v12, v12, v16
	v_add_f32_e32 v12, v12, v13
	v_lshlrev_b32_e32 v6, 16, v165
	v_mul_f32_e32 v17, 0xbfb8aa3b, v10
	v_exp_f32_e32 v17, v17
	v_mov_b32_e32 v13, v6
	v_pk_mul_f32 v[12:13], v[12:13], v[6:7]
	v_fma_f32 v33, v8, v6, 0
	v_add_f32_e32 v12, v31, v207
	v_mov_b32_e32 v8, v17
	v_max_f32_e64 v34, -v12, 0
	s_nop 1
	v_mul_f32_e64 v12, |v12|, s76
	v_exp_f32_e32 v12, v12
	s_nop 0
	v_add_f32_e32 v20, 1.0, v12
	v_add_f32_e32 v16, -1.0, v20
	v_sub_f32_e32 v17, v16, v20
	v_add_f32_e32 v17, 1.0, v17
	v_sub_f32_e32 v16, v12, v16
	v_add_f32_e32 v21, v16, v17
	v_frexp_mant_f32_e32 v22, v20
	v_cvt_f64_f32_e32 v[16:17], v20
	v_frexp_exp_i32_f64_e32 v16, v[16:17]
	v_cmp_gt_f32_e32 vcc, s81, v22
	s_nop 1
	v_subbrev_co_u32_e32 v26, vcc, 0, v16, vcc
	v_sub_u32_e32 v16, 0, v26
	v_ldexp_f32 v17, v20, v16
	v_add_f32_e32 v20, -1.0, v17
	v_add_f32_e32 v22, 1.0, v17
	v_ldexp_f32 v16, v21, v16
	v_add_f32_e32 v21, 1.0, v20
	v_add_f32_e32 v23, -1.0, v22
	v_sub_f32_e32 v21, v17, v21
	v_sub_f32_e32 v17, v17, v23
	v_add_f32_e32 v21, v16, v21
	v_add_f32_e32 v16, v16, v17
	v_add_f32_e32 v27, v22, v16
	v_rcp_f32_e32 v29, v27
	v_sub_f32_e32 v17, v22, v27
	v_add_f32_e32 v28, v16, v17
	v_add_f32_e32 v17, v20, v21
	v_mul_f32_e32 v31, v17, v29
	v_sub_f32_e32 v16, v20, v17
	v_mul_f32_e32 v20, v27, v31
	v_fma_f32 v22, v31, v27, -v20
	v_fmac_f32_e32 v22, v31, v28
	v_add_f32_e32 v30, v21, v16
	v_add_f32_e32 v16, v20, v22
	v_sub_f32_e32 v21, v17, v16
	v_pk_add_f32 v[24:25], v[16:17], v[20:21] neg_lo:[0,1] neg_hi:[0,1]
	v_mov_b32_e32 v23, v16
	v_pk_add_f32 v[16:17], v[24:25], v[22:23] neg_lo:[0,1] neg_hi:[0,1]
	v_add_f32_e32 v17, v30, v17
	v_add_f32_e32 v16, v16, v17
	v_add_f32_e32 v17, v21, v16
	v_mul_f32_e32 v30, v29, v17
	v_mul_f32_e32 v20, v27, v30
	v_fma_f32 v22, v30, v27, -v20
	v_fmac_f32_e32 v22, v30, v28
	v_sub_f32_e32 v21, v21, v17
	v_add_f32_e32 v27, v16, v21
	v_add_f32_e32 v16, v20, v22
	v_sub_f32_e32 v21, v17, v16
	v_pk_add_f32 v[24:25], v[16:17], v[20:21] neg_lo:[0,1] neg_hi:[0,1]
	v_mov_b32_e32 v23, v16
	v_pk_add_f32 v[16:17], v[24:25], v[22:23] neg_lo:[0,1] neg_hi:[0,1]
	s_nop 0
	v_add_f32_e32 v17, v27, v17
	v_add_f32_e32 v16, v16, v17
	v_add_f32_e32 v17, v31, v30
	v_add_f32_e32 v16, v21, v16
	v_sub_f32_e32 v20, v17, v31
	v_mul_f32_e32 v16, v29, v16
	v_sub_f32_e32 v20, v30, v20
	v_add_f32_e32 v20, v20, v16
	v_add_f32_e32 v22, v17, v20
	v_mul_f32_e32 v23, v22, v22
	v_fmamk_f32 v16, v23, 0x3e9b6dac, v202
	v_fmaak_f32 v99, v23, v16, 0x3f2aaada
	v_cvt_f32_i32_e32 v16, v26
	v_sub_f32_e32 v17, v22, v17
	v_sub_f32_e32 v17, v20, v17
	v_ldexp_f32 v24, v17, 1
	v_mul_f32_e32 v17, v22, v23
	v_ldexp_f32 v21, v22, 1
	v_pk_mul_f32 v[22:23], v[16:17], v[98:99]
	s_nop 0
	v_fma_f32 v20, v16, s82, -v22
	v_fmac_f32_e32 v20, 0xb102e308, v16
	v_pk_add_f32 v[16:17], v[22:23], v[20:21]
	s_nop 0
	v_sub_f32_e32 v21, v17, v21
	v_sub_f32_e32 v21, v23, v21
	v_add_f32_e32 v25, v24, v21
	v_mov_b32_e32 v24, v22
	v_pk_add_f32 v[22:23], v[16:17], v[22:23] neg_lo:[0,1] neg_hi:[0,1]
	v_pk_add_f32 v[26:27], v[16:17], v[24:25]
	v_mov_b32_e32 v21, v16
	v_mov_b32_e32 v23, v27
	v_pk_add_f32 v[28:29], v[20:21], v[22:23] neg_lo:[0,1] neg_hi:[0,1]
	v_pk_add_f32 v[20:21], v[20:21], v[22:23]
	v_mov_b32_e32 v24, v25
	v_pk_add_f32 v[22:23], v[20:21], v[16:17] op_sel:[1,0] op_sel_hi:[0,1] neg_lo:[0,1] neg_hi:[0,1]
	v_pk_add_f32 v[30:31], v[26:27], v[22:23] op_sel_hi:[1,0] neg_lo:[0,1] neg_hi:[0,1]
	v_mov_b32_e32 v26, v27
	v_mov_b32_e32 v27, v21
	v_pk_mov_b32 v[22:23], v[16:17], v[22:23] op_sel:[1,0]
	v_mov_b32_e32 v25, v16
	v_pk_add_f32 v[22:23], v[26:27], v[22:23] neg_lo:[0,1] neg_hi:[0,1]
	v_mov_b32_e32 v30, v28
	v_pk_add_f32 v[16:17], v[24:25], v[22:23] neg_lo:[0,1] neg_hi:[0,1]
	v_mov_b32_e32 v29, v21
	v_pk_add_f32 v[22:23], v[30:31], v[16:17]
	s_nop 0
	v_pk_add_f32 v[24:25], v[22:23], v[22:23] op_sel:[0,1] op_sel_hi:[1,0]
	s_nop 0
	v_pk_add_f32 v[20:21], v[20:21], v[24:25] op_sel:[1,0] op_sel_hi:[0,1]
	v_mov_b32_e32 v23, v20
	v_pk_add_f32 v[26:27], v[22:23], v[28:29] neg_lo:[0,1] neg_hi:[0,1]
	v_lshlrev_b32_e32 v23, 16, v32
	s_nop 0
	v_add_f32_e32 v16, 1.0, v12
	v_log_f32_e32 v16, v16
	s_nop 0
	v_mul_f32_e32 v12, 0x3f317218, v16
	v_add_f32_e32 v12, v34, v12
	v_sub_f32_e32 v12, -0.5, v12
	v_mul_f32_e32 v20, 0xbfb8aa3b, v15
	v_rndne_f32_e32 v22, v20
	v_cvt_i32_f32_e32 v21, v22
	v_mul_f32_e32 v16, 0x3fb8aa3b, v12
	v_exp_f32_e32 v16, v16
	v_mov_b32_e32 v22, v8
	v_mov_b32_e32 v8, v16
	s_nop 0
	s_nop 1
	v_mul_f32_e32 v10, 0xbfb8aa3b, v15
	v_exp_f32_e32 v10, v10
	s_nop 0
	v_add_f32_e32 v10, 1.0, v10
	v_div_scale_f32 v15, s[0:1], v10, v10, 1.0
	v_rcp_f32_e32 v16, v15
	s_nop 0
	v_fma_f32 v12, -v15, v16, 1.0
	v_fmac_f32_e32 v16, v12, v16
	v_div_scale_f32 v12, vcc, 1.0, v10, 1.0
	v_mul_f32_e32 v17, v12, v16
	v_fma_f32 v20, -v15, v17, v12
	v_fmac_f32_e32 v17, v20, v16
	v_fma_f32 v12, -v15, v17, v12
	v_div_fmas_f32 v12, v12, v16, v17
	v_div_fixup_f32 v10, v12, v10, 1.0
	v_add_f32_e32 v12, -1.0, v10
	v_fma_f32 v12, v205, v12, 1.0
	v_mul_f32_e32 v9, v12, v9
	v_cvt_pk_bf16_f32 v12, v8, 0
	v_cvt_pk_bf16_f32 v8, v9, 0
	v_mul_f32_e32 v9, v10, v11
	global_store_short v[18:19], v12, off offset:64
	global_store_short v[4:5], v8, off
	v_lshl_add_u64 v[4:5], s[20:21], 0, v[2:3]
	v_cvt_pk_bf16_f32 v10, v9, 0
	global_store_short v[4:5], v14, off
	v_lshl_add_u64 v[2:3], s[18:19], 0, v[2:3]
	v_lshlrev_b32_e32 v4, 16, v12
	global_store_short v[2:3], v10, off
	v_mul_f32_e32 v3, 0xbfb8aa3b, v4
	v_lshlrev_b32_e32 v2, 16, v10
	v_fma_f32 v5, v4, s76, -v3
	v_rndne_f32_e32 v10, v3
	v_fmac_f32_e32 v5, 0xb2a5705f, v4
	v_sub_f32_e32 v3, v3, v10
	v_add_f32_e32 v3, v3, v5
	v_exp_f32_e32 v5, v3
	v_lshlrev_b32_e32 v9, 16, v8
	v_lshlrev_b32_e32 v8, 16, v164
	v_mov_b32_e32 v3, v8
	v_fmac_f32_e32 v33, v2, v8
	v_pk_mul_f32 v[2:3], v[2:3], v[8:9]
	s_nop 0
	v_add_f32_dpp v5, v33, v33 quad_perm:[1,0,3,2] row_mask:0xf bank_mask:0xf bound_ctrl:1
	v_cmp_ngt_f32_e32 vcc, s79, v4
	s_nop 0
	v_add_f32_dpp v5, v5, v5 quad_perm:[2,3,0,1] row_mask:0xf bank_mask:0xf bound_ctrl:1
	v_mov_b32_e32 v12, v7
	v_mov_b32_e32 v7, v68
	v_add_f32_dpp v5, v5, v5 row_half_mirror row_mask:0xf bank_mask:0xf bound_ctrl:1
	v_mul_f32_e32 v15, 0xbfb8aa3b, v4
	v_exp_f32_e32 v15, v15
	v_mov_b32_e32 v2, v9
	v_add_f32_dpp v5, v5, v5 row_mirror row_mask:0xf bank_mask:0xf bound_ctrl:1
	ds_bpermute_b32 v10, v199, v5
	v_mov_b32_e32 v9, v204
	v_lshlrev_b32_e32 v14, 16, v14
	s_waitcnt lgkmcnt(0)
	v_add_f32_e32 v16, v5, v10
	v_pk_fma_f32 v[4:5], v[12:13], v[6:7], 0 op_sel_hi:[1,1,0]
	v_mul_f32_e32 v7, v16, v23
	v_pk_fma_f32 v[2:3], v[2:3], v[8:9], v[4:5]
	v_lshlrev_b64 v[10:11], 11, v[0:1]
	v_fma_f32 v6, v22, v6, -v7
	v_mov_b32_dpp v4, v2 quad_perm:[1,0,3,2] row_mask:0xf bank_mask:0xf bound_ctrl:1
	v_mov_b32_dpp v5, v3 quad_perm:[1,0,3,2] row_mask:0xf bank_mask:0xf bound_ctrl:1
	v_pk_add_f32 v[2:3], v[2:3], v[4:5]
	v_lshl_add_u64 v[10:11], v[64:65], 0, v[10:11]
	v_cvt_pk_bf16_f32 v6, v6, s0
	v_mov_b32_dpp v4, v2 quad_perm:[2,3,0,1] row_mask:0xf bank_mask:0xf bound_ctrl:1
	v_mov_b32_dpp v5, v3 quad_perm:[2,3,0,1] row_mask:0xf bank_mask:0xf bound_ctrl:1
	v_pk_add_f32 v[2:3], v[2:3], v[4:5]
	global_store_short v[10:11], v6, off
	v_mul_f32_e32 v6, v16, v14
	v_mov_b32_dpp v4, v2 row_half_mirror row_mask:0xf bank_mask:0xf bound_ctrl:1
	v_mov_b32_dpp v5, v3 row_half_mirror row_mask:0xf bank_mask:0xf bound_ctrl:1
	v_pk_add_f32 v[2:3], v[2:3], v[4:5]
	v_fma_f32 v6, v15, v8, -v6
	v_cvt_pk_bf16_f32 v6, v6, s0
	v_mov_b32_dpp v4, v2 row_mirror row_mask:0xf bank_mask:0xf bound_ctrl:1
	v_mov_b32_dpp v5, v3 row_mirror row_mask:0xf bank_mask:0xf bound_ctrl:1
	v_pk_add_f32 v[2:3], v[2:3], v[4:5]
	ds_bpermute_b32 v4, v199, v2
	ds_bpermute_b32 v5, v199, v3
	global_store_short v[10:11], v6, off offset:64
	s_and_saveexec_b64 s[0:1], s[2:3]
	s_cbranch_execz .LBB0_538
	v_lshlrev_b64 v[0:1], 7, v[0:1]
	v_lshl_add_u64 v[0:1], s[72:73], 0, v[0:1]
	s_waitcnt lgkmcnt(0)
	v_pk_add_f32 v[2:3], v[2:3], v[4:5]
	global_store_dwordx2 v[0:1], v[2:3], off
	s_branch .LBB0_538

.LBB0_1082:
	s_or_b64 exec, exec, s[0:1]
	s_add_u32 s6, s56, 0x14000000
	s_addc_u32 s7, s57, 0
	s_add_u32 s8, s56, 0x1700000
	s_addc_u32 s9, s57, 0
	v_mov_b32_e32 v0, v196
	s_cmpk_gt_i32 s12, 0x7ff
	s_waitcnt lgkmcnt(0)
	s_barrier
	s_cbranch_scc1 .LBB0_1112
	v_and_b32_e32 v1, 63, v0
	v_lshlrev_b32_e32 v2, 2, v1
	v_mov_b32_e32 v3, 0
	v_lshl_add_u64 v[2:3], s[56:57], 0, v[2:3]
	s_mov_b64 s[0:1], 0x2800000
	s_waitcnt vmcnt(0)
	v_lshlrev_b32_e32 v71, 2, v0
	v_lshl_add_u64 v[2:3], v[2:3], 0, s[0:1]
	v_not_b32_e32 v70, v0
	v_add_u32_e32 v1, 0x100, v0
	v_add_u32_e32 v72, 16, v71
	s_movk_i32 s1, 0xff
	s_mov_b32 s0, 0x3b800000
	s_mov_b32 s10, s12
	s_mov_b32 s11, s12
	s_and_b32 s64, s58, 31
	s_cmp_eq_u32 s64, 0
	s_cselect_b32 s64, 31, 0
	s_branch .LBB0_1086

.LBB0_1085:
	s_add_i32 s11, s11, s58
	s_add_i32 s10, s10, s58
	s_xor_b32 s11, s11, s64
	s_xor_b32 s10, s10, s64
	v_lshl_add_u64 v[4:5], v[4:5], 2, s[8:9]
	s_cmpk_gt_i32 s11, 0x7ff
	global_store_dword v[4:5], v6, off
	s_cbranch_scc1 .LBB0_1112
